# GEMM: first two K-loop waits after an epilogue relaxed to vmcnt(24) (stores stay in flight); FF1/in-proj epilogue stores global nt
# speedup vs baseline: 1.0102x; 1.0102x over previous
.LBB0_30:
	v_lshrrev_b32_e32 v17, 1, v158
	v_and_b32_e32 v17, 24, v17
	v_and_b32_e32 v16, 15, v158
	v_lshlrev_b32_e32 v18, 1, v17
	s_add_u32 s6, s2, 0x9c00000
	v_lshl_or_b32 v159, s1, 6, v16
	v_lshl_or_b32 v16, v16, 6, v18
	v_lshlrev_b32_e32 v18, 2, v158
	s_sext_i32_i8 s44, s0
	s_addc_u32 s7, s3, 0
	s_lshl_b32 s0, s1, 13
	v_and_b32_e32 v18, 32, v18
	v_bitop3_b32 v19, v16, s0, v18 bitop3:0xde
	s_lshl_b32 s0, s9, 5
	s_and_b32 s10, s0, 0x60
	s_add_i32 m0, s19, 0x18000
	v_lshl_add_u64 v[8:9], v[8:9], 0, s[96:97]
	s_lshl_b32 s0, s10, 7
	s_waitcnt vmcnt(2)
	s_barrier
	global_load_lds_dwordx4 v[8:9], off
	v_lshl_add_u64 v[6:7], v[6:7], 0, s[96:97]
	s_add_i32 m0, s19, 0x1a000
	s_add_i32 s40, s19, 0x8000
	s_add_i32 s41, s19, 0xa000
	v_bitop3_b32 v162, s0, v16, v18 bitop3:0xf6
	global_load_lds_dwordx4 v[6:7], off
	v_lshl_add_u64 v[2:3], v[2:3], 0, s[96:97]
	s_mov_b32 m0, s40
	s_add_u32 s0, s20, 0x40080
	global_load_lds_dwordx4 v[2:3], off
	v_lshl_add_u64 v[2:3], v[4:5], 0, s[96:97]
	s_mov_b32 m0, s41
	s_addc_u32 s1, s21, 0
	global_load_lds_dwordx4 v[2:3], off
	s_add_i32 m0, s19, 0x1c000
	v_lshl_add_u64 v[2:3], s[0:1], 0, v[0:1]
	global_load_lds_dwordx4 v[2:3], off
	v_lshl_add_u64 v[2:3], s[0:1], 0, v[134:135]
	s_add_i32 m0, s19, 0x1e000
	s_cmpk_lt_u32 s8, 0x100
	global_load_lds_dwordx4 v[2:3], off
	v_lshlrev_b32_e32 v2, 14, v13
	v_and_b32_e32 v2, 0xffff8000, v2
	v_lshl_add_u32 v2, v14, 11, v2
	v_and_b32_e32 v3, 1, v13
	v_lshl_or_b32 v2, v3, 6, v2
	v_lshl_add_u32 v136, v15, 1, v2
	v_lshlrev_b32_e32 v2, 14, v10
	v_and_b32_e32 v2, 0xffff8000, v2
	s_waitcnt vmcnt(6)
	v_lshl_add_u32 v2, v11, 11, v2
	v_and_b32_e32 v3, 1, v10
	v_lshl_or_b32 v2, v3, 6, v2
	s_cselect_b64 s[8:9], -1, 0
	s_ashr_i32 s42, s36, 31
	v_or_b32_e32 v163, s10, v17
	v_mov_b32_e32 v137, v1
	v_lshl_add_u32 v138, v12, 1, v2
	v_mov_b32_e32 v139, v1
	s_mov_b32 s43, 0
	v_add_u32_e32 v164, 0, v19
	s_barrier
	s_mov_b32 s98, 0
	s_branch .LBB0_36

.LBB0_43:
	s_add_u32 s22, s20, 0xfffc0080
	s_addc_u32 s23, s21, -1
	s_add_i32 s55, 0, 0x10000
	s_cmp_eq_u32 s49, 12
	s_cselect_b32 s25, s13, s23
	s_cselect_b32 s24, s45, s22
	v_add_u32_e32 v148, s55, v162
	s_cselect_b32 s23, s11, s48
	s_cselect_b32 s22, s46, s47
	s_add_i32 s58, 0, 0x14000
	ds_read_b128 v[140:143], v148
	ds_read_b128 v[144:147], v148 offset:1024
	ds_read_b128 v[154:157], v148 offset:2048
	ds_read_b128 v[166:169], v148 offset:3072
	v_add_u32_e32 v148, s58, v162
	ds_read_b128 v[170:173], v148
	ds_read_b128 v[174:177], v148 offset:1024
	ds_read_b128 v[178:181], v148 offset:2048
	ds_read_b128 v[182:185], v148 offset:3072
	v_lshl_add_u64 v[148:149], s[20:21], 0, v[138:139]
	s_add_i32 m0, s19, 0xc000
	ds_read_b128 v[186:189], v164
	ds_read_b128 v[190:193], v164 offset:1024
	ds_read_b128 v[194:197], v164 offset:2048
	ds_read_b128 v[198:201], v164 offset:3072
	ds_read_b128 v[202:205], v164 offset:4096
	ds_read_b128 v[206:209], v164 offset:5120
	ds_read_b128 v[210:213], v164 offset:6144
	ds_read_b128 v[222:225], v164 offset:7168
	global_load_lds_dwordx4 v[148:149], off
	v_lshl_add_u64 v[148:149], s[20:21], 0, v[136:137]
	s_add_i32 m0, s19, 0xe000
	s_nop 0
	global_load_lds_dwordx4 v[148:149], off
	s_cmp_lg_u32 s98, 0
	s_cbranch_scc1 .Lrelax_ff1_w1
	s_waitcnt vmcnt(8)
.Lback_ff1_w1:
	s_waitcnt lgkmcnt(0)
	s_barrier
	s_setprio 1
	s_waitcnt lgkmcnt(0)
	v_mfma_f32_16x16x32_bf16 v[126:129], v[140:143], v[186:189], v[126:129]
	v_mfma_f32_16x16x32_bf16 v[122:125], v[154:157], v[186:189], v[122:125]
	v_mfma_f32_16x16x32_bf16 v[110:113], v[140:143], v[194:197], v[110:113]
	v_mfma_f32_16x16x32_bf16 v[106:109], v[154:157], v[194:197], v[106:109]
	v_mfma_f32_16x16x32_bf16 v[94:97], v[140:143], v[202:205], v[94:97]
	v_mfma_f32_16x16x32_bf16 v[90:93], v[154:157], v[202:205], v[90:93]
	v_mfma_f32_16x16x32_bf16 v[78:81], v[140:143], v[210:213], v[78:81]
	v_mfma_f32_16x16x32_bf16 v[74:77], v[154:157], v[210:213], v[74:77]
	v_mfma_f32_16x16x32_bf16 v[126:129], v[144:147], v[190:193], v[126:129]
	v_mfma_f32_16x16x32_bf16 v[122:125], v[166:169], v[190:193], v[122:125]
	v_mfma_f32_16x16x32_bf16 v[110:113], v[144:147], v[198:201], v[110:113]
	v_mfma_f32_16x16x32_bf16 v[106:109], v[166:169], v[198:201], v[106:109]
	v_mfma_f32_16x16x32_bf16 v[94:97], v[144:147], v[206:209], v[94:97]
	v_mfma_f32_16x16x32_bf16 v[90:93], v[166:169], v[206:209], v[90:93]
	v_mfma_f32_16x16x32_bf16 v[78:81], v[144:147], v[222:225], v[78:81]
	v_mfma_f32_16x16x32_bf16 v[74:77], v[166:169], v[222:225], v[74:77]
	s_setprio 0
	s_setprio 1
	v_mfma_f32_16x16x32_bf16 v[118:121], v[170:173], v[186:189], v[118:121]
	v_mfma_f32_16x16x32_bf16 v[114:117], v[178:181], v[186:189], v[114:117]
	v_mfma_f32_16x16x32_bf16 v[102:105], v[170:173], v[194:197], v[102:105]
	v_mfma_f32_16x16x32_bf16 v[98:101], v[178:181], v[194:197], v[98:101]
	v_mfma_f32_16x16x32_bf16 v[86:89], v[170:173], v[202:205], v[86:89]
	v_mfma_f32_16x16x32_bf16 v[82:85], v[178:181], v[202:205], v[82:85]
	v_mfma_f32_16x16x32_bf16 v[70:73], v[170:173], v[210:213], v[70:73]
	v_mfma_f32_16x16x32_bf16 v[66:69], v[178:181], v[210:213], v[66:69]
	v_mfma_f32_16x16x32_bf16 v[118:121], v[174:177], v[190:193], v[118:121]
	v_mfma_f32_16x16x32_bf16 v[114:117], v[182:185], v[190:193], v[114:117]
	v_mfma_f32_16x16x32_bf16 v[102:105], v[174:177], v[198:201], v[102:105]
	v_mfma_f32_16x16x32_bf16 v[98:101], v[182:185], v[198:201], v[98:101]
	v_mfma_f32_16x16x32_bf16 v[86:89], v[174:177], v[206:209], v[86:89]
	v_mfma_f32_16x16x32_bf16 v[82:85], v[182:185], v[206:209], v[82:85]
	v_mfma_f32_16x16x32_bf16 v[70:73], v[174:177], v[222:225], v[70:73]
	v_mfma_f32_16x16x32_bf16 v[66:69], v[182:185], v[222:225], v[66:69]
	s_setprio 0
	s_barrier
	s_add_i32 s55, s55, s31
	v_lshl_add_u64 v[148:149], s[22:23], 0, v[0:1]
	s_mov_b32 m0, s55
	ds_read_b128 v[186:189], v164 offset:16384
	ds_read_b128 v[190:193], v164 offset:17408
	ds_read_b128 v[194:197], v164 offset:18432
	ds_read_b128 v[198:201], v164 offset:19456
	ds_read_b128 v[202:205], v164 offset:20480
	ds_read_b128 v[206:209], v164 offset:21504
	ds_read_b128 v[210:213], v164 offset:22528
	ds_read_b128 v[222:225], v164 offset:23552
	global_load_lds_dwordx4 v[148:149], off
	s_add_i32 m0, s55, 0x2000
	s_add_u32 s56, s22, 0x40000
	v_lshl_add_u64 v[226:227], s[22:23], 0, v[134:135]
	s_addc_u32 s57, s23, 0
	s_add_i32 s55, s58, s31
	global_load_lds_dwordx4 v[226:227], off
	v_lshl_add_u64 v[228:229], s[56:57], 0, v[0:1]
	s_mov_b32 m0, s55
	v_lshl_add_u64 v[230:231], s[24:25], 0, v[132:133]
	global_load_lds_dwordx4 v[228:229], off
	v_lshl_add_u64 v[228:229], s[56:57], 0, v[134:135]
	s_add_i32 m0, s55, 0x2000
	s_nop 0
	global_load_lds_dwordx4 v[228:229], off
	v_lshl_add_u64 v[228:229], s[24:25], 0, v[130:131]
	s_mov_b32 m0, s19
	s_nop 0
	global_load_lds_dwordx4 v[228:229], off
	s_mov_b32 m0, s37
	s_nop 0
	global_load_lds_dwordx4 v[230:231], off
	s_cmp_lg_u32 s98, 0
	s_cbranch_scc1 .Lrelax_ff1_w2
	s_waitcnt vmcnt(8)
.Lback_ff1_w2:
	s_waitcnt lgkmcnt(0)
	s_barrier
	s_setprio 1
	s_waitcnt lgkmcnt(0)
	v_mfma_f32_16x16x32_bf16 v[62:65], v[140:143], v[186:189], v[62:65]
	v_mfma_f32_16x16x32_bf16 v[58:61], v[154:157], v[186:189], v[58:61]
	v_mfma_f32_16x16x32_bf16 v[46:49], v[140:143], v[194:197], v[46:49]
	v_mfma_f32_16x16x32_bf16 v[42:45], v[154:157], v[194:197], v[42:45]
	v_mfma_f32_16x16x32_bf16 v[30:33], v[140:143], v[202:205], v[30:33]
	v_mfma_f32_16x16x32_bf16 v[26:29], v[154:157], v[202:205], v[26:29]
	v_mfma_f32_16x16x32_bf16 v[14:17], v[140:143], v[210:213], v[14:17]
	v_mfma_f32_16x16x32_bf16 v[10:13], v[154:157], v[210:213], v[10:13]
	v_mfma_f32_16x16x32_bf16 v[62:65], v[144:147], v[190:193], v[62:65]
	v_mfma_f32_16x16x32_bf16 v[58:61], v[166:169], v[190:193], v[58:61]
	v_mfma_f32_16x16x32_bf16 v[46:49], v[144:147], v[198:201], v[46:49]
	v_mfma_f32_16x16x32_bf16 v[42:45], v[166:169], v[198:201], v[42:45]
	v_mfma_f32_16x16x32_bf16 v[30:33], v[144:147], v[206:209], v[30:33]
	v_mfma_f32_16x16x32_bf16 v[26:29], v[166:169], v[206:209], v[26:29]
	v_mfma_f32_16x16x32_bf16 v[14:17], v[144:147], v[222:225], v[14:17]
	v_mfma_f32_16x16x32_bf16 v[10:13], v[166:169], v[222:225], v[10:13]
	s_setprio 0
	s_setprio 1
	v_mfma_f32_16x16x32_bf16 v[54:57], v[170:173], v[186:189], v[54:57]
	v_mfma_f32_16x16x32_bf16 v[50:53], v[178:181], v[186:189], v[50:53]
	v_mfma_f32_16x16x32_bf16 v[38:41], v[170:173], v[194:197], v[38:41]
	v_mfma_f32_16x16x32_bf16 v[34:37], v[178:181], v[194:197], v[34:37]
	v_mfma_f32_16x16x32_bf16 v[22:25], v[170:173], v[202:205], v[22:25]
	v_mfma_f32_16x16x32_bf16 v[18:21], v[178:181], v[202:205], v[18:21]
	v_mfma_f32_16x16x32_bf16 v[6:9], v[170:173], v[210:213], v[6:9]
	v_mfma_f32_16x16x32_bf16 v[2:5], v[178:181], v[210:213], v[2:5]
	v_mfma_f32_16x16x32_bf16 v[54:57], v[174:177], v[190:193], v[54:57]
	v_mfma_f32_16x16x32_bf16 v[50:53], v[182:185], v[190:193], v[50:53]
	v_mfma_f32_16x16x32_bf16 v[38:41], v[174:177], v[198:201], v[38:41]
	v_mfma_f32_16x16x32_bf16 v[34:37], v[182:185], v[198:201], v[34:37]
	v_mfma_f32_16x16x32_bf16 v[22:25], v[174:177], v[206:209], v[22:25]
	v_mfma_f32_16x16x32_bf16 v[18:21], v[182:185], v[206:209], v[18:21]
	v_mfma_f32_16x16x32_bf16 v[6:9], v[174:177], v[222:225], v[6:9]
	v_mfma_f32_16x16x32_bf16 v[2:5], v[182:185], v[222:225], v[2:5]
	s_setprio 0
	s_barrier
	s_add_i32 s55, 0, 0x18000
	v_add_u32_e32 v165, s55, v162
	s_add_i32 s56, 0, 0x1c000
	ds_read_b128 v[140:143], v165
	ds_read_b128 v[144:147], v165 offset:1024
	ds_read_b128 v[154:157], v165 offset:2048
	ds_read_b128 v[166:169], v165 offset:3072
	v_add_u32_e32 v165, s56, v162
	ds_read_b128 v[170:173], v165
	ds_read_b128 v[174:177], v165 offset:1024
	ds_read_b128 v[178:181], v165 offset:2048
	ds_read_b128 v[182:185], v165 offset:3072
	s_add_u32 s24, s24, 0x40000
	s_addc_u32 s25, s25, 0
	s_mov_b32 m0, s38
	v_lshl_add_u64 v[232:233], s[24:25], 0, v[130:131]
	ds_read_b128 v[186:189], v164 offset:32768
	ds_read_b128 v[190:193], v164 offset:33792
	ds_read_b128 v[194:197], v164 offset:34816
	ds_read_b128 v[198:201], v164 offset:35840
	ds_read_b128 v[202:205], v164 offset:36864
	ds_read_b128 v[206:209], v164 offset:37888
	ds_read_b128 v[210:213], v164 offset:38912
	ds_read_b128 v[222:225], v164 offset:39936
	global_load_lds_dwordx4 v[232:233], off
	v_lshl_add_u64 v[232:233], s[24:25], 0, v[132:133]
	s_mov_b32 m0, s39
	s_nop 0
	global_load_lds_dwordx4 v[232:233], off
	s_waitcnt vmcnt(8)
	s_waitcnt lgkmcnt(0)
	s_barrier
	s_setprio 1
	s_waitcnt lgkmcnt(0)
	v_mfma_f32_16x16x32_bf16 v[126:129], v[140:143], v[186:189], v[126:129]
	v_mfma_f32_16x16x32_bf16 v[122:125], v[154:157], v[186:189], v[122:125]
	v_mfma_f32_16x16x32_bf16 v[110:113], v[140:143], v[194:197], v[110:113]
	v_mfma_f32_16x16x32_bf16 v[106:109], v[154:157], v[194:197], v[106:109]
	v_mfma_f32_16x16x32_bf16 v[94:97], v[140:143], v[202:205], v[94:97]
	v_mfma_f32_16x16x32_bf16 v[90:93], v[154:157], v[202:205], v[90:93]
	v_mfma_f32_16x16x32_bf16 v[78:81], v[140:143], v[210:213], v[78:81]
	v_mfma_f32_16x16x32_bf16 v[74:77], v[154:157], v[210:213], v[74:77]
	v_mfma_f32_16x16x32_bf16 v[126:129], v[144:147], v[190:193], v[126:129]
	v_mfma_f32_16x16x32_bf16 v[122:125], v[166:169], v[190:193], v[122:125]
	v_mfma_f32_16x16x32_bf16 v[110:113], v[144:147], v[198:201], v[110:113]
	v_mfma_f32_16x16x32_bf16 v[106:109], v[166:169], v[198:201], v[106:109]
	v_mfma_f32_16x16x32_bf16 v[94:97], v[144:147], v[206:209], v[94:97]
	v_mfma_f32_16x16x32_bf16 v[90:93], v[166:169], v[206:209], v[90:93]
	v_mfma_f32_16x16x32_bf16 v[78:81], v[144:147], v[222:225], v[78:81]
	v_mfma_f32_16x16x32_bf16 v[74:77], v[166:169], v[222:225], v[74:77]
	s_setprio 0
	s_setprio 1
	v_mfma_f32_16x16x32_bf16 v[118:121], v[170:173], v[186:189], v[118:121]
	v_mfma_f32_16x16x32_bf16 v[114:117], v[178:181], v[186:189], v[114:117]
	v_mfma_f32_16x16x32_bf16 v[102:105], v[170:173], v[194:197], v[102:105]
	v_mfma_f32_16x16x32_bf16 v[98:101], v[178:181], v[194:197], v[98:101]
	v_mfma_f32_16x16x32_bf16 v[86:89], v[170:173], v[202:205], v[86:89]
	v_mfma_f32_16x16x32_bf16 v[82:85], v[178:181], v[202:205], v[82:85]
	v_mfma_f32_16x16x32_bf16 v[70:73], v[170:173], v[210:213], v[70:73]
	v_mfma_f32_16x16x32_bf16 v[66:69], v[178:181], v[210:213], v[66:69]
	v_mfma_f32_16x16x32_bf16 v[118:121], v[174:177], v[190:193], v[118:121]
	v_mfma_f32_16x16x32_bf16 v[114:117], v[182:185], v[190:193], v[114:117]
	v_mfma_f32_16x16x32_bf16 v[102:105], v[174:177], v[198:201], v[102:105]
	v_mfma_f32_16x16x32_bf16 v[98:101], v[182:185], v[198:201], v[98:101]
	v_mfma_f32_16x16x32_bf16 v[86:89], v[174:177], v[206:209], v[86:89]
	v_mfma_f32_16x16x32_bf16 v[82:85], v[182:185], v[206:209], v[82:85]
	v_mfma_f32_16x16x32_bf16 v[70:73], v[174:177], v[222:225], v[70:73]
	v_mfma_f32_16x16x32_bf16 v[66:69], v[182:185], v[222:225], v[66:69]
	s_setprio 0
	s_barrier
	s_add_i32 s24, s55, s31
	v_lshl_add_u64 v[148:149], v[148:149], 0, s[96:97]
	s_mov_b32 m0, s24
	ds_read_b128 v[186:189], v164 offset:49152
	ds_read_b128 v[190:193], v164 offset:50176
	ds_read_b128 v[194:197], v164 offset:51200
	ds_read_b128 v[198:201], v164 offset:52224
	ds_read_b128 v[202:205], v164 offset:53248
	ds_read_b128 v[206:209], v164 offset:54272
	ds_read_b128 v[210:213], v164 offset:55296
	ds_read_b128 v[222:225], v164 offset:56320
	global_load_lds_dwordx4 v[148:149], off
	s_add_i32 m0, s24, 0x2000
	s_add_u32 s22, s22, 0x40080
	v_lshl_add_u64 v[148:149], v[226:227], 0, s[96:97]
	s_addc_u32 s23, s23, 0
	s_add_i32 s24, s56, s31
	global_load_lds_dwordx4 v[148:149], off
	v_lshl_add_u64 v[148:149], s[22:23], 0, v[0:1]
	s_mov_b32 m0, s24
	s_nop 0
	global_load_lds_dwordx4 v[148:149], off
	v_lshl_add_u64 v[148:149], s[22:23], 0, v[134:135]
	s_add_i32 m0, s24, 0x2000
	s_nop 0
	global_load_lds_dwordx4 v[148:149], off
	v_lshl_add_u64 v[148:149], v[228:229], 0, s[96:97]
	s_mov_b32 m0, s40
	s_nop 0
	global_load_lds_dwordx4 v[148:149], off
	v_lshl_add_u64 v[148:149], v[230:231], 0, s[96:97]
	s_mov_b32 m0, s41
	s_nop 0
	global_load_lds_dwordx4 v[148:149], off
	s_waitcnt vmcnt(8)
	s_waitcnt lgkmcnt(0)
	s_barrier
	s_setprio 1
	s_waitcnt lgkmcnt(0)
	v_mfma_f32_16x16x32_bf16 v[62:65], v[140:143], v[186:189], v[62:65]
	v_mfma_f32_16x16x32_bf16 v[58:61], v[154:157], v[186:189], v[58:61]
	v_mfma_f32_16x16x32_bf16 v[46:49], v[140:143], v[194:197], v[46:49]
	v_mfma_f32_16x16x32_bf16 v[42:45], v[154:157], v[194:197], v[42:45]
	v_mfma_f32_16x16x32_bf16 v[30:33], v[140:143], v[202:205], v[30:33]
	v_mfma_f32_16x16x32_bf16 v[26:29], v[154:157], v[202:205], v[26:29]
	v_mfma_f32_16x16x32_bf16 v[14:17], v[140:143], v[210:213], v[14:17]
	v_mfma_f32_16x16x32_bf16 v[10:13], v[154:157], v[210:213], v[10:13]
	v_mfma_f32_16x16x32_bf16 v[62:65], v[144:147], v[190:193], v[62:65]
	v_mfma_f32_16x16x32_bf16 v[58:61], v[166:169], v[190:193], v[58:61]
	v_mfma_f32_16x16x32_bf16 v[46:49], v[144:147], v[198:201], v[46:49]
	v_mfma_f32_16x16x32_bf16 v[42:45], v[166:169], v[198:201], v[42:45]
	v_mfma_f32_16x16x32_bf16 v[30:33], v[144:147], v[206:209], v[30:33]
	v_mfma_f32_16x16x32_bf16 v[26:29], v[166:169], v[206:209], v[26:29]
	v_mfma_f32_16x16x32_bf16 v[14:17], v[144:147], v[222:225], v[14:17]
	v_mfma_f32_16x16x32_bf16 v[10:13], v[166:169], v[222:225], v[10:13]
	s_setprio 0
	s_setprio 1
	v_mfma_f32_16x16x32_bf16 v[54:57], v[170:173], v[186:189], v[54:57]
	v_mfma_f32_16x16x32_bf16 v[50:53], v[178:181], v[186:189], v[50:53]
	v_mfma_f32_16x16x32_bf16 v[38:41], v[170:173], v[194:197], v[38:41]
	v_mfma_f32_16x16x32_bf16 v[34:37], v[178:181], v[194:197], v[34:37]
	v_mfma_f32_16x16x32_bf16 v[22:25], v[170:173], v[202:205], v[22:25]
	v_mfma_f32_16x16x32_bf16 v[18:21], v[178:181], v[202:205], v[18:21]
	v_mfma_f32_16x16x32_bf16 v[6:9], v[170:173], v[210:213], v[6:9]
	v_mfma_f32_16x16x32_bf16 v[2:5], v[178:181], v[210:213], v[2:5]
	v_mfma_f32_16x16x32_bf16 v[54:57], v[174:177], v[190:193], v[54:57]
	v_mfma_f32_16x16x32_bf16 v[50:53], v[182:185], v[190:193], v[50:53]
	v_mfma_f32_16x16x32_bf16 v[38:41], v[174:177], v[198:201], v[38:41]
	v_mfma_f32_16x16x32_bf16 v[34:37], v[182:185], v[198:201], v[34:37]
	v_mfma_f32_16x16x32_bf16 v[22:25], v[174:177], v[206:209], v[22:25]
	v_mfma_f32_16x16x32_bf16 v[18:21], v[182:185], v[206:209], v[18:21]
	v_mfma_f32_16x16x32_bf16 v[6:9], v[174:177], v[222:225], v[6:9]
	v_mfma_f32_16x16x32_bf16 v[2:5], v[182:185], v[222:225], v[2:5]
	s_setprio 0
	s_barrier
	s_add_i32 s49, s49, 2
	s_add_u32 s47, s47, 0x100
	s_addc_u32 s48, s48, 0
	s_add_u32 s20, s20, 0x100
	s_addc_u32 s21, s21, 0
	s_cmp_gt_u32 s49, 13
	s_cbranch_scc0 .LBB0_43
	s_and_b64 vcc, exec, s[8:9]
	s_movk_i32 s46, 0xd000
	s_movk_i32 s47, 0xec00
	s_cbranch_vccz .LBB0_46
	s_barrier
.LBB0_46:
	v_lshl_add_u32 v144, s18, 8, v159
	v_lshl_or_b32 v140, s44, 8, v163
	v_ashrrev_i32_e32 v141, 31, v140
	v_ashrrev_i32_e32 v145, 31, v144
	v_pk_add_f32 v[128:129], v[128:129], 0 op_sel_hi:[1,0]
	v_pk_add_f32 v[126:127], v[126:127], 0 op_sel_hi:[1,0]
	v_pk_add_f32 v[124:125], v[124:125], 0 op_sel_hi:[1,0]
	v_pk_add_f32 v[122:123], v[122:123], 0 op_sel_hi:[1,0]
	v_lshl_add_u64 v[142:143], v[140:141], 1, s[6:7]
	v_lshlrev_b64 v[140:141], 13, v[144:145]
	v_max_f32_e32 v127, 0, v127
	v_max_f32_e32 v126, 0, v126
	v_max_f32_e32 v129, 0, v129
	v_max_f32_e32 v128, 0, v128
	v_max_f32_e32 v123, 0, v123
	v_max_f32_e32 v122, 0, v122
	v_max_f32_e32 v125, 0, v125
	v_max_f32_e32 v124, 0, v124
	v_pk_add_f32 v[118:119], v[118:119], 0 op_sel_hi:[1,0]
	v_pk_add_f32 v[116:117], v[116:117], 0 op_sel_hi:[1,0]
	v_pk_add_f32 v[114:115], v[114:115], 0 op_sel_hi:[1,0]
	v_lshl_add_u64 v[140:141], v[142:143], 0, v[140:141]
	v_pk_mul_f32 v[128:129], v[128:129], v[128:129]
	v_pk_mul_f32 v[126:127], v[126:127], v[126:127]
	v_pk_mul_f32 v[146:147], v[124:125], v[124:125]
	v_pk_mul_f32 v[124:125], v[122:123], v[122:123]
	v_cvt_pk_bf16_f32 v122, v126, v127
	v_cvt_pk_bf16_f32 v123, v128, v129
	v_pk_add_f32 v[120:121], v[120:121], 0 op_sel_hi:[1,0]
	v_max_f32_e32 v119, 0, v119
	v_max_f32_e32 v118, 0, v118
	v_max_f32_e32 v115, 0, v115
	v_max_f32_e32 v114, 0, v114
	v_max_f32_e32 v117, 0, v117
	v_max_f32_e32 v116, 0, v116
	v_cvt_pk_bf16_f32 v124, v124, v125
	v_cvt_pk_bf16_f32 v125, v146, v147
	global_store_dwordx4 v[140:141], v[122:125], off nt
	v_max_f32_e32 v121, 0, v121
	v_max_f32_e32 v120, 0, v120
	v_pk_mul_f32 v[118:119], v[118:119], v[118:119]
	v_pk_mul_f32 v[122:123], v[116:117], v[116:117]
	v_pk_mul_f32 v[116:117], v[114:115], v[114:115]
	v_cvt_pk_bf16_f32 v114, v118, v119
	v_pk_mul_f32 v[120:121], v[120:121], v[120:121]
	v_pk_add_f32 v[112:113], v[112:113], 0 op_sel_hi:[1,0]
	v_cvt_pk_bf16_f32 v115, v120, v121
	v_cvt_pk_bf16_f32 v116, v116, v117
	v_cvt_pk_bf16_f32 v117, v122, v123
	global_store_dwordx4 v[140:141], v[114:117], off offset:256 nt
	v_pk_add_f32 v[110:111], v[110:111], 0 op_sel_hi:[1,0]
	v_pk_add_f32 v[108:109], v[108:109], 0 op_sel_hi:[1,0]
	v_or_b32_e32 v114, 16, v144
	v_ashrrev_i32_e32 v115, 31, v114
	v_pk_add_f32 v[106:107], v[106:107], 0 op_sel_hi:[1,0]
	v_lshlrev_b64 v[114:115], 13, v[114:115]
	v_max_f32_e32 v111, 0, v111
	v_max_f32_e32 v110, 0, v110
	v_max_f32_e32 v113, 0, v113
	v_max_f32_e32 v112, 0, v112
	v_max_f32_e32 v107, 0, v107
	v_max_f32_e32 v106, 0, v106
	v_max_f32_e32 v109, 0, v109
	v_max_f32_e32 v108, 0, v108
	v_pk_add_f32 v[102:103], v[102:103], 0 op_sel_hi:[1,0]
	v_pk_add_f32 v[100:101], v[100:101], 0 op_sel_hi:[1,0]
	v_pk_add_f32 v[98:99], v[98:99], 0 op_sel_hi:[1,0]
	v_lshl_add_u64 v[114:115], v[142:143], 0, v[114:115]
	v_pk_mul_f32 v[112:113], v[112:113], v[112:113]
	v_pk_mul_f32 v[110:111], v[110:111], v[110:111]
	v_pk_mul_f32 v[116:117], v[108:109], v[108:109]
	v_pk_mul_f32 v[108:109], v[106:107], v[106:107]
	v_cvt_pk_bf16_f32 v106, v110, v111
	v_cvt_pk_bf16_f32 v107, v112, v113
	v_pk_add_f32 v[104:105], v[104:105], 0 op_sel_hi:[1,0]
	v_max_f32_e32 v103, 0, v103
	v_max_f32_e32 v102, 0, v102
	v_max_f32_e32 v99, 0, v99
	v_max_f32_e32 v98, 0, v98
	v_max_f32_e32 v101, 0, v101
	v_max_f32_e32 v100, 0, v100
	v_cvt_pk_bf16_f32 v108, v108, v109
	v_cvt_pk_bf16_f32 v109, v116, v117
	global_store_dwordx4 v[114:115], v[106:109], off nt
	v_max_f32_e32 v105, 0, v105
	v_max_f32_e32 v104, 0, v104
	v_pk_mul_f32 v[102:103], v[102:103], v[102:103]
	v_pk_mul_f32 v[106:107], v[100:101], v[100:101]
	v_pk_mul_f32 v[100:101], v[98:99], v[98:99]
	v_cvt_pk_bf16_f32 v98, v102, v103
	v_pk_mul_f32 v[104:105], v[104:105], v[104:105]
	v_pk_add_f32 v[96:97], v[96:97], 0 op_sel_hi:[1,0]
	v_cvt_pk_bf16_f32 v99, v104, v105
	v_cvt_pk_bf16_f32 v100, v100, v101
	v_cvt_pk_bf16_f32 v101, v106, v107
	global_store_dwordx4 v[114:115], v[98:101], off offset:256 nt
	v_pk_add_f32 v[94:95], v[94:95], 0 op_sel_hi:[1,0]
	v_pk_add_f32 v[92:93], v[92:93], 0 op_sel_hi:[1,0]
	v_or_b32_e32 v98, 32, v144
	v_ashrrev_i32_e32 v99, 31, v98
	v_pk_add_f32 v[90:91], v[90:91], 0 op_sel_hi:[1,0]
	v_lshlrev_b64 v[98:99], 13, v[98:99]
	v_max_f32_e32 v95, 0, v95
	v_max_f32_e32 v94, 0, v94
	v_max_f32_e32 v97, 0, v97
	v_max_f32_e32 v96, 0, v96
	v_max_f32_e32 v91, 0, v91
	v_max_f32_e32 v90, 0, v90
	v_max_f32_e32 v93, 0, v93
	v_max_f32_e32 v92, 0, v92
	v_pk_add_f32 v[86:87], v[86:87], 0 op_sel_hi:[1,0]
	v_pk_add_f32 v[84:85], v[84:85], 0 op_sel_hi:[1,0]
	v_pk_add_f32 v[82:83], v[82:83], 0 op_sel_hi:[1,0]
	v_lshl_add_u64 v[98:99], v[142:143], 0, v[98:99]
	v_pk_mul_f32 v[96:97], v[96:97], v[96:97]
	v_pk_mul_f32 v[94:95], v[94:95], v[94:95]
	v_pk_mul_f32 v[100:101], v[92:93], v[92:93]
	v_pk_mul_f32 v[92:93], v[90:91], v[90:91]
	v_cvt_pk_bf16_f32 v90, v94, v95
	v_cvt_pk_bf16_f32 v91, v96, v97
	v_pk_add_f32 v[88:89], v[88:89], 0 op_sel_hi:[1,0]
	v_max_f32_e32 v87, 0, v87
	v_max_f32_e32 v86, 0, v86
	v_max_f32_e32 v83, 0, v83
	v_max_f32_e32 v82, 0, v82
	v_max_f32_e32 v85, 0, v85
	v_max_f32_e32 v84, 0, v84
	v_cvt_pk_bf16_f32 v92, v92, v93
	v_cvt_pk_bf16_f32 v93, v100, v101
	global_store_dwordx4 v[98:99], v[90:93], off nt
	v_max_f32_e32 v89, 0, v89
	v_max_f32_e32 v88, 0, v88
	v_pk_mul_f32 v[86:87], v[86:87], v[86:87]
	v_pk_mul_f32 v[90:91], v[84:85], v[84:85]
	v_pk_mul_f32 v[84:85], v[82:83], v[82:83]
	v_cvt_pk_bf16_f32 v82, v86, v87
	v_pk_mul_f32 v[88:89], v[88:89], v[88:89]
	v_pk_add_f32 v[80:81], v[80:81], 0 op_sel_hi:[1,0]
	v_cvt_pk_bf16_f32 v83, v88, v89
	v_cvt_pk_bf16_f32 v84, v84, v85
	v_cvt_pk_bf16_f32 v85, v90, v91
	global_store_dwordx4 v[98:99], v[82:85], off offset:256 nt
	v_pk_add_f32 v[78:79], v[78:79], 0 op_sel_hi:[1,0]
	v_pk_add_f32 v[76:77], v[76:77], 0 op_sel_hi:[1,0]
	v_or_b32_e32 v82, 48, v144
	v_ashrrev_i32_e32 v83, 31, v82
	v_pk_add_f32 v[74:75], v[74:75], 0 op_sel_hi:[1,0]
	v_lshlrev_b64 v[82:83], 13, v[82:83]
	v_max_f32_e32 v79, 0, v79
	v_max_f32_e32 v78, 0, v78
	v_max_f32_e32 v81, 0, v81
	v_max_f32_e32 v80, 0, v80
	v_max_f32_e32 v75, 0, v75
	v_max_f32_e32 v74, 0, v74
	v_max_f32_e32 v77, 0, v77
	v_max_f32_e32 v76, 0, v76
	v_pk_add_f32 v[68:69], v[68:69], 0 op_sel_hi:[1,0]
	v_pk_add_f32 v[66:67], v[66:67], 0 op_sel_hi:[1,0]
	v_lshl_add_u64 v[82:83], v[142:143], 0, v[82:83]
	v_pk_mul_f32 v[80:81], v[80:81], v[80:81]
	v_pk_mul_f32 v[78:79], v[78:79], v[78:79]
	v_pk_mul_f32 v[84:85], v[76:77], v[76:77]
	v_pk_mul_f32 v[76:77], v[74:75], v[74:75]
	v_cvt_pk_bf16_f32 v74, v78, v79
	v_cvt_pk_bf16_f32 v75, v80, v81
	v_pk_add_f32 v[72:73], v[72:73], 0 op_sel_hi:[1,0]
	v_pk_add_f32 v[70:71], v[70:71], 0 op_sel_hi:[1,0]
	v_max_f32_e32 v67, 0, v67
	v_max_f32_e32 v66, 0, v66
	v_max_f32_e32 v69, 0, v69
	v_max_f32_e32 v68, 0, v68
	v_pk_add_f32 v[62:63], v[62:63], 0 op_sel_hi:[1,0]
	v_cvt_pk_bf16_f32 v76, v76, v77
	v_cvt_pk_bf16_f32 v77, v84, v85
	global_store_dwordx4 v[82:83], v[74:77], off nt
	v_max_f32_e32 v71, 0, v71
	v_max_f32_e32 v70, 0, v70
	v_max_f32_e32 v73, 0, v73
	v_max_f32_e32 v72, 0, v72
	v_pk_mul_f32 v[74:75], v[68:69], v[68:69]
	v_pk_mul_f32 v[68:69], v[66:67], v[66:67]
	v_pk_add_f32 v[60:61], v[60:61], 0 op_sel_hi:[1,0]
	v_pk_add_f32 v[58:59], v[58:59], 0 op_sel_hi:[1,0]
	v_max_f32_e32 v63, 0, v63
	v_max_f32_e32 v62, 0, v62
	v_pk_mul_f32 v[72:73], v[72:73], v[72:73]
	v_pk_mul_f32 v[70:71], v[70:71], v[70:71]
	v_pk_add_f32 v[64:65], v[64:65], 0 op_sel_hi:[1,0]
	v_cvt_pk_bf16_f32 v66, v70, v71
	v_cvt_pk_bf16_f32 v67, v72, v73
	v_cvt_pk_bf16_f32 v68, v68, v69
	v_cvt_pk_bf16_f32 v69, v74, v75
	v_max_f32_e32 v59, 0, v59
	v_max_f32_e32 v58, 0, v58
	v_max_f32_e32 v61, 0, v61
	v_max_f32_e32 v60, 0, v60
	v_pk_mul_f32 v[62:63], v[62:63], v[62:63]
	s_mov_b32 s11, 0x100000
	global_store_dwordx4 v[82:83], v[66:69], off offset:256 nt
	v_max_f32_e32 v65, 0, v65
	v_max_f32_e32 v64, 0, v64
	v_pk_mul_f32 v[68:69], v[60:61], v[60:61]
	v_pk_mul_f32 v[60:61], v[58:59], v[58:59]
	v_cvt_pk_bf16_f32 v58, v62, v63
	v_add_co_u32_e32 v62, vcc, s11, v140
	v_pk_add_f32 v[52:53], v[52:53], 0 op_sel_hi:[1,0]
	v_pk_add_f32 v[50:51], v[50:51], 0 op_sel_hi:[1,0]
	v_pk_mul_f32 v[64:65], v[64:65], v[64:65]
	v_addc_co_u32_e32 v63, vcc, 0, v141, vcc
	v_cvt_pk_bf16_f32 v59, v64, v65
	v_pk_add_f32 v[56:57], v[56:57], 0 op_sel_hi:[1,0]
	v_pk_add_f32 v[54:55], v[54:55], 0 op_sel_hi:[1,0]
	v_max_f32_e32 v51, 0, v51
	v_max_f32_e32 v50, 0, v50
	v_max_f32_e32 v53, 0, v53
	v_max_f32_e32 v52, 0, v52
	v_pk_add_f32 v[46:47], v[46:47], 0 op_sel_hi:[1,0]
	s_mov_b64 s[20:21], 0x100000
	v_cvt_pk_bf16_f32 v60, v60, v61
	v_cvt_pk_bf16_f32 v61, v68, v69
	global_store_dwordx4 v[62:63], v[58:61], off nt
	v_max_f32_e32 v55, 0, v55
	v_max_f32_e32 v54, 0, v54
	v_max_f32_e32 v57, 0, v57
	v_max_f32_e32 v56, 0, v56
	v_pk_mul_f32 v[58:59], v[52:53], v[52:53]
	v_pk_mul_f32 v[52:53], v[50:51], v[50:51]
	v_pk_add_f32 v[44:45], v[44:45], 0 op_sel_hi:[1,0]
	v_pk_add_f32 v[42:43], v[42:43], 0 op_sel_hi:[1,0]
	v_max_f32_e32 v47, 0, v47
	v_max_f32_e32 v46, 0, v46
	v_lshl_add_u64 v[66:67], v[140:141], 0, s[20:21]
	v_pk_mul_f32 v[56:57], v[56:57], v[56:57]
	v_pk_mul_f32 v[54:55], v[54:55], v[54:55]
	v_pk_add_f32 v[48:49], v[48:49], 0 op_sel_hi:[1,0]
	v_cvt_pk_bf16_f32 v50, v54, v55
	v_cvt_pk_bf16_f32 v51, v56, v57
	v_cvt_pk_bf16_f32 v52, v52, v53
	v_cvt_pk_bf16_f32 v53, v58, v59
	v_max_f32_e32 v43, 0, v43
	v_max_f32_e32 v42, 0, v42
	v_max_f32_e32 v45, 0, v45
	v_max_f32_e32 v44, 0, v44
	v_pk_mul_f32 v[46:47], v[46:47], v[46:47]
	s_mov_b32 s11, 0x120000
	global_store_dwordx4 v[66:67], v[50:53], off offset:256 nt
	v_max_f32_e32 v49, 0, v49
	v_max_f32_e32 v48, 0, v48
	v_pk_mul_f32 v[52:53], v[44:45], v[44:45]
	v_pk_mul_f32 v[44:45], v[42:43], v[42:43]
	v_cvt_pk_bf16_f32 v42, v46, v47
	v_add_co_u32_e32 v46, vcc, s11, v140
	v_pk_add_f32 v[36:37], v[36:37], 0 op_sel_hi:[1,0]
	v_pk_add_f32 v[34:35], v[34:35], 0 op_sel_hi:[1,0]
	v_pk_mul_f32 v[48:49], v[48:49], v[48:49]
	v_addc_co_u32_e32 v47, vcc, 0, v141, vcc
	v_cvt_pk_bf16_f32 v43, v48, v49
	v_pk_add_f32 v[40:41], v[40:41], 0 op_sel_hi:[1,0]
	v_pk_add_f32 v[38:39], v[38:39], 0 op_sel_hi:[1,0]
	v_max_f32_e32 v35, 0, v35
	v_max_f32_e32 v34, 0, v34
	v_max_f32_e32 v37, 0, v37
	v_max_f32_e32 v36, 0, v36
	v_pk_add_f32 v[30:31], v[30:31], 0 op_sel_hi:[1,0]
	s_mov_b64 s[20:21], 0x120000
	v_cvt_pk_bf16_f32 v44, v44, v45
	v_cvt_pk_bf16_f32 v45, v52, v53
	global_store_dwordx4 v[46:47], v[42:45], off nt
	v_max_f32_e32 v39, 0, v39
	v_max_f32_e32 v38, 0, v38
	v_max_f32_e32 v41, 0, v41
	v_max_f32_e32 v40, 0, v40
	v_pk_mul_f32 v[42:43], v[36:37], v[36:37]
	v_pk_mul_f32 v[36:37], v[34:35], v[34:35]
	v_pk_add_f32 v[28:29], v[28:29], 0 op_sel_hi:[1,0]
	v_pk_add_f32 v[26:27], v[26:27], 0 op_sel_hi:[1,0]
	v_max_f32_e32 v31, 0, v31
	v_max_f32_e32 v30, 0, v30
	v_lshl_add_u64 v[50:51], v[140:141], 0, s[20:21]
	v_pk_mul_f32 v[40:41], v[40:41], v[40:41]
	v_pk_mul_f32 v[38:39], v[38:39], v[38:39]
	v_pk_add_f32 v[32:33], v[32:33], 0 op_sel_hi:[1,0]
	v_cvt_pk_bf16_f32 v34, v38, v39
	v_cvt_pk_bf16_f32 v35, v40, v41
	v_cvt_pk_bf16_f32 v36, v36, v37
	v_cvt_pk_bf16_f32 v37, v42, v43
	v_max_f32_e32 v27, 0, v27
	v_max_f32_e32 v26, 0, v26
	v_max_f32_e32 v29, 0, v29
	v_max_f32_e32 v28, 0, v28
	v_pk_mul_f32 v[30:31], v[30:31], v[30:31]
	s_mov_b32 s11, 0x140000
	global_store_dwordx4 v[50:51], v[34:37], off offset:256 nt
	v_max_f32_e32 v33, 0, v33
	v_max_f32_e32 v32, 0, v32
	v_pk_mul_f32 v[36:37], v[28:29], v[28:29]
	v_pk_mul_f32 v[28:29], v[26:27], v[26:27]
	v_cvt_pk_bf16_f32 v26, v30, v31
	v_add_co_u32_e32 v30, vcc, s11, v140
	v_pk_add_f32 v[20:21], v[20:21], 0 op_sel_hi:[1,0]
	v_pk_add_f32 v[18:19], v[18:19], 0 op_sel_hi:[1,0]
	v_pk_mul_f32 v[32:33], v[32:33], v[32:33]
	v_addc_co_u32_e32 v31, vcc, 0, v141, vcc
	v_cvt_pk_bf16_f32 v27, v32, v33
	v_pk_add_f32 v[24:25], v[24:25], 0 op_sel_hi:[1,0]
	v_pk_add_f32 v[22:23], v[22:23], 0 op_sel_hi:[1,0]
	v_max_f32_e32 v19, 0, v19
	v_max_f32_e32 v18, 0, v18
	v_max_f32_e32 v21, 0, v21
	v_max_f32_e32 v20, 0, v20
	v_pk_add_f32 v[14:15], v[14:15], 0 op_sel_hi:[1,0]
	s_mov_b64 s[20:21], 0x140000
	v_cvt_pk_bf16_f32 v28, v28, v29
	v_cvt_pk_bf16_f32 v29, v36, v37
	global_store_dwordx4 v[30:31], v[26:29], off nt
	v_max_f32_e32 v23, 0, v23
	v_max_f32_e32 v22, 0, v22
	v_max_f32_e32 v25, 0, v25
	v_max_f32_e32 v24, 0, v24
	v_pk_mul_f32 v[26:27], v[20:21], v[20:21]
	v_pk_mul_f32 v[20:21], v[18:19], v[18:19]
	v_pk_add_f32 v[12:13], v[12:13], 0 op_sel_hi:[1,0]
	v_pk_add_f32 v[10:11], v[10:11], 0 op_sel_hi:[1,0]
	v_max_f32_e32 v15, 0, v15
	v_max_f32_e32 v14, 0, v14
	v_lshl_add_u64 v[34:35], v[140:141], 0, s[20:21]
	v_pk_mul_f32 v[24:25], v[24:25], v[24:25]
	v_pk_mul_f32 v[22:23], v[22:23], v[22:23]
	v_pk_add_f32 v[16:17], v[16:17], 0 op_sel_hi:[1,0]
	v_cvt_pk_bf16_f32 v18, v22, v23
	v_cvt_pk_bf16_f32 v19, v24, v25
	v_cvt_pk_bf16_f32 v20, v20, v21
	v_cvt_pk_bf16_f32 v21, v26, v27
	v_max_f32_e32 v11, 0, v11
	v_max_f32_e32 v10, 0, v10
	v_max_f32_e32 v13, 0, v13
	v_max_f32_e32 v12, 0, v12
	v_pk_mul_f32 v[14:15], v[14:15], v[14:15]
	s_mov_b32 s11, 0x160000
	global_store_dwordx4 v[34:35], v[18:21], off offset:256 nt
	v_max_f32_e32 v17, 0, v17
	v_max_f32_e32 v16, 0, v16
	v_pk_mul_f32 v[20:21], v[12:13], v[12:13]
	v_pk_mul_f32 v[12:13], v[10:11], v[10:11]
	v_cvt_pk_bf16_f32 v10, v14, v15
	v_add_co_u32_e32 v14, vcc, s11, v140
	v_pk_add_f32 v[4:5], v[4:5], 0 op_sel_hi:[1,0]
	v_pk_add_f32 v[2:3], v[2:3], 0 op_sel_hi:[1,0]
	s_mov_b64 s[20:21], 0x160000
	v_pk_mul_f32 v[16:17], v[16:17], v[16:17]
	v_addc_co_u32_e32 v15, vcc, 0, v141, vcc
	v_cvt_pk_bf16_f32 v11, v16, v17
	v_pk_add_f32 v[8:9], v[8:9], 0 op_sel_hi:[1,0]
	v_pk_add_f32 v[6:7], v[6:7], 0 op_sel_hi:[1,0]
	v_max_f32_e32 v3, 0, v3
	v_max_f32_e32 v2, 0, v2
	v_max_f32_e32 v5, 0, v5
	v_max_f32_e32 v4, 0, v4
	v_lshl_add_u64 v[18:19], v[140:141], 0, s[20:21]
	v_cvt_pk_bf16_f32 v12, v12, v13
	v_cvt_pk_bf16_f32 v13, v20, v21
	global_store_dwordx4 v[14:15], v[10:13], off nt
	v_max_f32_e32 v7, 0, v7
	v_max_f32_e32 v6, 0, v6
	v_max_f32_e32 v9, 0, v9
	v_max_f32_e32 v8, 0, v8
	v_pk_mul_f32 v[10:11], v[4:5], v[4:5]
	v_pk_mul_f32 v[4:5], v[2:3], v[2:3]
	s_andn2_b64 vcc, exec, s[0:1]
	s_mov_b64 s[0:1], -1
	s_movk_i32 s55, 0xf000
	v_pk_mul_f32 v[8:9], v[8:9], v[8:9]
	v_pk_mul_f32 v[6:7], v[6:7], v[6:7]
	s_nop 0
	v_cvt_pk_bf16_f32 v2, v6, v7
	v_cvt_pk_bf16_f32 v3, v8, v9
	v_cvt_pk_bf16_f32 v4, v4, v5
	v_cvt_pk_bf16_f32 v5, v10, v11
	global_store_dwordx4 v[18:19], v[2:5], off offset:256 nt
	s_mov_b32 s98, 1
	s_cbranch_vccnz .LBB0_35
	s_andn2_b64 vcc, exec, s[4:5]
	s_cbranch_vccnz .LBB0_34
	s_barrier
	s_branch .LBB0_34
.Lrelax_ff1_w1:
	s_waitcnt vmcnt(24)
	s_branch .Lback_ff1_w1
.Lrelax_ff1_w2:
	s_waitcnt vmcnt(24)
	s_mov_b32 s98, 0
	s_branch .Lback_ff1_w2

.LBB0_69:
	v_readlane_b32 s10, v254, 49
	s_sext_i32_i8 s44, s0
	s_mul_hi_i32 s0, s10, 0x30000
	s_mul_i32 s10, s10, 0x30000
	v_lshrrev_b32_e32 v17, 1, v158
	s_add_u32 s10, s82, s10
	v_and_b32_e32 v17, 24, v17
	s_addc_u32 s0, s83, s0
	v_and_b32_e32 v16, 15, v158
	v_lshlrev_b32_e32 v18, 1, v17
	s_add_u32 s38, s10, 0x2000
	v_lshl_or_b32 v159, s9, 6, v16
	v_lshl_or_b32 v16, v16, 6, v18
	v_lshlrev_b32_e32 v18, 2, v158
	s_addc_u32 s39, s0, 0
	s_lshl_b32 s0, s9, 13
	v_and_b32_e32 v18, 32, v18
	v_bitop3_b32 v19, v16, s0, v18 bitop3:0xde
	s_lshl_b32 s0, s1, 5
	s_and_b32 s10, s0, 0x60
	s_add_i32 m0, s19, 0x18000
	v_lshl_add_u64 v[8:9], v[8:9], 0, s[96:97]
	s_lshl_b32 s0, s10, 7
	s_waitcnt vmcnt(2)
	s_barrier
	global_load_lds_dwordx4 v[8:9], off
	v_lshl_add_u64 v[6:7], v[6:7], 0, s[96:97]
	s_add_i32 m0, s19, 0x1a000
	s_add_i32 s40, s19, 0x8000
	s_add_i32 s41, s19, 0xa000
	v_bitop3_b32 v176, s0, v16, v18 bitop3:0xf6
	global_load_lds_dwordx4 v[6:7], off
	v_lshl_add_u64 v[2:3], v[2:3], 0, s[96:97]
	s_mov_b32 m0, s40
	s_add_u32 s0, s20, 0x40080
	global_load_lds_dwordx4 v[2:3], off
	v_lshl_add_u64 v[2:3], v[4:5], 0, s[96:97]
	s_mov_b32 m0, s41
	s_addc_u32 s1, s21, 0
	global_load_lds_dwordx4 v[2:3], off
	s_add_i32 m0, s19, 0x1c000
	v_lshl_add_u64 v[2:3], s[0:1], 0, v[0:1]
	global_load_lds_dwordx4 v[2:3], off
	v_lshl_add_u64 v[2:3], s[0:1], 0, v[166:167]
	s_add_i32 m0, s19, 0x1e000
	s_cmpk_lt_u32 s8, 0x100
	global_load_lds_dwordx4 v[2:3], off
	v_lshlrev_b32_e32 v2, 14, v13
	v_and_b32_e32 v2, 0xffff8000, v2
	v_lshl_add_u32 v2, v14, 11, v2
	v_and_b32_e32 v3, 1, v13
	v_lshl_or_b32 v2, v3, 6, v2
	v_lshl_add_u32 v168, v15, 1, v2
	v_lshlrev_b32_e32 v2, 14, v10
	v_and_b32_e32 v2, 0xffff8000, v2
	s_waitcnt vmcnt(6)
	v_lshl_add_u32 v2, v11, 11, v2
	v_and_b32_e32 v3, 1, v10
	v_lshl_or_b32 v2, v3, 6, v2
	s_cselect_b64 s[8:9], -1, 0
	s_ashr_i32 s42, s36, 31
	v_or_b32_e32 v177, s10, v17
	v_mov_b32_e32 v169, v1
	v_lshl_add_u32 v170, v12, 1, v2
	v_mov_b32_e32 v171, v1
	s_mov_b32 s43, 0
	v_add_u32_e32 v178, 0, v19
	v_readlane_b32 s11, v254, 50
	s_barrier
	s_mov_b32 s98, 0
	s_branch .LBB0_72

.LBB0_79:
	s_add_u32 s22, s20, 0xfffc0080
	s_addc_u32 s23, s21, -1
	s_add_i32 s55, 0, 0x10000
	s_cmp_eq_u32 s49, 12
	s_cselect_b32 s25, s13, s23
	s_cselect_b32 s24, s45, s22
	s_cselect_b32 s23, s11, s48
	s_cselect_b32 s22, s46, s47
	s_add_i32 s58, 0, 0x14000
	v_add_u32_e32 v134, s55, v176
	v_add_u32_e32 v179, s58, v176
	ds_read_b128 v[122:125], v134
	ds_read_b128 v[126:129], v134 offset:1024
	ds_read_b128 v[130:133], v134 offset:2048
	ds_read_b128 v[134:137], v134 offset:3072
	ds_read_b128 v[146:149], v179
	ds_read_b128 v[154:157], v179 offset:1024
	ds_read_b128 v[172:175], v179 offset:2048
	ds_read_b128 v[180:183], v179 offset:3072
	v_lshl_add_u64 v[212:213], s[20:21], 0, v[170:171]
	s_add_i32 m0, s19, 0xc000
	ds_read_b128 v[184:187], v178
	ds_read_b128 v[188:191], v178 offset:1024
	ds_read_b128 v[192:195], v178 offset:2048
	ds_read_b128 v[196:199], v178 offset:3072
	ds_read_b128 v[200:203], v178 offset:4096
	ds_read_b128 v[204:207], v178 offset:5120
	ds_read_b128 v[208:211], v178 offset:6144
	ds_read_b128 v[222:225], v178 offset:7168
	global_load_lds_dwordx4 v[212:213], off
	v_lshl_add_u64 v[212:213], s[20:21], 0, v[168:169]
	s_add_i32 m0, s19, 0xe000
	s_nop 0
	global_load_lds_dwordx4 v[212:213], off
	s_cmp_lg_u32 s98, 0
	s_cbranch_scc1 .Lrelax_g2_w1
	s_waitcnt vmcnt(8)
.Lback_g2_w1:
	s_waitcnt lgkmcnt(0)
	s_barrier
	s_setprio 1
	s_waitcnt lgkmcnt(0)
	v_mfma_f32_16x16x32_bf16 v[142:145], v[122:125], v[184:187], v[142:145]
	v_mfma_f32_16x16x32_bf16 v[138:141], v[130:133], v[184:187], v[138:141]
	v_mfma_f32_16x16x32_bf16 v[118:121], v[122:125], v[192:195], v[118:121]
	v_mfma_f32_16x16x32_bf16 v[106:109], v[130:133], v[192:195], v[106:109]
	v_mfma_f32_16x16x32_bf16 v[98:101], v[122:125], v[200:203], v[98:101]
	v_mfma_f32_16x16x32_bf16 v[90:93], v[130:133], v[200:203], v[90:93]
	v_mfma_f32_16x16x32_bf16 v[86:89], v[122:125], v[208:211], v[86:89]
	v_mfma_f32_16x16x32_bf16 v[74:77], v[130:133], v[208:211], v[74:77]
	v_mfma_f32_16x16x32_bf16 v[142:145], v[126:129], v[188:191], v[142:145]
	v_mfma_f32_16x16x32_bf16 v[138:141], v[134:137], v[188:191], v[138:141]
	v_mfma_f32_16x16x32_bf16 v[118:121], v[126:129], v[196:199], v[118:121]
	v_mfma_f32_16x16x32_bf16 v[106:109], v[134:137], v[196:199], v[106:109]
	v_mfma_f32_16x16x32_bf16 v[98:101], v[126:129], v[204:207], v[98:101]
	v_mfma_f32_16x16x32_bf16 v[90:93], v[134:137], v[204:207], v[90:93]
	v_mfma_f32_16x16x32_bf16 v[86:89], v[126:129], v[222:225], v[86:89]
	v_mfma_f32_16x16x32_bf16 v[74:77], v[134:137], v[222:225], v[74:77]
	s_setprio 0
	s_setprio 1
	v_mfma_f32_16x16x32_bf16 v[114:117], v[146:149], v[184:187], v[114:117]
	v_mfma_f32_16x16x32_bf16 v[110:113], v[172:175], v[184:187], v[110:113]
	v_mfma_f32_16x16x32_bf16 v[102:105], v[146:149], v[192:195], v[102:105]
	v_mfma_f32_16x16x32_bf16 v[94:97], v[172:175], v[192:195], v[94:97]
	v_mfma_f32_16x16x32_bf16 v[82:85], v[146:149], v[200:203], v[82:85]
	v_mfma_f32_16x16x32_bf16 v[78:81], v[172:175], v[200:203], v[78:81]
	v_mfma_f32_16x16x32_bf16 v[70:73], v[146:149], v[208:211], v[70:73]
	v_mfma_f32_16x16x32_bf16 v[66:69], v[172:175], v[208:211], v[66:69]
	v_mfma_f32_16x16x32_bf16 v[114:117], v[154:157], v[188:191], v[114:117]
	v_mfma_f32_16x16x32_bf16 v[110:113], v[180:183], v[188:191], v[110:113]
	v_mfma_f32_16x16x32_bf16 v[102:105], v[154:157], v[196:199], v[102:105]
	v_mfma_f32_16x16x32_bf16 v[94:97], v[180:183], v[196:199], v[94:97]
	v_mfma_f32_16x16x32_bf16 v[82:85], v[154:157], v[204:207], v[82:85]
	v_mfma_f32_16x16x32_bf16 v[78:81], v[180:183], v[204:207], v[78:81]
	v_mfma_f32_16x16x32_bf16 v[70:73], v[154:157], v[222:225], v[70:73]
	v_mfma_f32_16x16x32_bf16 v[66:69], v[180:183], v[222:225], v[66:69]
	s_setprio 0
	s_barrier
	s_add_i32 s55, s55, s29
	v_lshl_add_u64 v[212:213], s[22:23], 0, v[0:1]
	s_mov_b32 m0, s55
	ds_read_b128 v[184:187], v178 offset:16384
	ds_read_b128 v[188:191], v178 offset:17408
	ds_read_b128 v[192:195], v178 offset:18432
	ds_read_b128 v[196:199], v178 offset:19456
	ds_read_b128 v[200:203], v178 offset:20480
	ds_read_b128 v[204:207], v178 offset:21504
	ds_read_b128 v[208:211], v178 offset:22528
	ds_read_b128 v[222:225], v178 offset:23552
	global_load_lds_dwordx4 v[212:213], off
	s_add_i32 m0, s55, 0x2000
	s_add_u32 s56, s22, 0x40000
	v_lshl_add_u64 v[226:227], s[22:23], 0, v[166:167]
	s_addc_u32 s57, s23, 0
	s_add_i32 s55, s58, s29
	global_load_lds_dwordx4 v[226:227], off
	v_lshl_add_u64 v[228:229], s[56:57], 0, v[0:1]
	s_mov_b32 m0, s55
	v_lshl_add_u64 v[230:231], s[24:25], 0, v[164:165]
	global_load_lds_dwordx4 v[228:229], off
	v_lshl_add_u64 v[228:229], s[56:57], 0, v[166:167]
	s_add_i32 m0, s55, 0x2000
	s_nop 0
	global_load_lds_dwordx4 v[228:229], off
	v_lshl_add_u64 v[228:229], s[24:25], 0, v[162:163]
	s_mov_b32 m0, s19
	s_nop 0
	global_load_lds_dwordx4 v[228:229], off
	s_mov_b32 m0, s30
	s_nop 0
	global_load_lds_dwordx4 v[230:231], off
	s_cmp_lg_u32 s98, 0
	s_cbranch_scc1 .Lrelax_g2_w2
	s_waitcnt vmcnt(8)
.Lback_g2_w2:
	s_waitcnt lgkmcnt(0)
	s_barrier
	s_setprio 1
	s_waitcnt lgkmcnt(0)
	v_mfma_f32_16x16x32_bf16 v[62:65], v[122:125], v[184:187], v[62:65]
	v_mfma_f32_16x16x32_bf16 v[58:61], v[130:133], v[184:187], v[58:61]
	v_mfma_f32_16x16x32_bf16 v[54:57], v[122:125], v[192:195], v[54:57]
	v_mfma_f32_16x16x32_bf16 v[42:45], v[130:133], v[192:195], v[42:45]
	v_mfma_f32_16x16x32_bf16 v[34:37], v[122:125], v[200:203], v[34:37]
	v_mfma_f32_16x16x32_bf16 v[26:29], v[130:133], v[200:203], v[26:29]
	v_mfma_f32_16x16x32_bf16 v[22:25], v[122:125], v[208:211], v[22:25]
	v_mfma_f32_16x16x32_bf16 v[10:13], v[130:133], v[208:211], v[10:13]
	v_mfma_f32_16x16x32_bf16 v[62:65], v[126:129], v[188:191], v[62:65]
	v_mfma_f32_16x16x32_bf16 v[58:61], v[134:137], v[188:191], v[58:61]
	v_mfma_f32_16x16x32_bf16 v[54:57], v[126:129], v[196:199], v[54:57]
	v_mfma_f32_16x16x32_bf16 v[42:45], v[134:137], v[196:199], v[42:45]
	v_mfma_f32_16x16x32_bf16 v[34:37], v[126:129], v[204:207], v[34:37]
	v_mfma_f32_16x16x32_bf16 v[26:29], v[134:137], v[204:207], v[26:29]
	v_mfma_f32_16x16x32_bf16 v[22:25], v[126:129], v[222:225], v[22:25]
	v_mfma_f32_16x16x32_bf16 v[10:13], v[134:137], v[222:225], v[10:13]
	s_setprio 0
	s_setprio 1
	v_mfma_f32_16x16x32_bf16 v[50:53], v[146:149], v[184:187], v[50:53]
	v_mfma_f32_16x16x32_bf16 v[46:49], v[172:175], v[184:187], v[46:49]
	v_mfma_f32_16x16x32_bf16 v[38:41], v[146:149], v[192:195], v[38:41]
	v_mfma_f32_16x16x32_bf16 v[30:33], v[172:175], v[192:195], v[30:33]
	v_mfma_f32_16x16x32_bf16 v[18:21], v[146:149], v[200:203], v[18:21]
	v_mfma_f32_16x16x32_bf16 v[14:17], v[172:175], v[200:203], v[14:17]
	v_mfma_f32_16x16x32_bf16 v[6:9], v[146:149], v[208:211], v[6:9]
	v_mfma_f32_16x16x32_bf16 v[2:5], v[172:175], v[208:211], v[2:5]
	v_mfma_f32_16x16x32_bf16 v[50:53], v[154:157], v[188:191], v[50:53]
	v_mfma_f32_16x16x32_bf16 v[46:49], v[180:183], v[188:191], v[46:49]
	v_mfma_f32_16x16x32_bf16 v[38:41], v[154:157], v[196:199], v[38:41]
	v_mfma_f32_16x16x32_bf16 v[30:33], v[180:183], v[196:199], v[30:33]
	v_mfma_f32_16x16x32_bf16 v[18:21], v[154:157], v[204:207], v[18:21]
	v_mfma_f32_16x16x32_bf16 v[14:17], v[180:183], v[204:207], v[14:17]
	v_mfma_f32_16x16x32_bf16 v[6:9], v[154:157], v[222:225], v[6:9]
	v_mfma_f32_16x16x32_bf16 v[2:5], v[180:183], v[222:225], v[2:5]
	s_setprio 0
	s_barrier
	s_add_i32 s55, 0, 0x18000
	s_add_i32 s56, 0, 0x1c000
	v_add_u32_e32 v134, s55, v176
	v_add_u32_e32 v179, s56, v176
	ds_read_b128 v[122:125], v134
	ds_read_b128 v[126:129], v134 offset:1024
	ds_read_b128 v[130:133], v134 offset:2048
	ds_read_b128 v[134:137], v134 offset:3072
	ds_read_b128 v[146:149], v179
	ds_read_b128 v[154:157], v179 offset:1024
	ds_read_b128 v[172:175], v179 offset:2048
	ds_read_b128 v[180:183], v179 offset:3072
	s_add_u32 s24, s24, 0x40000
	s_addc_u32 s25, s25, 0
	s_mov_b32 m0, s31
	v_lshl_add_u64 v[232:233], s[24:25], 0, v[162:163]
	ds_read_b128 v[184:187], v178 offset:32768
	ds_read_b128 v[188:191], v178 offset:33792
	ds_read_b128 v[192:195], v178 offset:34816
	ds_read_b128 v[196:199], v178 offset:35840
	ds_read_b128 v[200:203], v178 offset:36864
	ds_read_b128 v[204:207], v178 offset:37888
	ds_read_b128 v[208:211], v178 offset:38912
	ds_read_b128 v[222:225], v178 offset:39936
	global_load_lds_dwordx4 v[232:233], off
	v_lshl_add_u64 v[232:233], s[24:25], 0, v[164:165]
	s_mov_b32 m0, s37
	s_nop 0
	global_load_lds_dwordx4 v[232:233], off
	s_waitcnt vmcnt(8)
	s_waitcnt lgkmcnt(0)
	s_barrier
	s_setprio 1
	s_waitcnt lgkmcnt(0)
	v_mfma_f32_16x16x32_bf16 v[142:145], v[122:125], v[184:187], v[142:145]
	v_mfma_f32_16x16x32_bf16 v[138:141], v[130:133], v[184:187], v[138:141]
	v_mfma_f32_16x16x32_bf16 v[118:121], v[122:125], v[192:195], v[118:121]
	v_mfma_f32_16x16x32_bf16 v[106:109], v[130:133], v[192:195], v[106:109]
	v_mfma_f32_16x16x32_bf16 v[98:101], v[122:125], v[200:203], v[98:101]
	v_mfma_f32_16x16x32_bf16 v[90:93], v[130:133], v[200:203], v[90:93]
	v_mfma_f32_16x16x32_bf16 v[86:89], v[122:125], v[208:211], v[86:89]
	v_mfma_f32_16x16x32_bf16 v[74:77], v[130:133], v[208:211], v[74:77]
	v_mfma_f32_16x16x32_bf16 v[142:145], v[126:129], v[188:191], v[142:145]
	v_mfma_f32_16x16x32_bf16 v[138:141], v[134:137], v[188:191], v[138:141]
	v_mfma_f32_16x16x32_bf16 v[118:121], v[126:129], v[196:199], v[118:121]
	v_mfma_f32_16x16x32_bf16 v[106:109], v[134:137], v[196:199], v[106:109]
	v_mfma_f32_16x16x32_bf16 v[98:101], v[126:129], v[204:207], v[98:101]
	v_mfma_f32_16x16x32_bf16 v[90:93], v[134:137], v[204:207], v[90:93]
	v_mfma_f32_16x16x32_bf16 v[86:89], v[126:129], v[222:225], v[86:89]
	v_mfma_f32_16x16x32_bf16 v[74:77], v[134:137], v[222:225], v[74:77]
	s_setprio 0
	s_setprio 1
	v_mfma_f32_16x16x32_bf16 v[114:117], v[146:149], v[184:187], v[114:117]
	v_mfma_f32_16x16x32_bf16 v[110:113], v[172:175], v[184:187], v[110:113]
	v_mfma_f32_16x16x32_bf16 v[102:105], v[146:149], v[192:195], v[102:105]
	v_mfma_f32_16x16x32_bf16 v[94:97], v[172:175], v[192:195], v[94:97]
	v_mfma_f32_16x16x32_bf16 v[82:85], v[146:149], v[200:203], v[82:85]
	v_mfma_f32_16x16x32_bf16 v[78:81], v[172:175], v[200:203], v[78:81]
	v_mfma_f32_16x16x32_bf16 v[70:73], v[146:149], v[208:211], v[70:73]
	v_mfma_f32_16x16x32_bf16 v[66:69], v[172:175], v[208:211], v[66:69]
	v_mfma_f32_16x16x32_bf16 v[114:117], v[154:157], v[188:191], v[114:117]
	v_mfma_f32_16x16x32_bf16 v[110:113], v[180:183], v[188:191], v[110:113]
	v_mfma_f32_16x16x32_bf16 v[102:105], v[154:157], v[196:199], v[102:105]
	v_mfma_f32_16x16x32_bf16 v[94:97], v[180:183], v[196:199], v[94:97]
	v_mfma_f32_16x16x32_bf16 v[82:85], v[154:157], v[204:207], v[82:85]
	v_mfma_f32_16x16x32_bf16 v[78:81], v[180:183], v[204:207], v[78:81]
	v_mfma_f32_16x16x32_bf16 v[70:73], v[154:157], v[222:225], v[70:73]
	v_mfma_f32_16x16x32_bf16 v[66:69], v[180:183], v[222:225], v[66:69]
	s_setprio 0
	s_barrier
	s_add_i32 s24, s55, s29
	v_lshl_add_u64 v[212:213], v[212:213], 0, s[96:97]
	s_mov_b32 m0, s24
	ds_read_b128 v[184:187], v178 offset:49152
	ds_read_b128 v[188:191], v178 offset:50176
	ds_read_b128 v[192:195], v178 offset:51200
	ds_read_b128 v[196:199], v178 offset:52224
	ds_read_b128 v[200:203], v178 offset:53248
	ds_read_b128 v[204:207], v178 offset:54272
	ds_read_b128 v[208:211], v178 offset:55296
	ds_read_b128 v[222:225], v178 offset:56320
	global_load_lds_dwordx4 v[212:213], off
	s_add_i32 m0, s24, 0x2000
	s_add_u32 s22, s22, 0x40080
	v_lshl_add_u64 v[212:213], v[226:227], 0, s[96:97]
	s_addc_u32 s23, s23, 0
	s_add_i32 s24, s56, s29
	global_load_lds_dwordx4 v[212:213], off
	v_lshl_add_u64 v[212:213], s[22:23], 0, v[0:1]
	s_mov_b32 m0, s24
	s_nop 0
	global_load_lds_dwordx4 v[212:213], off
	v_lshl_add_u64 v[212:213], s[22:23], 0, v[166:167]
	s_add_i32 m0, s24, 0x2000
	s_nop 0
	global_load_lds_dwordx4 v[212:213], off
	v_lshl_add_u64 v[212:213], v[228:229], 0, s[96:97]
	s_mov_b32 m0, s40
	s_nop 0
	global_load_lds_dwordx4 v[212:213], off
	v_lshl_add_u64 v[212:213], v[230:231], 0, s[96:97]
	s_mov_b32 m0, s41
	s_nop 0
	global_load_lds_dwordx4 v[212:213], off
	s_waitcnt vmcnt(8)
	s_waitcnt lgkmcnt(0)
	s_barrier
	s_setprio 1
	s_waitcnt lgkmcnt(0)
	v_mfma_f32_16x16x32_bf16 v[62:65], v[122:125], v[184:187], v[62:65]
	v_mfma_f32_16x16x32_bf16 v[58:61], v[130:133], v[184:187], v[58:61]
	v_mfma_f32_16x16x32_bf16 v[54:57], v[122:125], v[192:195], v[54:57]
	v_mfma_f32_16x16x32_bf16 v[42:45], v[130:133], v[192:195], v[42:45]
	v_mfma_f32_16x16x32_bf16 v[34:37], v[122:125], v[200:203], v[34:37]
	v_mfma_f32_16x16x32_bf16 v[26:29], v[130:133], v[200:203], v[26:29]
	v_mfma_f32_16x16x32_bf16 v[22:25], v[122:125], v[208:211], v[22:25]
	v_mfma_f32_16x16x32_bf16 v[10:13], v[130:133], v[208:211], v[10:13]
	v_mfma_f32_16x16x32_bf16 v[62:65], v[126:129], v[188:191], v[62:65]
	v_mfma_f32_16x16x32_bf16 v[58:61], v[134:137], v[188:191], v[58:61]
	v_mfma_f32_16x16x32_bf16 v[54:57], v[126:129], v[196:199], v[54:57]
	v_mfma_f32_16x16x32_bf16 v[42:45], v[134:137], v[196:199], v[42:45]
	v_mfma_f32_16x16x32_bf16 v[34:37], v[126:129], v[204:207], v[34:37]
	v_mfma_f32_16x16x32_bf16 v[26:29], v[134:137], v[204:207], v[26:29]
	v_mfma_f32_16x16x32_bf16 v[22:25], v[126:129], v[222:225], v[22:25]
	v_mfma_f32_16x16x32_bf16 v[10:13], v[134:137], v[222:225], v[10:13]
	s_setprio 0
	s_setprio 1
	v_mfma_f32_16x16x32_bf16 v[50:53], v[146:149], v[184:187], v[50:53]
	v_mfma_f32_16x16x32_bf16 v[46:49], v[172:175], v[184:187], v[46:49]
	v_mfma_f32_16x16x32_bf16 v[38:41], v[146:149], v[192:195], v[38:41]
	v_mfma_f32_16x16x32_bf16 v[30:33], v[172:175], v[192:195], v[30:33]
	v_mfma_f32_16x16x32_bf16 v[18:21], v[146:149], v[200:203], v[18:21]
	v_mfma_f32_16x16x32_bf16 v[14:17], v[172:175], v[200:203], v[14:17]
	v_mfma_f32_16x16x32_bf16 v[6:9], v[146:149], v[208:211], v[6:9]
	v_mfma_f32_16x16x32_bf16 v[2:5], v[172:175], v[208:211], v[2:5]
	v_mfma_f32_16x16x32_bf16 v[50:53], v[154:157], v[188:191], v[50:53]
	v_mfma_f32_16x16x32_bf16 v[46:49], v[180:183], v[188:191], v[46:49]
	v_mfma_f32_16x16x32_bf16 v[38:41], v[154:157], v[196:199], v[38:41]
	v_mfma_f32_16x16x32_bf16 v[30:33], v[180:183], v[196:199], v[30:33]
	v_mfma_f32_16x16x32_bf16 v[18:21], v[154:157], v[204:207], v[18:21]
	v_mfma_f32_16x16x32_bf16 v[14:17], v[180:183], v[204:207], v[14:17]
	v_mfma_f32_16x16x32_bf16 v[6:9], v[154:157], v[222:225], v[6:9]
	v_mfma_f32_16x16x32_bf16 v[2:5], v[180:183], v[222:225], v[2:5]
	s_setprio 0
	s_barrier
	s_add_i32 s49, s49, 2
	s_add_u32 s47, s47, 0x100
	s_addc_u32 s48, s48, 0
	s_add_u32 s20, s20, 0x100
	s_addc_u32 s21, s21, 0
	s_cmp_gt_u32 s49, 13
	s_cbranch_scc0 .LBB0_79
	s_and_b64 vcc, exec, s[8:9]
	s_movk_i32 s46, 0xd000
	s_movk_i32 s47, 0xec00
	s_cbranch_vccz .LBB0_82
	s_barrier
.LBB0_82:
	v_lshl_add_u32 v172, s18, 8, v159
	v_lshl_or_b32 v122, s44, 8, v177
	v_ashrrev_i32_e32 v173, 31, v172
	v_ashrrev_i32_e32 v123, 31, v122
	v_lshlrev_b64 v[124:125], 11, v[172:173]
	v_lshl_add_u64 v[124:125], s[4:5], 0, v[124:125]
	v_lshlrev_b64 v[174:175], 1, v[122:123]
	s_ashr_i32 s11, s18, 4
	v_lshl_add_u64 v[154:155], v[124:125], 0, v[174:175]
	s_mul_hi_i32 s13, s11, 0x6000
	s_mulk_i32 s11, 0x6000
	flat_load_dwordx4 v[146:149], v[154:155]
	s_add_u32 s20, s38, s11
	s_addc_u32 s21, s39, s13
	v_lshl_add_u64 v[122:123], v[122:123], 2, s[20:21]
	flat_load_dwordx4 v[134:137], v[122:123]
	flat_load_dwordx4 v[130:133], v[122:123] offset:16
	flat_load_dwordx4 v[126:129], v[122:123] offset:512
	s_nop 0
	flat_load_dwordx4 v[122:125], v[122:123] offset:528
	s_andn2_b64 vcc, exec, s[0:1]
	s_mov_b64 s[0:1], -1
	s_movk_i32 s55, 0xf000
	s_waitcnt vmcnt(0) lgkmcnt(0)
	v_lshlrev_b32_e32 v156, 16, v146
	v_and_b32_e32 v157, 0xffff0000, v146
	v_lshlrev_b32_e32 v146, 16, v147
	v_and_b32_e32 v147, 0xffff0000, v147
	v_lshlrev_b32_e32 v180, 16, v148
	v_and_b32_e32 v181, 0xffff0000, v148
	v_lshlrev_b32_e32 v148, 16, v149
	v_and_b32_e32 v149, 0xffff0000, v149
	v_pk_fma_f32 v[144:145], v[144:145], v[136:137], v[146:147]
	v_pk_fma_f32 v[142:143], v[142:143], v[134:135], v[156:157]
	v_pk_fma_f32 v[146:147], v[140:141], v[132:133], v[148:149]
	v_pk_fma_f32 v[140:141], v[138:139], v[130:131], v[180:181]
	v_cvt_pk_bf16_f32 v138, v142, v143
	v_cvt_pk_bf16_f32 v139, v144, v145
	s_nop 0
	v_cvt_pk_bf16_f32 v140, v140, v141
	v_cvt_pk_bf16_f32 v141, v146, v147
	flat_load_dwordx4 v[142:145], v[154:155] offset:256
	v_or_b32_e32 v146, 16, v172
	v_ashrrev_i32_e32 v147, 31, v146
	v_lshlrev_b64 v[146:147], 11, v[146:147]
	v_lshl_add_u64 v[146:147], s[4:5], 0, v[146:147]
	flat_store_dwordx4 v[154:155], v[138:141]
	v_lshl_add_u64 v[146:147], v[146:147], 0, v[174:175]
	s_waitcnt vmcnt(0) lgkmcnt(0)
	v_lshlrev_b32_e32 v138, 16, v142
	v_and_b32_e32 v139, 0xffff0000, v142
	v_lshlrev_b32_e32 v140, 16, v143
	v_and_b32_e32 v141, 0xffff0000, v143
	v_lshlrev_b32_e32 v142, 16, v144
	v_and_b32_e32 v143, 0xffff0000, v144
	v_lshlrev_b32_e32 v144, 16, v145
	v_and_b32_e32 v145, 0xffff0000, v145
	v_pk_fma_f32 v[116:117], v[116:117], v[128:129], v[140:141]
	v_pk_fma_f32 v[114:115], v[114:115], v[126:127], v[138:139]
	v_pk_fma_f32 v[138:139], v[112:113], v[124:125], v[144:145]
	v_pk_fma_f32 v[112:113], v[110:111], v[122:123], v[142:143]
	v_cvt_pk_bf16_f32 v110, v114, v115
	v_cvt_pk_bf16_f32 v111, v116, v117
	s_nop 0
	v_cvt_pk_bf16_f32 v112, v112, v113
	v_cvt_pk_bf16_f32 v113, v138, v139
	flat_load_dwordx4 v[114:117], v[146:147]
	s_nop 0
	flat_store_dwordx4 v[154:155], v[110:113] offset:256
	s_waitcnt vmcnt(0) lgkmcnt(0)
	s_nop 0
	v_lshlrev_b32_e32 v110, 16, v114
	v_and_b32_e32 v111, 0xffff0000, v114
	v_lshlrev_b32_e32 v112, 16, v115
	v_and_b32_e32 v113, 0xffff0000, v115
	v_lshlrev_b32_e32 v114, 16, v116
	v_and_b32_e32 v115, 0xffff0000, v116
	v_lshlrev_b32_e32 v116, 16, v117
	v_and_b32_e32 v117, 0xffff0000, v117
	v_pk_fma_f32 v[112:113], v[120:121], v[136:137], v[112:113]
	v_pk_fma_f32 v[110:111], v[118:119], v[134:135], v[110:111]
	v_pk_fma_f32 v[116:117], v[108:109], v[132:133], v[116:117]
	v_pk_fma_f32 v[108:109], v[106:107], v[130:131], v[114:115]
	v_cvt_pk_bf16_f32 v106, v110, v111
	v_cvt_pk_bf16_f32 v107, v112, v113
	v_or_b32_e32 v114, 32, v172
	v_cvt_pk_bf16_f32 v108, v108, v109
	v_cvt_pk_bf16_f32 v109, v116, v117
	flat_load_dwordx4 v[110:113], v[146:147] offset:256
	v_ashrrev_i32_e32 v115, 31, v114
	flat_store_dwordx4 v[146:147], v[106:109]
	v_lshlrev_b64 v[114:115], 11, v[114:115]
	v_lshl_add_u64 v[114:115], s[4:5], 0, v[114:115]
	v_lshl_add_u64 v[114:115], v[114:115], 0, v[174:175]
	s_waitcnt vmcnt(0) lgkmcnt(0)
	v_lshlrev_b32_e32 v106, 16, v110
	v_and_b32_e32 v107, 0xffff0000, v110
	v_lshlrev_b32_e32 v108, 16, v111
	v_and_b32_e32 v109, 0xffff0000, v111
	v_lshlrev_b32_e32 v110, 16, v112
	v_and_b32_e32 v111, 0xffff0000, v112
	v_lshlrev_b32_e32 v112, 16, v113
	v_and_b32_e32 v113, 0xffff0000, v113
	v_pk_fma_f32 v[102:103], v[102:103], v[126:127], v[106:107]
	v_pk_fma_f32 v[106:107], v[96:97], v[124:125], v[112:113]
	v_pk_fma_f32 v[96:97], v[94:95], v[122:123], v[110:111]
	v_pk_fma_f32 v[104:105], v[104:105], v[128:129], v[108:109]
	v_cvt_pk_bf16_f32 v94, v102, v103
	s_nop 0
	v_cvt_pk_bf16_f32 v95, v104, v105
	v_cvt_pk_bf16_f32 v96, v96, v97
	v_cvt_pk_bf16_f32 v97, v106, v107
	flat_store_dwordx4 v[146:147], v[94:97] offset:256
	flat_load_dwordx4 v[94:97], v[114:115]
	s_waitcnt vmcnt(0) lgkmcnt(0)
	v_lshlrev_b32_e32 v102, 16, v94
	v_and_b32_e32 v103, 0xffff0000, v94
	v_lshlrev_b32_e32 v94, 16, v95
	v_and_b32_e32 v95, 0xffff0000, v95
	v_lshlrev_b32_e32 v104, 16, v96
	v_and_b32_e32 v105, 0xffff0000, v96
	v_lshlrev_b32_e32 v96, 16, v97
	v_and_b32_e32 v97, 0xffff0000, v97
	v_pk_fma_f32 v[94:95], v[100:101], v[136:137], v[94:95]
	v_pk_fma_f32 v[96:97], v[92:93], v[132:133], v[96:97]
	v_pk_fma_f32 v[92:93], v[90:91], v[130:131], v[104:105]
	v_pk_fma_f32 v[98:99], v[98:99], v[134:135], v[102:103]
	s_nop 0
	v_cvt_pk_bf16_f32 v90, v98, v99
	v_cvt_pk_bf16_f32 v91, v94, v95
	v_cvt_pk_bf16_f32 v92, v92, v93
	v_cvt_pk_bf16_f32 v93, v96, v97
	flat_load_dwordx4 v[94:97], v[114:115] offset:256
	v_or_b32_e32 v98, 48, v172
	v_ashrrev_i32_e32 v99, 31, v98
	v_lshlrev_b64 v[98:99], 11, v[98:99]
	v_lshl_add_u64 v[98:99], s[4:5], 0, v[98:99]
	flat_store_dwordx4 v[114:115], v[90:93]
	v_lshl_add_u64 v[98:99], v[98:99], 0, v[174:175]
	s_waitcnt vmcnt(0) lgkmcnt(0)
	v_lshlrev_b32_e32 v90, 16, v94
	v_and_b32_e32 v91, 0xffff0000, v94
	v_lshlrev_b32_e32 v92, 16, v95
	v_and_b32_e32 v93, 0xffff0000, v95
	v_lshlrev_b32_e32 v94, 16, v96
	v_and_b32_e32 v95, 0xffff0000, v96
	v_lshlrev_b32_e32 v96, 16, v97
	v_and_b32_e32 v97, 0xffff0000, v97
	v_pk_fma_f32 v[84:85], v[84:85], v[128:129], v[92:93]
	v_pk_fma_f32 v[82:83], v[82:83], v[126:127], v[90:91]
	v_pk_fma_f32 v[90:91], v[80:81], v[124:125], v[96:97]
	v_pk_fma_f32 v[80:81], v[78:79], v[122:123], v[94:95]
	v_cvt_pk_bf16_f32 v78, v82, v83
	v_cvt_pk_bf16_f32 v79, v84, v85
	s_nop 0
	v_cvt_pk_bf16_f32 v80, v80, v81
	v_cvt_pk_bf16_f32 v81, v90, v91
	flat_load_dwordx4 v[82:85], v[98:99]
	s_nop 0
	flat_store_dwordx4 v[114:115], v[78:81] offset:256
	s_waitcnt vmcnt(0) lgkmcnt(0)
	s_nop 0
	v_lshlrev_b32_e32 v78, 16, v82
	v_and_b32_e32 v79, 0xffff0000, v82
	v_lshlrev_b32_e32 v80, 16, v83
	v_and_b32_e32 v81, 0xffff0000, v83
	v_lshlrev_b32_e32 v82, 16, v84
	v_and_b32_e32 v83, 0xffff0000, v84
	v_lshlrev_b32_e32 v84, 16, v85
	v_and_b32_e32 v85, 0xffff0000, v85
	v_pk_fma_f32 v[80:81], v[88:89], v[136:137], v[80:81]
	v_pk_fma_f32 v[78:79], v[86:87], v[134:135], v[78:79]
	v_pk_fma_f32 v[84:85], v[76:77], v[132:133], v[84:85]
	v_pk_fma_f32 v[76:77], v[74:75], v[130:131], v[82:83]
	v_cvt_pk_bf16_f32 v74, v78, v79
	v_cvt_pk_bf16_f32 v75, v80, v81
	v_add_u32_e32 v82, 0x80, v172
	v_cvt_pk_bf16_f32 v76, v76, v77
	v_cvt_pk_bf16_f32 v77, v84, v85
	flat_load_dwordx4 v[78:81], v[98:99] offset:256
	v_ashrrev_i32_e32 v83, 31, v82
	flat_store_dwordx4 v[98:99], v[74:77]
	v_lshlrev_b64 v[82:83], 11, v[82:83]
	v_lshl_add_u64 v[82:83], s[4:5], 0, v[82:83]
	v_lshl_add_u64 v[82:83], v[82:83], 0, v[174:175]
	s_waitcnt vmcnt(0) lgkmcnt(0)
	v_lshlrev_b32_e32 v74, 16, v78
	v_and_b32_e32 v75, 0xffff0000, v78
	v_lshlrev_b32_e32 v76, 16, v79
	v_and_b32_e32 v77, 0xffff0000, v79
	v_lshlrev_b32_e32 v78, 16, v80
	v_and_b32_e32 v79, 0xffff0000, v80
	v_lshlrev_b32_e32 v80, 16, v81
	v_and_b32_e32 v81, 0xffff0000, v81
	v_pk_fma_f32 v[70:71], v[70:71], v[126:127], v[74:75]
	v_pk_fma_f32 v[74:75], v[68:69], v[124:125], v[80:81]
	v_pk_fma_f32 v[68:69], v[66:67], v[122:123], v[78:79]
	v_pk_fma_f32 v[72:73], v[72:73], v[128:129], v[76:77]
	v_cvt_pk_bf16_f32 v66, v70, v71
	s_nop 0
	v_cvt_pk_bf16_f32 v67, v72, v73
	v_cvt_pk_bf16_f32 v68, v68, v69
	v_cvt_pk_bf16_f32 v69, v74, v75
	flat_store_dwordx4 v[98:99], v[66:69] offset:256
	flat_load_dwordx4 v[66:69], v[82:83]
	s_waitcnt vmcnt(0) lgkmcnt(0)
	v_lshlrev_b32_e32 v70, 16, v66
	v_and_b32_e32 v71, 0xffff0000, v66
	v_lshlrev_b32_e32 v66, 16, v67
	v_and_b32_e32 v67, 0xffff0000, v67
	v_lshlrev_b32_e32 v72, 16, v68
	v_and_b32_e32 v73, 0xffff0000, v68
	v_lshlrev_b32_e32 v68, 16, v69
	v_and_b32_e32 v69, 0xffff0000, v69
	v_pk_fma_f32 v[64:65], v[64:65], v[136:137], v[66:67]
	v_pk_fma_f32 v[62:63], v[62:63], v[134:135], v[70:71]
	v_pk_fma_f32 v[66:67], v[60:61], v[132:133], v[68:69]
	v_pk_fma_f32 v[60:61], v[58:59], v[130:131], v[72:73]
	v_cvt_pk_bf16_f32 v58, v62, v63
	v_cvt_pk_bf16_f32 v59, v64, v65
	s_nop 0
	v_cvt_pk_bf16_f32 v60, v60, v61
	v_cvt_pk_bf16_f32 v61, v66, v67
	flat_load_dwordx4 v[62:65], v[82:83] offset:256
	v_add_u32_e32 v66, 0x90, v172
	v_ashrrev_i32_e32 v67, 31, v66
	v_lshlrev_b64 v[66:67], 11, v[66:67]
	v_lshl_add_u64 v[66:67], s[4:5], 0, v[66:67]
	flat_store_dwordx4 v[82:83], v[58:61]
	v_lshl_add_u64 v[66:67], v[66:67], 0, v[174:175]
	s_waitcnt vmcnt(0) lgkmcnt(0)
	v_lshlrev_b32_e32 v58, 16, v62
	v_and_b32_e32 v59, 0xffff0000, v62
	v_lshlrev_b32_e32 v60, 16, v63
	v_and_b32_e32 v61, 0xffff0000, v63
	v_lshlrev_b32_e32 v62, 16, v64
	v_and_b32_e32 v63, 0xffff0000, v64
	v_lshlrev_b32_e32 v64, 16, v65
	v_and_b32_e32 v65, 0xffff0000, v65
	v_pk_fma_f32 v[52:53], v[52:53], v[128:129], v[60:61]
	v_pk_fma_f32 v[50:51], v[50:51], v[126:127], v[58:59]
	v_pk_fma_f32 v[58:59], v[48:49], v[124:125], v[64:65]
	v_pk_fma_f32 v[48:49], v[46:47], v[122:123], v[62:63]
	v_cvt_pk_bf16_f32 v46, v50, v51
	v_cvt_pk_bf16_f32 v47, v52, v53
	s_nop 0
	v_cvt_pk_bf16_f32 v48, v48, v49
	v_cvt_pk_bf16_f32 v49, v58, v59
	flat_load_dwordx4 v[50:53], v[66:67]
	s_nop 0
	flat_store_dwordx4 v[82:83], v[46:49] offset:256
	s_waitcnt vmcnt(0) lgkmcnt(0)
	s_nop 0
	v_lshlrev_b32_e32 v46, 16, v50
	v_and_b32_e32 v47, 0xffff0000, v50
	v_lshlrev_b32_e32 v48, 16, v51
	v_and_b32_e32 v49, 0xffff0000, v51
	v_lshlrev_b32_e32 v50, 16, v52
	v_and_b32_e32 v51, 0xffff0000, v52
	v_lshlrev_b32_e32 v52, 16, v53
	v_and_b32_e32 v53, 0xffff0000, v53
	v_pk_fma_f32 v[48:49], v[56:57], v[136:137], v[48:49]
	v_pk_fma_f32 v[46:47], v[54:55], v[134:135], v[46:47]
	v_pk_fma_f32 v[52:53], v[44:45], v[132:133], v[52:53]
	v_pk_fma_f32 v[44:45], v[42:43], v[130:131], v[50:51]
	v_cvt_pk_bf16_f32 v42, v46, v47
	v_cvt_pk_bf16_f32 v43, v48, v49
	v_add_u32_e32 v50, 0xa0, v172
	v_cvt_pk_bf16_f32 v44, v44, v45
	v_cvt_pk_bf16_f32 v45, v52, v53
	flat_load_dwordx4 v[46:49], v[66:67] offset:256
	v_ashrrev_i32_e32 v51, 31, v50
	flat_store_dwordx4 v[66:67], v[42:45]
	v_lshlrev_b64 v[50:51], 11, v[50:51]
	v_lshl_add_u64 v[50:51], s[4:5], 0, v[50:51]
	v_lshl_add_u64 v[50:51], v[50:51], 0, v[174:175]
	s_waitcnt vmcnt(0) lgkmcnt(0)
	v_lshlrev_b32_e32 v42, 16, v46
	v_and_b32_e32 v43, 0xffff0000, v46
	v_lshlrev_b32_e32 v44, 16, v47
	v_and_b32_e32 v45, 0xffff0000, v47
	v_lshlrev_b32_e32 v46, 16, v48
	v_and_b32_e32 v47, 0xffff0000, v48
	v_lshlrev_b32_e32 v48, 16, v49
	v_and_b32_e32 v49, 0xffff0000, v49
	v_pk_fma_f32 v[38:39], v[38:39], v[126:127], v[42:43]
	v_pk_fma_f32 v[42:43], v[32:33], v[124:125], v[48:49]
	v_pk_fma_f32 v[32:33], v[30:31], v[122:123], v[46:47]
	v_pk_fma_f32 v[40:41], v[40:41], v[128:129], v[44:45]
	v_cvt_pk_bf16_f32 v30, v38, v39
	s_nop 0
	v_cvt_pk_bf16_f32 v31, v40, v41
	v_cvt_pk_bf16_f32 v32, v32, v33
	v_cvt_pk_bf16_f32 v33, v42, v43
	flat_store_dwordx4 v[66:67], v[30:33] offset:256
	flat_load_dwordx4 v[30:33], v[50:51]
	s_waitcnt vmcnt(0) lgkmcnt(0)
	v_lshlrev_b32_e32 v38, 16, v30
	v_and_b32_e32 v39, 0xffff0000, v30
	v_lshlrev_b32_e32 v30, 16, v31
	v_and_b32_e32 v31, 0xffff0000, v31
	v_lshlrev_b32_e32 v40, 16, v32
	v_and_b32_e32 v41, 0xffff0000, v32
	v_lshlrev_b32_e32 v32, 16, v33
	v_and_b32_e32 v33, 0xffff0000, v33
	v_pk_fma_f32 v[30:31], v[36:37], v[136:137], v[30:31]
	v_pk_fma_f32 v[32:33], v[28:29], v[132:133], v[32:33]
	v_pk_fma_f32 v[28:29], v[26:27], v[130:131], v[40:41]
	v_pk_fma_f32 v[34:35], v[34:35], v[134:135], v[38:39]
	s_nop 0
	v_cvt_pk_bf16_f32 v26, v34, v35
	v_cvt_pk_bf16_f32 v27, v30, v31
	v_cvt_pk_bf16_f32 v28, v28, v29
	v_cvt_pk_bf16_f32 v29, v32, v33
	flat_load_dwordx4 v[30:33], v[50:51] offset:256
	v_add_u32_e32 v34, 0xb0, v172
	v_ashrrev_i32_e32 v35, 31, v34
	v_lshlrev_b64 v[34:35], 11, v[34:35]
	v_lshl_add_u64 v[34:35], s[4:5], 0, v[34:35]
	flat_store_dwordx4 v[50:51], v[26:29]
	v_lshl_add_u64 v[34:35], v[34:35], 0, v[174:175]
	s_waitcnt vmcnt(0) lgkmcnt(0)
	v_lshlrev_b32_e32 v26, 16, v30
	v_and_b32_e32 v27, 0xffff0000, v30
	v_lshlrev_b32_e32 v28, 16, v31
	v_and_b32_e32 v29, 0xffff0000, v31
	v_lshlrev_b32_e32 v30, 16, v32
	v_and_b32_e32 v31, 0xffff0000, v32
	v_lshlrev_b32_e32 v32, 16, v33
	v_and_b32_e32 v33, 0xffff0000, v33
	v_pk_fma_f32 v[20:21], v[20:21], v[128:129], v[28:29]
	v_pk_fma_f32 v[18:19], v[18:19], v[126:127], v[26:27]
	v_pk_fma_f32 v[26:27], v[16:17], v[124:125], v[32:33]
	v_pk_fma_f32 v[16:17], v[14:15], v[122:123], v[30:31]
	v_cvt_pk_bf16_f32 v14, v18, v19
	v_cvt_pk_bf16_f32 v15, v20, v21
	s_nop 0
	v_cvt_pk_bf16_f32 v16, v16, v17
	v_cvt_pk_bf16_f32 v17, v26, v27
	flat_load_dwordx4 v[18:21], v[34:35]
	s_nop 0
	flat_store_dwordx4 v[50:51], v[14:17] offset:256
	s_waitcnt vmcnt(0) lgkmcnt(0)
	s_nop 0
	v_lshlrev_b32_e32 v14, 16, v18
	v_and_b32_e32 v15, 0xffff0000, v18
	v_lshlrev_b32_e32 v16, 16, v19
	v_and_b32_e32 v17, 0xffff0000, v19
	v_lshlrev_b32_e32 v18, 16, v20
	v_and_b32_e32 v19, 0xffff0000, v20
	v_lshlrev_b32_e32 v20, 16, v21
	v_and_b32_e32 v21, 0xffff0000, v21
	v_pk_fma_f32 v[16:17], v[24:25], v[136:137], v[16:17]
	v_pk_fma_f32 v[14:15], v[22:23], v[134:135], v[14:15]
	v_pk_fma_f32 v[20:21], v[12:13], v[132:133], v[20:21]
	v_pk_fma_f32 v[12:13], v[10:11], v[130:131], v[18:19]
	v_cvt_pk_bf16_f32 v10, v14, v15
	v_cvt_pk_bf16_f32 v11, v16, v17
	s_nop 0
	v_cvt_pk_bf16_f32 v12, v12, v13
	v_cvt_pk_bf16_f32 v13, v20, v21
	flat_load_dwordx4 v[14:17], v[34:35] offset:256
	s_nop 0
	flat_store_dwordx4 v[34:35], v[10:13]
	s_waitcnt vmcnt(0) lgkmcnt(0)
	s_nop 0
	v_lshlrev_b32_e32 v10, 16, v14
	v_and_b32_e32 v11, 0xffff0000, v14
	v_lshlrev_b32_e32 v12, 16, v15
	v_and_b32_e32 v13, 0xffff0000, v15
	v_lshlrev_b32_e32 v14, 16, v16
	v_and_b32_e32 v15, 0xffff0000, v16
	v_lshlrev_b32_e32 v16, 16, v17
	v_and_b32_e32 v17, 0xffff0000, v17
	v_pk_fma_f32 v[6:7], v[6:7], v[126:127], v[10:11]
	v_pk_fma_f32 v[10:11], v[4:5], v[124:125], v[16:17]
	v_pk_fma_f32 v[4:5], v[2:3], v[122:123], v[14:15]
	v_pk_fma_f32 v[8:9], v[8:9], v[128:129], v[12:13]
	v_cvt_pk_bf16_f32 v2, v6, v7
	s_nop 0
	v_cvt_pk_bf16_f32 v3, v8, v9
	v_cvt_pk_bf16_f32 v4, v4, v5
	v_cvt_pk_bf16_f32 v5, v10, v11
	flat_store_dwordx4 v[34:35], v[2:5] offset:256
	s_mov_b32 s98, 1
	s_cbranch_vccnz .LBB0_71
	s_andn2_b64 vcc, exec, s[6:7]
	s_cbranch_vccnz .LBB0_70
	s_barrier
	s_branch .LBB0_70

.LBB0_95:
	v_lshrrev_b32_e32 v17, 1, v158
	v_and_b32_e32 v17, 24, v17
	v_and_b32_e32 v16, 15, v158
	v_lshlrev_b32_e32 v18, 1, v17
	s_add_u32 s38, s2, 0x102000
	v_lshl_or_b32 v159, s1, 6, v16
	v_lshl_or_b32 v16, v16, 6, v18
	v_lshlrev_b32_e32 v18, 2, v158
	s_sext_i32_i8 s44, s0
	s_addc_u32 s39, s3, 0
	s_lshl_b32 s0, s1, 13
	v_and_b32_e32 v18, 32, v18
	v_bitop3_b32 v19, v16, s0, v18 bitop3:0xde
	s_lshl_b32 s0, s9, 5
	s_and_b32 s10, s0, 0x60
	s_add_i32 m0, s19, 0x18000
	v_lshl_add_u64 v[8:9], v[8:9], 0, s[96:97]
	s_lshl_b32 s0, s10, 7
	s_waitcnt vmcnt(2)
	s_barrier
	global_load_lds_dwordx4 v[8:9], off
	v_lshl_add_u64 v[6:7], v[6:7], 0, s[96:97]
	s_add_i32 m0, s19, 0x1a000
	s_add_i32 s40, s19, 0x8000
	s_add_i32 s41, s19, 0xa000
	v_bitop3_b32 v176, s0, v16, v18 bitop3:0xf6
	global_load_lds_dwordx4 v[6:7], off
	v_lshl_add_u64 v[2:3], v[2:3], 0, s[96:97]
	s_mov_b32 m0, s40
	s_add_u32 s0, s20, 0x40080
	global_load_lds_dwordx4 v[2:3], off
	v_lshl_add_u64 v[2:3], v[4:5], 0, s[96:97]
	s_mov_b32 m0, s41
	s_addc_u32 s1, s21, 0
	global_load_lds_dwordx4 v[2:3], off
	s_add_i32 m0, s19, 0x1c000
	v_lshl_add_u64 v[2:3], s[0:1], 0, v[0:1]
	global_load_lds_dwordx4 v[2:3], off
	v_lshl_add_u64 v[2:3], s[0:1], 0, v[166:167]
	s_add_i32 m0, s19, 0x1e000
	s_cmpk_lt_u32 s8, 0x100
	global_load_lds_dwordx4 v[2:3], off
	v_lshlrev_b32_e32 v2, 14, v13
	v_and_b32_e32 v2, 0xffff8000, v2
	v_lshl_add_u32 v2, v14, 11, v2
	v_and_b32_e32 v3, 1, v13
	v_lshl_or_b32 v2, v3, 6, v2
	v_lshl_add_u32 v168, v15, 1, v2
	v_lshlrev_b32_e32 v2, 14, v10
	v_and_b32_e32 v2, 0xffff8000, v2
	s_waitcnt vmcnt(6)
	v_lshl_add_u32 v2, v11, 11, v2
	v_and_b32_e32 v3, 1, v10
	v_lshl_or_b32 v2, v3, 6, v2
	s_cselect_b64 s[8:9], -1, 0
	s_ashr_i32 s42, s36, 31
	v_or_b32_e32 v177, s10, v17
	v_mov_b32_e32 v169, v1
	v_lshl_add_u32 v170, v12, 1, v2
	v_mov_b32_e32 v171, v1
	s_mov_b32 s43, 0
	v_add_u32_e32 v178, 0, v19
	s_barrier
	s_mov_b32 s98, 0
	s_branch .LBB0_98

.LBB0_105:
	s_add_u32 s22, s20, 0xfffc0080
	s_addc_u32 s23, s21, -1
	s_add_i32 s55, 0, 0x10000
	s_cmp_eq_u32 s49, 12
	s_cselect_b32 s25, s13, s23
	s_cselect_b32 s24, s45, s22
	s_cselect_b32 s23, s11, s48
	s_cselect_b32 s22, s46, s47
	s_add_i32 s58, 0, 0x14000
	v_add_u32_e32 v142, s55, v176
	v_add_u32_e32 v179, s58, v176
	ds_read_b128 v[130:133], v142
	ds_read_b128 v[134:137], v142 offset:1024
	ds_read_b128 v[138:141], v142 offset:2048
	ds_read_b128 v[142:145], v142 offset:3072
	ds_read_b128 v[146:149], v179
	ds_read_b128 v[154:157], v179 offset:1024
	ds_read_b128 v[172:175], v179 offset:2048
	ds_read_b128 v[180:183], v179 offset:3072
	v_lshl_add_u64 v[212:213], s[20:21], 0, v[170:171]
	s_add_i32 m0, s19, 0xc000
	ds_read_b128 v[184:187], v178
	ds_read_b128 v[188:191], v178 offset:1024
	ds_read_b128 v[192:195], v178 offset:2048
	ds_read_b128 v[196:199], v178 offset:3072
	ds_read_b128 v[200:203], v178 offset:4096
	ds_read_b128 v[204:207], v178 offset:5120
	ds_read_b128 v[208:211], v178 offset:6144
	ds_read_b128 v[222:225], v178 offset:7168
	global_load_lds_dwordx4 v[212:213], off
	v_lshl_add_u64 v[212:213], s[20:21], 0, v[168:169]
	s_add_i32 m0, s19, 0xe000
	s_nop 0
	global_load_lds_dwordx4 v[212:213], off
	s_cmp_lg_u32 s98, 0
	s_cbranch_scc1 .Lrelax_g3_w1
	s_waitcnt vmcnt(8)
.Lback_g3_w1:
	s_waitcnt lgkmcnt(0)
	s_barrier
	s_setprio 1
	s_waitcnt lgkmcnt(0)
	v_mfma_f32_16x16x32_bf16 v[126:129], v[130:133], v[184:187], v[126:129]
	v_mfma_f32_16x16x32_bf16 v[122:125], v[138:141], v[184:187], v[122:125]
	v_mfma_f32_16x16x32_bf16 v[110:113], v[130:133], v[192:195], v[110:113]
	v_mfma_f32_16x16x32_bf16 v[106:109], v[138:141], v[192:195], v[106:109]
	v_mfma_f32_16x16x32_bf16 v[94:97], v[130:133], v[200:203], v[94:97]
	v_mfma_f32_16x16x32_bf16 v[90:93], v[138:141], v[200:203], v[90:93]
	v_mfma_f32_16x16x32_bf16 v[78:81], v[130:133], v[208:211], v[78:81]
	v_mfma_f32_16x16x32_bf16 v[74:77], v[138:141], v[208:211], v[74:77]
	v_mfma_f32_16x16x32_bf16 v[126:129], v[134:137], v[188:191], v[126:129]
	v_mfma_f32_16x16x32_bf16 v[122:125], v[142:145], v[188:191], v[122:125]
	v_mfma_f32_16x16x32_bf16 v[110:113], v[134:137], v[196:199], v[110:113]
	v_mfma_f32_16x16x32_bf16 v[106:109], v[142:145], v[196:199], v[106:109]
	v_mfma_f32_16x16x32_bf16 v[94:97], v[134:137], v[204:207], v[94:97]
	v_mfma_f32_16x16x32_bf16 v[90:93], v[142:145], v[204:207], v[90:93]
	v_mfma_f32_16x16x32_bf16 v[78:81], v[134:137], v[222:225], v[78:81]
	v_mfma_f32_16x16x32_bf16 v[74:77], v[142:145], v[222:225], v[74:77]
	s_setprio 0
	s_setprio 1
	v_mfma_f32_16x16x32_bf16 v[118:121], v[146:149], v[184:187], v[118:121]
	v_mfma_f32_16x16x32_bf16 v[114:117], v[172:175], v[184:187], v[114:117]
	v_mfma_f32_16x16x32_bf16 v[102:105], v[146:149], v[192:195], v[102:105]
	v_mfma_f32_16x16x32_bf16 v[98:101], v[172:175], v[192:195], v[98:101]
	v_mfma_f32_16x16x32_bf16 v[86:89], v[146:149], v[200:203], v[86:89]
	v_mfma_f32_16x16x32_bf16 v[82:85], v[172:175], v[200:203], v[82:85]
	v_mfma_f32_16x16x32_bf16 v[70:73], v[146:149], v[208:211], v[70:73]
	v_mfma_f32_16x16x32_bf16 v[66:69], v[172:175], v[208:211], v[66:69]
	v_mfma_f32_16x16x32_bf16 v[118:121], v[154:157], v[188:191], v[118:121]
	v_mfma_f32_16x16x32_bf16 v[114:117], v[180:183], v[188:191], v[114:117]
	v_mfma_f32_16x16x32_bf16 v[102:105], v[154:157], v[196:199], v[102:105]
	v_mfma_f32_16x16x32_bf16 v[98:101], v[180:183], v[196:199], v[98:101]
	v_mfma_f32_16x16x32_bf16 v[86:89], v[154:157], v[204:207], v[86:89]
	v_mfma_f32_16x16x32_bf16 v[82:85], v[180:183], v[204:207], v[82:85]
	v_mfma_f32_16x16x32_bf16 v[70:73], v[154:157], v[222:225], v[70:73]
	v_mfma_f32_16x16x32_bf16 v[66:69], v[180:183], v[222:225], v[66:69]
	s_setprio 0
	s_barrier
	s_add_i32 s55, s55, s29
	v_lshl_add_u64 v[212:213], s[22:23], 0, v[0:1]
	s_mov_b32 m0, s55
	ds_read_b128 v[184:187], v178 offset:16384
	ds_read_b128 v[188:191], v178 offset:17408
	ds_read_b128 v[192:195], v178 offset:18432
	ds_read_b128 v[196:199], v178 offset:19456
	ds_read_b128 v[200:203], v178 offset:20480
	ds_read_b128 v[204:207], v178 offset:21504
	ds_read_b128 v[208:211], v178 offset:22528
	ds_read_b128 v[222:225], v178 offset:23552
	global_load_lds_dwordx4 v[212:213], off
	s_add_i32 m0, s55, 0x2000
	s_add_u32 s56, s22, 0x40000
	v_lshl_add_u64 v[226:227], s[22:23], 0, v[166:167]
	s_addc_u32 s57, s23, 0
	s_add_i32 s55, s58, s29
	global_load_lds_dwordx4 v[226:227], off
	v_lshl_add_u64 v[228:229], s[56:57], 0, v[0:1]
	s_mov_b32 m0, s55
	v_lshl_add_u64 v[230:231], s[24:25], 0, v[164:165]
	global_load_lds_dwordx4 v[228:229], off
	v_lshl_add_u64 v[228:229], s[56:57], 0, v[166:167]
	s_add_i32 m0, s55, 0x2000
	s_nop 0
	global_load_lds_dwordx4 v[228:229], off
	v_lshl_add_u64 v[228:229], s[24:25], 0, v[162:163]
	s_mov_b32 m0, s19
	s_nop 0
	global_load_lds_dwordx4 v[228:229], off
	s_mov_b32 m0, s30
	s_nop 0
	global_load_lds_dwordx4 v[230:231], off
	s_cmp_lg_u32 s98, 0
	s_cbranch_scc1 .Lrelax_g3_w2
	s_waitcnt vmcnt(8)
.Lback_g3_w2:
	s_waitcnt lgkmcnt(0)
	s_barrier
	s_setprio 1
	s_waitcnt lgkmcnt(0)
	v_mfma_f32_16x16x32_bf16 v[62:65], v[130:133], v[184:187], v[62:65]
	v_mfma_f32_16x16x32_bf16 v[58:61], v[138:141], v[184:187], v[58:61]
	v_mfma_f32_16x16x32_bf16 v[46:49], v[130:133], v[192:195], v[46:49]
	v_mfma_f32_16x16x32_bf16 v[42:45], v[138:141], v[192:195], v[42:45]
	v_mfma_f32_16x16x32_bf16 v[30:33], v[130:133], v[200:203], v[30:33]
	v_mfma_f32_16x16x32_bf16 v[26:29], v[138:141], v[200:203], v[26:29]
	v_mfma_f32_16x16x32_bf16 v[14:17], v[130:133], v[208:211], v[14:17]
	v_mfma_f32_16x16x32_bf16 v[10:13], v[138:141], v[208:211], v[10:13]
	v_mfma_f32_16x16x32_bf16 v[62:65], v[134:137], v[188:191], v[62:65]
	v_mfma_f32_16x16x32_bf16 v[58:61], v[142:145], v[188:191], v[58:61]
	v_mfma_f32_16x16x32_bf16 v[46:49], v[134:137], v[196:199], v[46:49]
	v_mfma_f32_16x16x32_bf16 v[42:45], v[142:145], v[196:199], v[42:45]
	v_mfma_f32_16x16x32_bf16 v[30:33], v[134:137], v[204:207], v[30:33]
	v_mfma_f32_16x16x32_bf16 v[26:29], v[142:145], v[204:207], v[26:29]
	v_mfma_f32_16x16x32_bf16 v[14:17], v[134:137], v[222:225], v[14:17]
	v_mfma_f32_16x16x32_bf16 v[10:13], v[142:145], v[222:225], v[10:13]
	s_setprio 0
	s_setprio 1
	v_mfma_f32_16x16x32_bf16 v[54:57], v[146:149], v[184:187], v[54:57]
	v_mfma_f32_16x16x32_bf16 v[50:53], v[172:175], v[184:187], v[50:53]
	v_mfma_f32_16x16x32_bf16 v[38:41], v[146:149], v[192:195], v[38:41]
	v_mfma_f32_16x16x32_bf16 v[34:37], v[172:175], v[192:195], v[34:37]
	v_mfma_f32_16x16x32_bf16 v[22:25], v[146:149], v[200:203], v[22:25]
	v_mfma_f32_16x16x32_bf16 v[18:21], v[172:175], v[200:203], v[18:21]
	v_mfma_f32_16x16x32_bf16 v[6:9], v[146:149], v[208:211], v[6:9]
	v_mfma_f32_16x16x32_bf16 v[2:5], v[172:175], v[208:211], v[2:5]
	v_mfma_f32_16x16x32_bf16 v[54:57], v[154:157], v[188:191], v[54:57]
	v_mfma_f32_16x16x32_bf16 v[50:53], v[180:183], v[188:191], v[50:53]
	v_mfma_f32_16x16x32_bf16 v[38:41], v[154:157], v[196:199], v[38:41]
	v_mfma_f32_16x16x32_bf16 v[34:37], v[180:183], v[196:199], v[34:37]
	v_mfma_f32_16x16x32_bf16 v[22:25], v[154:157], v[204:207], v[22:25]
	v_mfma_f32_16x16x32_bf16 v[18:21], v[180:183], v[204:207], v[18:21]
	v_mfma_f32_16x16x32_bf16 v[6:9], v[154:157], v[222:225], v[6:9]
	v_mfma_f32_16x16x32_bf16 v[2:5], v[180:183], v[222:225], v[2:5]
	s_setprio 0
	s_barrier
	s_add_i32 s55, 0, 0x18000
	s_add_i32 s56, 0, 0x1c000
	v_add_u32_e32 v142, s55, v176
	v_add_u32_e32 v179, s56, v176
	ds_read_b128 v[130:133], v142
	ds_read_b128 v[134:137], v142 offset:1024
	ds_read_b128 v[138:141], v142 offset:2048
	ds_read_b128 v[142:145], v142 offset:3072
	ds_read_b128 v[146:149], v179
	ds_read_b128 v[154:157], v179 offset:1024
	ds_read_b128 v[172:175], v179 offset:2048
	ds_read_b128 v[180:183], v179 offset:3072
	s_add_u32 s24, s24, 0x40000
	s_addc_u32 s25, s25, 0
	s_mov_b32 m0, s31
	v_lshl_add_u64 v[232:233], s[24:25], 0, v[162:163]
	ds_read_b128 v[184:187], v178 offset:32768
	ds_read_b128 v[188:191], v178 offset:33792
	ds_read_b128 v[192:195], v178 offset:34816
	ds_read_b128 v[196:199], v178 offset:35840
	ds_read_b128 v[200:203], v178 offset:36864
	ds_read_b128 v[204:207], v178 offset:37888
	ds_read_b128 v[208:211], v178 offset:38912
	ds_read_b128 v[222:225], v178 offset:39936
	global_load_lds_dwordx4 v[232:233], off
	v_lshl_add_u64 v[232:233], s[24:25], 0, v[164:165]
	s_mov_b32 m0, s37
	s_nop 0
	global_load_lds_dwordx4 v[232:233], off
	s_waitcnt vmcnt(8)
	s_waitcnt lgkmcnt(0)
	s_barrier
	s_setprio 1
	s_waitcnt lgkmcnt(0)
	v_mfma_f32_16x16x32_bf16 v[126:129], v[130:133], v[184:187], v[126:129]
	v_mfma_f32_16x16x32_bf16 v[122:125], v[138:141], v[184:187], v[122:125]
	v_mfma_f32_16x16x32_bf16 v[110:113], v[130:133], v[192:195], v[110:113]
	v_mfma_f32_16x16x32_bf16 v[106:109], v[138:141], v[192:195], v[106:109]
	v_mfma_f32_16x16x32_bf16 v[94:97], v[130:133], v[200:203], v[94:97]
	v_mfma_f32_16x16x32_bf16 v[90:93], v[138:141], v[200:203], v[90:93]
	v_mfma_f32_16x16x32_bf16 v[78:81], v[130:133], v[208:211], v[78:81]
	v_mfma_f32_16x16x32_bf16 v[74:77], v[138:141], v[208:211], v[74:77]
	v_mfma_f32_16x16x32_bf16 v[126:129], v[134:137], v[188:191], v[126:129]
	v_mfma_f32_16x16x32_bf16 v[122:125], v[142:145], v[188:191], v[122:125]
	v_mfma_f32_16x16x32_bf16 v[110:113], v[134:137], v[196:199], v[110:113]
	v_mfma_f32_16x16x32_bf16 v[106:109], v[142:145], v[196:199], v[106:109]
	v_mfma_f32_16x16x32_bf16 v[94:97], v[134:137], v[204:207], v[94:97]
	v_mfma_f32_16x16x32_bf16 v[90:93], v[142:145], v[204:207], v[90:93]
	v_mfma_f32_16x16x32_bf16 v[78:81], v[134:137], v[222:225], v[78:81]
	v_mfma_f32_16x16x32_bf16 v[74:77], v[142:145], v[222:225], v[74:77]
	s_setprio 0
	s_setprio 1
	v_mfma_f32_16x16x32_bf16 v[118:121], v[146:149], v[184:187], v[118:121]
	v_mfma_f32_16x16x32_bf16 v[114:117], v[172:175], v[184:187], v[114:117]
	v_mfma_f32_16x16x32_bf16 v[102:105], v[146:149], v[192:195], v[102:105]
	v_mfma_f32_16x16x32_bf16 v[98:101], v[172:175], v[192:195], v[98:101]
	v_mfma_f32_16x16x32_bf16 v[86:89], v[146:149], v[200:203], v[86:89]
	v_mfma_f32_16x16x32_bf16 v[82:85], v[172:175], v[200:203], v[82:85]
	v_mfma_f32_16x16x32_bf16 v[70:73], v[146:149], v[208:211], v[70:73]
	v_mfma_f32_16x16x32_bf16 v[66:69], v[172:175], v[208:211], v[66:69]
	v_mfma_f32_16x16x32_bf16 v[118:121], v[154:157], v[188:191], v[118:121]
	v_mfma_f32_16x16x32_bf16 v[114:117], v[180:183], v[188:191], v[114:117]
	v_mfma_f32_16x16x32_bf16 v[102:105], v[154:157], v[196:199], v[102:105]
	v_mfma_f32_16x16x32_bf16 v[98:101], v[180:183], v[196:199], v[98:101]
	v_mfma_f32_16x16x32_bf16 v[86:89], v[154:157], v[204:207], v[86:89]
	v_mfma_f32_16x16x32_bf16 v[82:85], v[180:183], v[204:207], v[82:85]
	v_mfma_f32_16x16x32_bf16 v[70:73], v[154:157], v[222:225], v[70:73]
	v_mfma_f32_16x16x32_bf16 v[66:69], v[180:183], v[222:225], v[66:69]
	s_setprio 0
	s_barrier
	s_add_i32 s24, s55, s29
	v_lshl_add_u64 v[212:213], v[212:213], 0, s[96:97]
	s_mov_b32 m0, s24
	ds_read_b128 v[184:187], v178 offset:49152
	ds_read_b128 v[188:191], v178 offset:50176
	ds_read_b128 v[192:195], v178 offset:51200
	ds_read_b128 v[196:199], v178 offset:52224
	ds_read_b128 v[200:203], v178 offset:53248
	ds_read_b128 v[204:207], v178 offset:54272
	ds_read_b128 v[208:211], v178 offset:55296
	ds_read_b128 v[222:225], v178 offset:56320
	global_load_lds_dwordx4 v[212:213], off
	s_add_i32 m0, s24, 0x2000
	s_add_u32 s22, s22, 0x40080
	v_lshl_add_u64 v[212:213], v[226:227], 0, s[96:97]
	s_addc_u32 s23, s23, 0
	s_add_i32 s24, s56, s29
	global_load_lds_dwordx4 v[212:213], off
	v_lshl_add_u64 v[212:213], s[22:23], 0, v[0:1]
	s_mov_b32 m0, s24
	s_nop 0
	global_load_lds_dwordx4 v[212:213], off
	v_lshl_add_u64 v[212:213], s[22:23], 0, v[166:167]
	s_add_i32 m0, s24, 0x2000
	s_nop 0
	global_load_lds_dwordx4 v[212:213], off
	v_lshl_add_u64 v[212:213], v[228:229], 0, s[96:97]
	s_mov_b32 m0, s40
	s_nop 0
	global_load_lds_dwordx4 v[212:213], off
	v_lshl_add_u64 v[212:213], v[230:231], 0, s[96:97]
	s_mov_b32 m0, s41
	s_nop 0
	global_load_lds_dwordx4 v[212:213], off
	s_waitcnt vmcnt(8)
	s_waitcnt lgkmcnt(0)
	s_barrier
	s_setprio 1
	s_waitcnt lgkmcnt(0)
	v_mfma_f32_16x16x32_bf16 v[62:65], v[130:133], v[184:187], v[62:65]
	v_mfma_f32_16x16x32_bf16 v[58:61], v[138:141], v[184:187], v[58:61]
	v_mfma_f32_16x16x32_bf16 v[46:49], v[130:133], v[192:195], v[46:49]
	v_mfma_f32_16x16x32_bf16 v[42:45], v[138:141], v[192:195], v[42:45]
	v_mfma_f32_16x16x32_bf16 v[30:33], v[130:133], v[200:203], v[30:33]
	v_mfma_f32_16x16x32_bf16 v[26:29], v[138:141], v[200:203], v[26:29]
	v_mfma_f32_16x16x32_bf16 v[14:17], v[130:133], v[208:211], v[14:17]
	v_mfma_f32_16x16x32_bf16 v[10:13], v[138:141], v[208:211], v[10:13]
	v_mfma_f32_16x16x32_bf16 v[62:65], v[134:137], v[188:191], v[62:65]
	v_mfma_f32_16x16x32_bf16 v[58:61], v[142:145], v[188:191], v[58:61]
	v_mfma_f32_16x16x32_bf16 v[46:49], v[134:137], v[196:199], v[46:49]
	v_mfma_f32_16x16x32_bf16 v[42:45], v[142:145], v[196:199], v[42:45]
	v_mfma_f32_16x16x32_bf16 v[30:33], v[134:137], v[204:207], v[30:33]
	v_mfma_f32_16x16x32_bf16 v[26:29], v[142:145], v[204:207], v[26:29]
	v_mfma_f32_16x16x32_bf16 v[14:17], v[134:137], v[222:225], v[14:17]
	v_mfma_f32_16x16x32_bf16 v[10:13], v[142:145], v[222:225], v[10:13]
	s_setprio 0
	s_setprio 1
	v_mfma_f32_16x16x32_bf16 v[54:57], v[146:149], v[184:187], v[54:57]
	v_mfma_f32_16x16x32_bf16 v[50:53], v[172:175], v[184:187], v[50:53]
	v_mfma_f32_16x16x32_bf16 v[38:41], v[146:149], v[192:195], v[38:41]
	v_mfma_f32_16x16x32_bf16 v[34:37], v[172:175], v[192:195], v[34:37]
	v_mfma_f32_16x16x32_bf16 v[22:25], v[146:149], v[200:203], v[22:25]
	v_mfma_f32_16x16x32_bf16 v[18:21], v[172:175], v[200:203], v[18:21]
	v_mfma_f32_16x16x32_bf16 v[6:9], v[146:149], v[208:211], v[6:9]
	v_mfma_f32_16x16x32_bf16 v[2:5], v[172:175], v[208:211], v[2:5]
	v_mfma_f32_16x16x32_bf16 v[54:57], v[154:157], v[188:191], v[54:57]
	v_mfma_f32_16x16x32_bf16 v[50:53], v[180:183], v[188:191], v[50:53]
	v_mfma_f32_16x16x32_bf16 v[38:41], v[154:157], v[196:199], v[38:41]
	v_mfma_f32_16x16x32_bf16 v[34:37], v[180:183], v[196:199], v[34:37]
	v_mfma_f32_16x16x32_bf16 v[22:25], v[154:157], v[204:207], v[22:25]
	v_mfma_f32_16x16x32_bf16 v[18:21], v[180:183], v[204:207], v[18:21]
	v_mfma_f32_16x16x32_bf16 v[6:9], v[154:157], v[222:225], v[6:9]
	v_mfma_f32_16x16x32_bf16 v[2:5], v[180:183], v[222:225], v[2:5]
	s_setprio 0
	s_barrier
	s_add_i32 s49, s49, 2
	s_add_u32 s47, s47, 0x100
	s_addc_u32 s48, s48, 0
	s_add_u32 s20, s20, 0x100
	s_addc_u32 s21, s21, 0
	s_cmp_gt_u32 s49, 13
	s_cbranch_scc0 .LBB0_105
	s_and_b64 vcc, exec, s[8:9]
	s_movk_i32 s46, 0xd000
	s_movk_i32 s47, 0xec00
	s_cbranch_vccz .LBB0_108
	s_barrier
.LBB0_108:
	s_ashr_i32 s11, s18, 4
	v_lshl_add_u32 v174, s18, 8, v159
	v_lshl_or_b32 v172, s44, 8, v177
	s_mul_hi_i32 s13, s11, 0x6000
	s_mulk_i32 s11, 0x6000
	v_ashrrev_i32_e32 v175, 31, v174
	s_add_u32 s20, s38, s11
	v_ashrrev_i32_e32 v173, 31, v172
	v_lshlrev_b64 v[134:135], 10, v[174:175]
	v_readlane_b32 s64, v253, 62
	s_addc_u32 s21, s39, s13
	v_lshl_add_u64 v[140:141], v[134:135], 0, v[172:173]
	v_readlane_b32 s65, v253, 63
	v_lshl_add_u64 v[138:139], v[172:173], 2, s[20:21]
	flat_load_dwordx4 v[130:133], v[138:139]
	v_lshl_add_u64 v[180:181], v[140:141], 2, s[64:65]
	global_load_dwordx4 v[146:149], v[180:181], off
	global_load_dwordx4 v[154:157], v[180:181], off offset:16
	flat_load_dwordx4 v[134:137], v[138:139] offset:16
	v_lshl_add_u64 v[182:183], v[140:141], 1, s[4:5]
	flat_load_dwordx4 v[142:145], v[138:139] offset:512
	s_nop 0
	flat_load_dwordx4 v[138:141], v[138:139] offset:528
	s_andn2_b64 vcc, exec, s[0:1]
	s_mov_b64 s[0:1], -1
	s_movk_i32 s55, 0xf000
	v_readlane_b32 s66, v254, 0
	v_readlane_b32 s67, v254, 1
	v_readlane_b32 s68, v254, 2
	v_readlane_b32 s69, v254, 3
	v_readlane_b32 s70, v254, 4
	v_readlane_b32 s71, v254, 5
	v_readlane_b32 s72, v254, 6
	v_readlane_b32 s73, v254, 7
	v_readlane_b32 s74, v254, 8
	v_readlane_b32 s75, v254, 9
	v_readlane_b32 s76, v254, 10
	v_readlane_b32 s77, v254, 11
	v_readlane_b32 s78, v254, 12
	v_readlane_b32 s79, v254, 13
	s_waitcnt vmcnt(0) lgkmcnt(0)
	v_pk_fma_f32 v[126:127], v[126:127], v[130:131], v[146:147]
	v_pk_fma_f32 v[128:129], v[128:129], v[132:133], v[148:149]
	v_pk_fma_f32 v[146:147], v[124:125], v[136:137], v[156:157]
	v_pk_fma_f32 v[124:125], v[122:123], v[134:135], v[154:155]
	v_cvt_pk_bf16_f32 v122, v126, v127
	v_cvt_pk_bf16_f32 v123, v128, v129
	s_nop 0
	v_cvt_pk_bf16_f32 v124, v124, v125
	v_cvt_pk_bf16_f32 v125, v146, v147
	flat_store_dwordx4 v[182:183], v[122:125]
	global_load_dwordx4 v[122:125], v[180:181], off offset:512
	s_nop 0
	global_load_dwordx4 v[126:129], v[180:181], off offset:528
	v_or_b32_e32 v146, 16, v174
	v_ashrrev_i32_e32 v147, 31, v146
	v_lshlrev_b64 v[146:147], 10, v[146:147]
	v_lshl_add_u64 v[146:147], v[146:147], 0, v[172:173]
	v_lshl_add_u64 v[148:149], v[146:147], 2, s[64:65]
	s_waitcnt vmcnt(0)
	v_pk_fma_f32 v[118:119], v[118:119], v[142:143], v[122:123]
	v_pk_fma_f32 v[122:123], v[116:117], v[140:141], v[128:129]
	v_pk_fma_f32 v[116:117], v[114:115], v[138:139], v[126:127]
	v_pk_fma_f32 v[120:121], v[120:121], v[144:145], v[124:125]
	v_cvt_pk_bf16_f32 v114, v118, v119
	s_nop 0
	v_cvt_pk_bf16_f32 v115, v120, v121
	v_cvt_pk_bf16_f32 v116, v116, v117
	v_cvt_pk_bf16_f32 v117, v122, v123
	flat_store_dwordx4 v[182:183], v[114:117] offset:256
	global_load_dwordx4 v[114:117], v[148:149], off
	s_nop 0
	global_load_dwordx4 v[118:121], v[148:149], off offset:16
	v_lshl_add_u64 v[122:123], v[146:147], 1, s[4:5]
	s_waitcnt vmcnt(0)
	v_pk_fma_f32 v[110:111], v[110:111], v[130:131], v[114:115]
	v_pk_fma_f32 v[114:115], v[108:109], v[136:137], v[120:121]
	v_pk_fma_f32 v[108:109], v[106:107], v[134:135], v[118:119]
	v_pk_fma_f32 v[112:113], v[112:113], v[132:133], v[116:117]
	v_cvt_pk_bf16_f32 v106, v110, v111
	s_nop 0
	v_cvt_pk_bf16_f32 v107, v112, v113
	v_cvt_pk_bf16_f32 v108, v108, v109
	v_cvt_pk_bf16_f32 v109, v114, v115
	flat_store_dwordx4 v[122:123], v[106:109]
	global_load_dwordx4 v[106:109], v[148:149], off offset:512
	s_nop 0
	global_load_dwordx4 v[110:113], v[148:149], off offset:528
	v_or_b32_e32 v114, 32, v174
	v_ashrrev_i32_e32 v115, 31, v114
	v_lshlrev_b64 v[114:115], 10, v[114:115]
	v_lshl_add_u64 v[114:115], v[114:115], 0, v[172:173]
	v_lshl_add_u64 v[116:117], v[114:115], 2, s[64:65]
	s_waitcnt vmcnt(0)
	v_pk_fma_f32 v[102:103], v[102:103], v[142:143], v[106:107]
	v_pk_fma_f32 v[106:107], v[100:101], v[140:141], v[112:113]
	v_pk_fma_f32 v[100:101], v[98:99], v[138:139], v[110:111]
	v_pk_fma_f32 v[104:105], v[104:105], v[144:145], v[108:109]
	v_cvt_pk_bf16_f32 v98, v102, v103
	s_nop 0
	v_cvt_pk_bf16_f32 v99, v104, v105
	v_cvt_pk_bf16_f32 v100, v100, v101
	v_cvt_pk_bf16_f32 v101, v106, v107
	flat_store_dwordx4 v[122:123], v[98:101] offset:256
	global_load_dwordx4 v[98:101], v[116:117], off
	global_load_dwordx4 v[102:105], v[116:117], off offset:16
	v_lshl_add_u64 v[106:107], v[114:115], 1, s[4:5]
	s_waitcnt vmcnt(0)
	v_pk_fma_f32 v[94:95], v[94:95], v[130:131], v[98:99]
	v_pk_fma_f32 v[98:99], v[92:93], v[136:137], v[104:105]
	v_pk_fma_f32 v[92:93], v[90:91], v[134:135], v[102:103]
	v_pk_fma_f32 v[96:97], v[96:97], v[132:133], v[100:101]
	v_cvt_pk_bf16_f32 v90, v94, v95
	s_nop 0
	v_cvt_pk_bf16_f32 v91, v96, v97
	v_cvt_pk_bf16_f32 v92, v92, v93
	v_cvt_pk_bf16_f32 v93, v98, v99
	flat_store_dwordx4 v[106:107], v[90:93]
	global_load_dwordx4 v[90:93], v[116:117], off offset:512
	s_nop 0
	global_load_dwordx4 v[94:97], v[116:117], off offset:528
	v_or_b32_e32 v98, 48, v174
	v_ashrrev_i32_e32 v99, 31, v98
	v_lshlrev_b64 v[98:99], 10, v[98:99]
	v_lshl_add_u64 v[98:99], v[98:99], 0, v[172:173]
	v_lshl_add_u64 v[100:101], v[98:99], 2, s[64:65]
	s_waitcnt vmcnt(0)
	v_pk_fma_f32 v[86:87], v[86:87], v[142:143], v[90:91]
	v_pk_fma_f32 v[90:91], v[84:85], v[140:141], v[96:97]
	v_pk_fma_f32 v[84:85], v[82:83], v[138:139], v[94:95]
	v_pk_fma_f32 v[88:89], v[88:89], v[144:145], v[92:93]
	v_cvt_pk_bf16_f32 v82, v86, v87
	s_nop 0
	v_cvt_pk_bf16_f32 v83, v88, v89
	v_cvt_pk_bf16_f32 v84, v84, v85
	v_cvt_pk_bf16_f32 v85, v90, v91
	flat_store_dwordx4 v[106:107], v[82:85] offset:256
	global_load_dwordx4 v[82:85], v[100:101], off
	s_nop 0
	global_load_dwordx4 v[86:89], v[100:101], off offset:16
	v_lshl_add_u64 v[90:91], v[98:99], 1, s[4:5]
	s_waitcnt vmcnt(0)
	v_pk_fma_f32 v[78:79], v[78:79], v[130:131], v[82:83]
	v_pk_fma_f32 v[82:83], v[76:77], v[136:137], v[88:89]
	v_pk_fma_f32 v[76:77], v[74:75], v[134:135], v[86:87]
	v_pk_fma_f32 v[80:81], v[80:81], v[132:133], v[84:85]
	v_cvt_pk_bf16_f32 v74, v78, v79
	s_nop 0
	v_cvt_pk_bf16_f32 v75, v80, v81
	v_cvt_pk_bf16_f32 v76, v76, v77
	v_cvt_pk_bf16_f32 v77, v82, v83
	flat_store_dwordx4 v[90:91], v[74:77]
	global_load_dwordx4 v[74:77], v[100:101], off offset:512
	s_nop 0
	global_load_dwordx4 v[78:81], v[100:101], off offset:528
	v_add_u32_e32 v82, 0x80, v174
	v_ashrrev_i32_e32 v83, 31, v82
	v_lshlrev_b64 v[82:83], 10, v[82:83]
	v_lshl_add_u64 v[82:83], v[82:83], 0, v[172:173]
	v_lshl_add_u64 v[84:85], v[82:83], 2, s[64:65]
	s_waitcnt vmcnt(0)
	v_pk_fma_f32 v[70:71], v[70:71], v[142:143], v[74:75]
	v_pk_fma_f32 v[74:75], v[68:69], v[140:141], v[80:81]
	v_pk_fma_f32 v[68:69], v[66:67], v[138:139], v[78:79]
	v_pk_fma_f32 v[72:73], v[72:73], v[144:145], v[76:77]
	v_cvt_pk_bf16_f32 v66, v70, v71
	s_nop 0
	v_cvt_pk_bf16_f32 v67, v72, v73
	v_cvt_pk_bf16_f32 v68, v68, v69
	v_cvt_pk_bf16_f32 v69, v74, v75
	flat_store_dwordx4 v[90:91], v[66:69] offset:256
	global_load_dwordx4 v[66:69], v[84:85], off
	global_load_dwordx4 v[70:73], v[84:85], off offset:16
	v_lshl_add_u64 v[74:75], v[82:83], 1, s[4:5]
	s_waitcnt vmcnt(0)
	v_pk_fma_f32 v[62:63], v[62:63], v[130:131], v[66:67]
	v_pk_fma_f32 v[66:67], v[60:61], v[136:137], v[72:73]
	v_pk_fma_f32 v[60:61], v[58:59], v[134:135], v[70:71]
	v_pk_fma_f32 v[64:65], v[64:65], v[132:133], v[68:69]
	v_cvt_pk_bf16_f32 v58, v62, v63
	s_nop 0
	v_cvt_pk_bf16_f32 v59, v64, v65
	v_cvt_pk_bf16_f32 v60, v60, v61
	v_cvt_pk_bf16_f32 v61, v66, v67
	flat_store_dwordx4 v[74:75], v[58:61]
	global_load_dwordx4 v[58:61], v[84:85], off offset:512
	s_nop 0
	global_load_dwordx4 v[62:65], v[84:85], off offset:528
	v_add_u32_e32 v66, 0x90, v174
	v_ashrrev_i32_e32 v67, 31, v66
	v_lshlrev_b64 v[66:67], 10, v[66:67]
	v_lshl_add_u64 v[66:67], v[66:67], 0, v[172:173]
	v_lshl_add_u64 v[68:69], v[66:67], 2, s[64:65]
	s_waitcnt vmcnt(0)
	v_pk_fma_f32 v[54:55], v[54:55], v[142:143], v[58:59]
	v_pk_fma_f32 v[58:59], v[52:53], v[140:141], v[64:65]
	v_pk_fma_f32 v[52:53], v[50:51], v[138:139], v[62:63]
	v_pk_fma_f32 v[56:57], v[56:57], v[144:145], v[60:61]
	v_cvt_pk_bf16_f32 v50, v54, v55
	s_nop 0
	v_cvt_pk_bf16_f32 v51, v56, v57
	v_cvt_pk_bf16_f32 v52, v52, v53
	v_cvt_pk_bf16_f32 v53, v58, v59
	flat_store_dwordx4 v[74:75], v[50:53] offset:256
	global_load_dwordx4 v[50:53], v[68:69], off
	s_nop 0
	global_load_dwordx4 v[54:57], v[68:69], off offset:16
	v_lshl_add_u64 v[58:59], v[66:67], 1, s[4:5]
	s_waitcnt vmcnt(0)
	v_pk_fma_f32 v[46:47], v[46:47], v[130:131], v[50:51]
	v_pk_fma_f32 v[50:51], v[44:45], v[136:137], v[56:57]
	v_pk_fma_f32 v[44:45], v[42:43], v[134:135], v[54:55]
	v_pk_fma_f32 v[48:49], v[48:49], v[132:133], v[52:53]
	v_cvt_pk_bf16_f32 v42, v46, v47
	s_nop 0
	v_cvt_pk_bf16_f32 v43, v48, v49
	v_cvt_pk_bf16_f32 v44, v44, v45
	v_cvt_pk_bf16_f32 v45, v50, v51
	flat_store_dwordx4 v[58:59], v[42:45]
	global_load_dwordx4 v[42:45], v[68:69], off offset:512
	s_nop 0
	global_load_dwordx4 v[46:49], v[68:69], off offset:528
	v_add_u32_e32 v50, 0xa0, v174
	v_ashrrev_i32_e32 v51, 31, v50
	v_lshlrev_b64 v[50:51], 10, v[50:51]
	v_lshl_add_u64 v[50:51], v[50:51], 0, v[172:173]
	v_lshl_add_u64 v[52:53], v[50:51], 2, s[64:65]
	s_waitcnt vmcnt(0)
	v_pk_fma_f32 v[38:39], v[38:39], v[142:143], v[42:43]
	v_pk_fma_f32 v[42:43], v[36:37], v[140:141], v[48:49]
	v_pk_fma_f32 v[36:37], v[34:35], v[138:139], v[46:47]
	v_pk_fma_f32 v[40:41], v[40:41], v[144:145], v[44:45]
	v_cvt_pk_bf16_f32 v34, v38, v39
	s_nop 0
	v_cvt_pk_bf16_f32 v35, v40, v41
	v_cvt_pk_bf16_f32 v36, v36, v37
	v_cvt_pk_bf16_f32 v37, v42, v43
	flat_store_dwordx4 v[58:59], v[34:37] offset:256
	global_load_dwordx4 v[34:37], v[52:53], off
	global_load_dwordx4 v[38:41], v[52:53], off offset:16
	v_lshl_add_u64 v[42:43], v[50:51], 1, s[4:5]
	s_waitcnt vmcnt(0)
	v_pk_fma_f32 v[30:31], v[30:31], v[130:131], v[34:35]
	v_pk_fma_f32 v[34:35], v[28:29], v[136:137], v[40:41]
	v_pk_fma_f32 v[28:29], v[26:27], v[134:135], v[38:39]
	v_pk_fma_f32 v[32:33], v[32:33], v[132:133], v[36:37]
	v_cvt_pk_bf16_f32 v26, v30, v31
	s_nop 0
	v_cvt_pk_bf16_f32 v27, v32, v33
	v_cvt_pk_bf16_f32 v28, v28, v29
	v_cvt_pk_bf16_f32 v29, v34, v35
	flat_store_dwordx4 v[42:43], v[26:29]
	global_load_dwordx4 v[26:29], v[52:53], off offset:512
	s_nop 0
	global_load_dwordx4 v[30:33], v[52:53], off offset:528
	v_add_u32_e32 v34, 0xb0, v174
	v_ashrrev_i32_e32 v35, 31, v34
	v_lshlrev_b64 v[34:35], 10, v[34:35]
	v_lshl_add_u64 v[34:35], v[34:35], 0, v[172:173]
	v_lshl_add_u64 v[36:37], v[34:35], 2, s[64:65]
	s_waitcnt vmcnt(0)
	v_pk_fma_f32 v[22:23], v[22:23], v[142:143], v[26:27]
	v_pk_fma_f32 v[26:27], v[20:21], v[140:141], v[32:33]
	v_pk_fma_f32 v[20:21], v[18:19], v[138:139], v[30:31]
	v_pk_fma_f32 v[24:25], v[24:25], v[144:145], v[28:29]
	v_cvt_pk_bf16_f32 v18, v22, v23
	s_nop 0
	v_cvt_pk_bf16_f32 v19, v24, v25
	v_cvt_pk_bf16_f32 v20, v20, v21
	v_cvt_pk_bf16_f32 v21, v26, v27
	flat_store_dwordx4 v[42:43], v[18:21] offset:256
	global_load_dwordx4 v[18:21], v[36:37], off
	s_nop 0
	global_load_dwordx4 v[22:25], v[36:37], off offset:16
	v_lshl_add_u64 v[26:27], v[34:35], 1, s[4:5]
	s_waitcnt vmcnt(0)
	v_pk_fma_f32 v[14:15], v[14:15], v[130:131], v[18:19]
	v_pk_fma_f32 v[18:19], v[12:13], v[136:137], v[24:25]
	v_pk_fma_f32 v[12:13], v[10:11], v[134:135], v[22:23]
	v_pk_fma_f32 v[16:17], v[16:17], v[132:133], v[20:21]
	v_cvt_pk_bf16_f32 v10, v14, v15
	s_nop 0
	v_cvt_pk_bf16_f32 v11, v16, v17
	v_cvt_pk_bf16_f32 v12, v12, v13
	v_cvt_pk_bf16_f32 v13, v18, v19
	flat_store_dwordx4 v[26:27], v[10:13]
	global_load_dwordx4 v[10:13], v[36:37], off offset:512
	s_nop 0
	global_load_dwordx4 v[14:17], v[36:37], off offset:528
	s_waitcnt vmcnt(0)
	v_pk_fma_f32 v[6:7], v[6:7], v[142:143], v[10:11]
	v_pk_fma_f32 v[10:11], v[4:5], v[140:141], v[16:17]
	v_pk_fma_f32 v[4:5], v[2:3], v[138:139], v[14:15]
	v_pk_fma_f32 v[8:9], v[8:9], v[144:145], v[12:13]
	v_cvt_pk_bf16_f32 v2, v6, v7
	s_nop 0
	v_cvt_pk_bf16_f32 v3, v8, v9
	v_cvt_pk_bf16_f32 v4, v4, v5
	v_cvt_pk_bf16_f32 v5, v10, v11
	flat_store_dwordx4 v[26:27], v[2:5] offset:256
	s_mov_b32 s98, 1
	s_cbranch_vccnz .LBB0_97
	s_andn2_b64 vcc, exec, s[6:7]
	s_cbranch_vccnz .LBB0_96
	s_barrier
	s_branch .LBB0_96

.LBB0_347:
	v_lshrrev_b32_e32 v17, 1, v158
	v_and_b32_e32 v17, 24, v17
	v_and_b32_e32 v16, 15, v158
	v_lshlrev_b32_e32 v18, 1, v17
	s_add_u32 s6, s2, 0x9c00000
	v_lshl_or_b32 v142, s9, 6, v16
	v_lshl_or_b32 v16, v16, 6, v18
	v_lshlrev_b32_e32 v18, 2, v158
	s_sext_i32_i8 s44, s0
	s_addc_u32 s7, s3, 0
	s_lshl_b32 s0, s9, 13
	v_and_b32_e32 v18, 32, v18
	v_bitop3_b32 v19, v16, s0, v18 bitop3:0xde
	s_lshl_b32 s0, s8, 5
	s_and_b32 s0, s0, 0x60
	s_add_i32 m0, s19, 0x18000
	v_lshl_add_u64 v[8:9], v[8:9], 0, s[96:97]
	s_lshl_b32 s8, s0, 7
	s_waitcnt vmcnt(2)
	s_barrier
	global_load_lds_dwordx4 v[8:9], off
	v_lshl_add_u64 v[6:7], v[6:7], 0, s[96:97]
	s_add_i32 m0, s19, 0x1a000
	s_add_i32 s40, s19, 0x8000
	s_add_i32 s41, s19, 0xa000
	v_bitop3_b32 v143, s8, v16, v18 bitop3:0xf6
	global_load_lds_dwordx4 v[6:7], off
	v_lshl_add_u64 v[2:3], v[2:3], 0, s[96:97]
	s_mov_b32 m0, s40
	s_add_u32 s8, s20, 0x40080
	global_load_lds_dwordx4 v[2:3], off
	v_lshl_add_u64 v[2:3], v[4:5], 0, s[96:97]
	s_mov_b32 m0, s41
	s_addc_u32 s9, s21, 0
	global_load_lds_dwordx4 v[2:3], off
	s_add_i32 m0, s19, 0x1c000
	v_lshl_add_u64 v[2:3], s[8:9], 0, v[0:1]
	global_load_lds_dwordx4 v[2:3], off
	v_lshl_add_u64 v[2:3], s[8:9], 0, v[130:131]
	s_add_i32 m0, s19, 0x1e000
	s_cmpk_lt_u32 s1, 0x100
	global_load_lds_dwordx4 v[2:3], off
	v_lshlrev_b32_e32 v2, 14, v10
	v_and_b32_e32 v2, 0xffff8000, v2
	v_lshl_add_u32 v2, v11, 11, v2
	v_and_b32_e32 v3, 1, v10
	v_lshl_or_b32 v2, v3, 6, v2
	v_lshl_add_u32 v136, v12, 1, v2
	v_lshlrev_b32_e32 v2, 14, v14
	v_and_b32_e32 v2, 0xffff8000, v2
	s_waitcnt vmcnt(6)
	v_lshl_add_u32 v2, v13, 11, v2
	v_and_b32_e32 v3, 1, v14
	v_lshl_or_b32 v2, v3, 6, v2
	s_cselect_b64 s[8:9], -1, 0
	s_ashr_i32 s42, s36, 31
	v_or_b32_e32 v144, s0, v17
	v_mov_b32_e32 v137, v1
	v_lshl_add_u32 v138, v15, 1, v2
	v_mov_b32_e32 v139, v1
	s_mov_b32 s43, 0
	v_add_u32_e32 v145, 0, v19
	s_barrier
	s_mov_b32 s98, 0
	s_branch .LBB0_350

.LBB0_353:
	s_add_u32 s22, s20, 0xfffc0080
	s_addc_u32 s23, s21, -1
	s_add_i32 s55, 0, 0x10000
	s_cmp_eq_u32 s49, 12
	s_cselect_b32 s25, s13, s23
	s_cselect_b32 s24, s45, s22
	v_add_u32_e32 v140, s55, v143
	s_cselect_b32 s23, s11, s48
	s_cselect_b32 s22, s46, s47
	s_add_i32 s58, 0, 0x14000
	ds_read_b128 v[162:165], v140
	ds_read_b128 v[166:169], v140 offset:1024
	ds_read_b128 v[170:173], v140 offset:2048
	ds_read_b128 v[174:177], v140 offset:3072
	v_add_u32_e32 v140, s58, v143
	ds_read_b128 v[178:181], v140
	ds_read_b128 v[182:185], v140 offset:1024
	ds_read_b128 v[186:189], v140 offset:2048
	ds_read_b128 v[190:193], v140 offset:3072
	v_lshl_add_u64 v[140:141], s[20:21], 0, v[138:139]
	s_add_i32 m0, s19, 0xc000
	ds_read_b128 v[194:197], v145
	ds_read_b128 v[198:201], v145 offset:1024
	ds_read_b128 v[202:205], v145 offset:2048
	ds_read_b128 v[206:209], v145 offset:3072
	ds_read_b128 v[210:213], v145 offset:4096
	ds_read_b128 v[222:225], v145 offset:5120
	ds_read_b128 v[226:229], v145 offset:6144
	ds_read_b128 v[230:233], v145 offset:7168
	global_load_lds_dwordx4 v[140:141], off
	v_lshl_add_u64 v[140:141], s[20:21], 0, v[136:137]
	s_add_i32 m0, s19, 0xe000
	s_nop 0
	global_load_lds_dwordx4 v[140:141], off
	s_cmp_lg_u32 s98, 0
	s_cbranch_scc1 .Lrelax_g4_w1
	s_waitcnt vmcnt(8)
.Lback_g4_w1:
	s_waitcnt lgkmcnt(0)
	s_barrier
	s_setprio 1
	s_waitcnt lgkmcnt(0)
	v_mfma_f32_16x16x32_bf16 v[126:129], v[162:165], v[194:197], v[126:129]
	v_mfma_f32_16x16x32_bf16 v[122:125], v[170:173], v[194:197], v[122:125]
	v_mfma_f32_16x16x32_bf16 v[114:117], v[162:165], v[202:205], v[114:117]
	v_mfma_f32_16x16x32_bf16 v[106:109], v[170:173], v[202:205], v[106:109]
	v_mfma_f32_16x16x32_bf16 v[98:101], v[162:165], v[210:213], v[98:101]
	v_mfma_f32_16x16x32_bf16 v[90:93], v[170:173], v[210:213], v[90:93]
	v_mfma_f32_16x16x32_bf16 v[82:85], v[162:165], v[226:229], v[82:85]
	v_mfma_f32_16x16x32_bf16 v[74:77], v[170:173], v[226:229], v[74:77]
	v_mfma_f32_16x16x32_bf16 v[126:129], v[166:169], v[198:201], v[126:129]
	v_mfma_f32_16x16x32_bf16 v[122:125], v[174:177], v[198:201], v[122:125]
	v_mfma_f32_16x16x32_bf16 v[114:117], v[166:169], v[206:209], v[114:117]
	v_mfma_f32_16x16x32_bf16 v[106:109], v[174:177], v[206:209], v[106:109]
	v_mfma_f32_16x16x32_bf16 v[98:101], v[166:169], v[222:225], v[98:101]
	v_mfma_f32_16x16x32_bf16 v[90:93], v[174:177], v[222:225], v[90:93]
	v_mfma_f32_16x16x32_bf16 v[82:85], v[166:169], v[230:233], v[82:85]
	v_mfma_f32_16x16x32_bf16 v[74:77], v[174:177], v[230:233], v[74:77]
	s_setprio 0
	s_setprio 1
	v_mfma_f32_16x16x32_bf16 v[118:121], v[178:181], v[194:197], v[118:121]
	v_mfma_f32_16x16x32_bf16 v[110:113], v[186:189], v[194:197], v[110:113]
	v_mfma_f32_16x16x32_bf16 v[102:105], v[178:181], v[202:205], v[102:105]
	v_mfma_f32_16x16x32_bf16 v[94:97], v[186:189], v[202:205], v[94:97]
	v_mfma_f32_16x16x32_bf16 v[86:89], v[178:181], v[210:213], v[86:89]
	v_mfma_f32_16x16x32_bf16 v[78:81], v[186:189], v[210:213], v[78:81]
	v_mfma_f32_16x16x32_bf16 v[70:73], v[178:181], v[226:229], v[70:73]
	v_mfma_f32_16x16x32_bf16 v[66:69], v[186:189], v[226:229], v[66:69]
	v_mfma_f32_16x16x32_bf16 v[118:121], v[182:185], v[198:201], v[118:121]
	v_mfma_f32_16x16x32_bf16 v[110:113], v[190:193], v[198:201], v[110:113]
	v_mfma_f32_16x16x32_bf16 v[102:105], v[182:185], v[206:209], v[102:105]
	v_mfma_f32_16x16x32_bf16 v[94:97], v[190:193], v[206:209], v[94:97]
	v_mfma_f32_16x16x32_bf16 v[86:89], v[182:185], v[222:225], v[86:89]
	v_mfma_f32_16x16x32_bf16 v[78:81], v[190:193], v[222:225], v[78:81]
	v_mfma_f32_16x16x32_bf16 v[70:73], v[182:185], v[230:233], v[70:73]
	v_mfma_f32_16x16x32_bf16 v[66:69], v[190:193], v[230:233], v[66:69]
	s_setprio 0
	s_barrier
	s_add_i32 s55, s55, s30
	v_lshl_add_u64 v[140:141], s[22:23], 0, v[0:1]
	s_mov_b32 m0, s55
	ds_read_b128 v[194:197], v145 offset:16384
	ds_read_b128 v[198:201], v145 offset:17408
	ds_read_b128 v[202:205], v145 offset:18432
	ds_read_b128 v[206:209], v145 offset:19456
	ds_read_b128 v[210:213], v145 offset:20480
	ds_read_b128 v[222:225], v145 offset:21504
	ds_read_b128 v[226:229], v145 offset:22528
	ds_read_b128 v[230:233], v145 offset:23552
	global_load_lds_dwordx4 v[140:141], off
	s_add_i32 m0, s55, 0x2000
	s_add_u32 s56, s22, 0x40000
	v_lshl_add_u64 v[146:147], s[22:23], 0, v[130:131]
	s_addc_u32 s57, s23, 0
	s_add_i32 s55, s58, s30
	global_load_lds_dwordx4 v[146:147], off
	v_lshl_add_u64 v[148:149], s[56:57], 0, v[0:1]
	s_mov_b32 m0, s55
	v_lshl_add_u64 v[154:155], s[24:25], 0, v[132:133]
	global_load_lds_dwordx4 v[148:149], off
	v_lshl_add_u64 v[148:149], s[56:57], 0, v[130:131]
	s_add_i32 m0, s55, 0x2000
	s_nop 0
	global_load_lds_dwordx4 v[148:149], off
	v_lshl_add_u64 v[148:149], s[24:25], 0, v[134:135]
	s_mov_b32 m0, s19
	s_nop 0
	global_load_lds_dwordx4 v[148:149], off
	s_mov_b32 m0, s37
	s_nop 0
	global_load_lds_dwordx4 v[154:155], off
	s_cmp_lg_u32 s98, 0
	s_cbranch_scc1 .Lrelax_g4_w2
	s_waitcnt vmcnt(8)
.Lback_g4_w2:
	s_waitcnt lgkmcnt(0)
	s_barrier
	s_setprio 1
	s_waitcnt lgkmcnt(0)
	v_mfma_f32_16x16x32_bf16 v[62:65], v[162:165], v[194:197], v[62:65]
	v_mfma_f32_16x16x32_bf16 v[58:61], v[170:173], v[194:197], v[58:61]
	v_mfma_f32_16x16x32_bf16 v[50:53], v[162:165], v[202:205], v[50:53]
	v_mfma_f32_16x16x32_bf16 v[42:45], v[170:173], v[202:205], v[42:45]
	v_mfma_f32_16x16x32_bf16 v[34:37], v[162:165], v[210:213], v[34:37]
	v_mfma_f32_16x16x32_bf16 v[26:29], v[170:173], v[210:213], v[26:29]
	v_mfma_f32_16x16x32_bf16 v[18:21], v[162:165], v[226:229], v[18:21]
	v_mfma_f32_16x16x32_bf16 v[10:13], v[170:173], v[226:229], v[10:13]
	v_mfma_f32_16x16x32_bf16 v[62:65], v[166:169], v[198:201], v[62:65]
	v_mfma_f32_16x16x32_bf16 v[58:61], v[174:177], v[198:201], v[58:61]
	v_mfma_f32_16x16x32_bf16 v[50:53], v[166:169], v[206:209], v[50:53]
	v_mfma_f32_16x16x32_bf16 v[42:45], v[174:177], v[206:209], v[42:45]
	v_mfma_f32_16x16x32_bf16 v[34:37], v[166:169], v[222:225], v[34:37]
	v_mfma_f32_16x16x32_bf16 v[26:29], v[174:177], v[222:225], v[26:29]
	v_mfma_f32_16x16x32_bf16 v[18:21], v[166:169], v[230:233], v[18:21]
	v_mfma_f32_16x16x32_bf16 v[10:13], v[174:177], v[230:233], v[10:13]
	s_setprio 0
	s_setprio 1
	v_mfma_f32_16x16x32_bf16 v[54:57], v[178:181], v[194:197], v[54:57]
	v_mfma_f32_16x16x32_bf16 v[46:49], v[186:189], v[194:197], v[46:49]
	v_mfma_f32_16x16x32_bf16 v[38:41], v[178:181], v[202:205], v[38:41]
	v_mfma_f32_16x16x32_bf16 v[30:33], v[186:189], v[202:205], v[30:33]
	v_mfma_f32_16x16x32_bf16 v[22:25], v[178:181], v[210:213], v[22:25]
	v_mfma_f32_16x16x32_bf16 v[14:17], v[186:189], v[210:213], v[14:17]
	v_mfma_f32_16x16x32_bf16 v[6:9], v[178:181], v[226:229], v[6:9]
	v_mfma_f32_16x16x32_bf16 v[2:5], v[186:189], v[226:229], v[2:5]
	v_mfma_f32_16x16x32_bf16 v[54:57], v[182:185], v[198:201], v[54:57]
	v_mfma_f32_16x16x32_bf16 v[46:49], v[190:193], v[198:201], v[46:49]
	v_mfma_f32_16x16x32_bf16 v[38:41], v[182:185], v[206:209], v[38:41]
	v_mfma_f32_16x16x32_bf16 v[30:33], v[190:193], v[206:209], v[30:33]
	v_mfma_f32_16x16x32_bf16 v[22:25], v[182:185], v[222:225], v[22:25]
	v_mfma_f32_16x16x32_bf16 v[14:17], v[190:193], v[222:225], v[14:17]
	v_mfma_f32_16x16x32_bf16 v[6:9], v[182:185], v[230:233], v[6:9]
	v_mfma_f32_16x16x32_bf16 v[2:5], v[190:193], v[230:233], v[2:5]
	s_setprio 0
	s_barrier
	s_add_i32 s55, 0, 0x18000
	v_add_u32_e32 v156, s55, v143
	s_add_i32 s56, 0, 0x1c000
	ds_read_b128 v[162:165], v156
	ds_read_b128 v[166:169], v156 offset:1024
	ds_read_b128 v[170:173], v156 offset:2048
	ds_read_b128 v[174:177], v156 offset:3072
	v_add_u32_e32 v156, s56, v143
	ds_read_b128 v[178:181], v156
	ds_read_b128 v[182:185], v156 offset:1024
	ds_read_b128 v[186:189], v156 offset:2048
	ds_read_b128 v[190:193], v156 offset:3072
	s_add_u32 s24, s24, 0x40000
	s_addc_u32 s25, s25, 0
	s_mov_b32 m0, s38
	v_lshl_add_u64 v[156:157], s[24:25], 0, v[134:135]
	ds_read_b128 v[194:197], v145 offset:32768
	ds_read_b128 v[198:201], v145 offset:33792
	ds_read_b128 v[202:205], v145 offset:34816
	ds_read_b128 v[206:209], v145 offset:35840
	ds_read_b128 v[210:213], v145 offset:36864
	ds_read_b128 v[222:225], v145 offset:37888
	ds_read_b128 v[226:229], v145 offset:38912
	ds_read_b128 v[230:233], v145 offset:39936
	global_load_lds_dwordx4 v[156:157], off
	v_lshl_add_u64 v[156:157], s[24:25], 0, v[132:133]
	s_mov_b32 m0, s39
	s_nop 0
	global_load_lds_dwordx4 v[156:157], off
	s_waitcnt vmcnt(8)
	s_waitcnt lgkmcnt(0)
	s_barrier
	s_setprio 1
	s_waitcnt lgkmcnt(0)
	v_mfma_f32_16x16x32_bf16 v[126:129], v[162:165], v[194:197], v[126:129]
	v_mfma_f32_16x16x32_bf16 v[122:125], v[170:173], v[194:197], v[122:125]
	v_mfma_f32_16x16x32_bf16 v[114:117], v[162:165], v[202:205], v[114:117]
	v_mfma_f32_16x16x32_bf16 v[106:109], v[170:173], v[202:205], v[106:109]
	v_mfma_f32_16x16x32_bf16 v[98:101], v[162:165], v[210:213], v[98:101]
	v_mfma_f32_16x16x32_bf16 v[90:93], v[170:173], v[210:213], v[90:93]
	v_mfma_f32_16x16x32_bf16 v[82:85], v[162:165], v[226:229], v[82:85]
	v_mfma_f32_16x16x32_bf16 v[74:77], v[170:173], v[226:229], v[74:77]
	v_mfma_f32_16x16x32_bf16 v[126:129], v[166:169], v[198:201], v[126:129]
	v_mfma_f32_16x16x32_bf16 v[122:125], v[174:177], v[198:201], v[122:125]
	v_mfma_f32_16x16x32_bf16 v[114:117], v[166:169], v[206:209], v[114:117]
	v_mfma_f32_16x16x32_bf16 v[106:109], v[174:177], v[206:209], v[106:109]
	v_mfma_f32_16x16x32_bf16 v[98:101], v[166:169], v[222:225], v[98:101]
	v_mfma_f32_16x16x32_bf16 v[90:93], v[174:177], v[222:225], v[90:93]
	v_mfma_f32_16x16x32_bf16 v[82:85], v[166:169], v[230:233], v[82:85]
	v_mfma_f32_16x16x32_bf16 v[74:77], v[174:177], v[230:233], v[74:77]
	s_setprio 0
	s_setprio 1
	v_mfma_f32_16x16x32_bf16 v[118:121], v[178:181], v[194:197], v[118:121]
	v_mfma_f32_16x16x32_bf16 v[110:113], v[186:189], v[194:197], v[110:113]
	v_mfma_f32_16x16x32_bf16 v[102:105], v[178:181], v[202:205], v[102:105]
	v_mfma_f32_16x16x32_bf16 v[94:97], v[186:189], v[202:205], v[94:97]
	v_mfma_f32_16x16x32_bf16 v[86:89], v[178:181], v[210:213], v[86:89]
	v_mfma_f32_16x16x32_bf16 v[78:81], v[186:189], v[210:213], v[78:81]
	v_mfma_f32_16x16x32_bf16 v[70:73], v[178:181], v[226:229], v[70:73]
	v_mfma_f32_16x16x32_bf16 v[66:69], v[186:189], v[226:229], v[66:69]
	v_mfma_f32_16x16x32_bf16 v[118:121], v[182:185], v[198:201], v[118:121]
	v_mfma_f32_16x16x32_bf16 v[110:113], v[190:193], v[198:201], v[110:113]
	v_mfma_f32_16x16x32_bf16 v[102:105], v[182:185], v[206:209], v[102:105]
	v_mfma_f32_16x16x32_bf16 v[94:97], v[190:193], v[206:209], v[94:97]
	v_mfma_f32_16x16x32_bf16 v[86:89], v[182:185], v[222:225], v[86:89]
	v_mfma_f32_16x16x32_bf16 v[78:81], v[190:193], v[222:225], v[78:81]
	v_mfma_f32_16x16x32_bf16 v[70:73], v[182:185], v[230:233], v[70:73]
	v_mfma_f32_16x16x32_bf16 v[66:69], v[190:193], v[230:233], v[66:69]
	s_setprio 0
	s_barrier
	s_add_i32 s24, s55, s30
	v_lshl_add_u64 v[140:141], v[140:141], 0, s[96:97]
	s_mov_b32 m0, s24
	ds_read_b128 v[194:197], v145 offset:49152
	ds_read_b128 v[198:201], v145 offset:50176
	ds_read_b128 v[202:205], v145 offset:51200
	ds_read_b128 v[206:209], v145 offset:52224
	ds_read_b128 v[210:213], v145 offset:53248
	ds_read_b128 v[222:225], v145 offset:54272
	ds_read_b128 v[226:229], v145 offset:55296
	ds_read_b128 v[230:233], v145 offset:56320
	global_load_lds_dwordx4 v[140:141], off
	s_add_i32 m0, s24, 0x2000
	s_add_u32 s22, s22, 0x40080
	v_lshl_add_u64 v[140:141], v[146:147], 0, s[96:97]
	s_addc_u32 s23, s23, 0
	s_add_i32 s24, s56, s30
	global_load_lds_dwordx4 v[140:141], off
	v_lshl_add_u64 v[140:141], s[22:23], 0, v[0:1]
	s_mov_b32 m0, s24
	s_nop 0
	global_load_lds_dwordx4 v[140:141], off
	v_lshl_add_u64 v[140:141], s[22:23], 0, v[130:131]
	s_add_i32 m0, s24, 0x2000
	s_nop 0
	global_load_lds_dwordx4 v[140:141], off
	v_lshl_add_u64 v[140:141], v[148:149], 0, s[96:97]
	s_mov_b32 m0, s40
	s_nop 0
	global_load_lds_dwordx4 v[140:141], off
	v_lshl_add_u64 v[140:141], v[154:155], 0, s[96:97]
	s_mov_b32 m0, s41
	s_nop 0
	global_load_lds_dwordx4 v[140:141], off
	s_waitcnt vmcnt(8)
	s_waitcnt lgkmcnt(0)
	s_barrier
	s_setprio 1
	s_waitcnt lgkmcnt(0)
	v_mfma_f32_16x16x32_bf16 v[62:65], v[162:165], v[194:197], v[62:65]
	v_mfma_f32_16x16x32_bf16 v[58:61], v[170:173], v[194:197], v[58:61]
	v_mfma_f32_16x16x32_bf16 v[50:53], v[162:165], v[202:205], v[50:53]
	v_mfma_f32_16x16x32_bf16 v[42:45], v[170:173], v[202:205], v[42:45]
	v_mfma_f32_16x16x32_bf16 v[34:37], v[162:165], v[210:213], v[34:37]
	v_mfma_f32_16x16x32_bf16 v[26:29], v[170:173], v[210:213], v[26:29]
	v_mfma_f32_16x16x32_bf16 v[18:21], v[162:165], v[226:229], v[18:21]
	v_mfma_f32_16x16x32_bf16 v[10:13], v[170:173], v[226:229], v[10:13]
	v_mfma_f32_16x16x32_bf16 v[62:65], v[166:169], v[198:201], v[62:65]
	v_mfma_f32_16x16x32_bf16 v[58:61], v[174:177], v[198:201], v[58:61]
	v_mfma_f32_16x16x32_bf16 v[50:53], v[166:169], v[206:209], v[50:53]
	v_mfma_f32_16x16x32_bf16 v[42:45], v[174:177], v[206:209], v[42:45]
	v_mfma_f32_16x16x32_bf16 v[34:37], v[166:169], v[222:225], v[34:37]
	v_mfma_f32_16x16x32_bf16 v[26:29], v[174:177], v[222:225], v[26:29]
	v_mfma_f32_16x16x32_bf16 v[18:21], v[166:169], v[230:233], v[18:21]
	v_mfma_f32_16x16x32_bf16 v[10:13], v[174:177], v[230:233], v[10:13]
	s_setprio 0
	s_setprio 1
	v_mfma_f32_16x16x32_bf16 v[54:57], v[178:181], v[194:197], v[54:57]
	v_mfma_f32_16x16x32_bf16 v[46:49], v[186:189], v[194:197], v[46:49]
	v_mfma_f32_16x16x32_bf16 v[38:41], v[178:181], v[202:205], v[38:41]
	v_mfma_f32_16x16x32_bf16 v[30:33], v[186:189], v[202:205], v[30:33]
	v_mfma_f32_16x16x32_bf16 v[22:25], v[178:181], v[210:213], v[22:25]
	v_mfma_f32_16x16x32_bf16 v[14:17], v[186:189], v[210:213], v[14:17]
	v_mfma_f32_16x16x32_bf16 v[6:9], v[178:181], v[226:229], v[6:9]
	v_mfma_f32_16x16x32_bf16 v[2:5], v[186:189], v[226:229], v[2:5]
	v_mfma_f32_16x16x32_bf16 v[54:57], v[182:185], v[198:201], v[54:57]
	v_mfma_f32_16x16x32_bf16 v[46:49], v[190:193], v[198:201], v[46:49]
	v_mfma_f32_16x16x32_bf16 v[38:41], v[182:185], v[206:209], v[38:41]
	v_mfma_f32_16x16x32_bf16 v[30:33], v[190:193], v[206:209], v[30:33]
	v_mfma_f32_16x16x32_bf16 v[22:25], v[182:185], v[222:225], v[22:25]
	v_mfma_f32_16x16x32_bf16 v[14:17], v[190:193], v[222:225], v[14:17]
	v_mfma_f32_16x16x32_bf16 v[6:9], v[182:185], v[230:233], v[6:9]
	v_mfma_f32_16x16x32_bf16 v[2:5], v[190:193], v[230:233], v[2:5]
	s_setprio 0
	s_barrier
	s_add_i32 s49, s49, 2
	s_add_u32 s47, s47, 0x100
	s_addc_u32 s48, s48, 0
	s_add_u32 s20, s20, 0x100
	s_addc_u32 s21, s21, 0
	s_cmp_gt_u32 s49, 13
	s_cbranch_scc0 .LBB0_353
	s_and_b64 vcc, exec, s[8:9]
	s_cbranch_vccz .LBB0_356
	s_barrier
.LBB0_356:
	v_lshl_or_b32 v140, s44, 8, v144
	v_ashrrev_i32_e32 v141, 31, v140
	v_lshl_add_u32 v154, s18, 8, v142
	v_lshl_add_u64 v[140:141], v[140:141], 1, s[6:7]
	s_movk_i32 s11, 0x1800
	v_mad_i64_i32 v[146:147], s[20:21], v154, s11, v[140:141]
	v_pk_add_f32 v[128:129], v[128:129], 0 op_sel_hi:[1,0]
	v_pk_add_f32 v[126:127], v[126:127], 0 op_sel_hi:[1,0]
	v_pk_add_f32 v[148:149], v[124:125], 0 op_sel_hi:[1,0]
	v_pk_add_f32 v[124:125], v[122:123], 0 op_sel_hi:[1,0]
	v_cvt_pk_bf16_f32 v122, v126, v127
	v_cvt_pk_bf16_f32 v123, v128, v129
	v_pk_add_f32 v[118:119], v[118:119], 0 op_sel_hi:[1,0]
	v_cvt_pk_bf16_f32 v124, v124, v125
	v_cvt_pk_bf16_f32 v125, v148, v149
	global_store_dwordx4 v[146:147], v[122:125], off nt
	v_pk_add_f32 v[120:121], v[120:121], 0 op_sel_hi:[1,0]
	v_pk_add_f32 v[114:115], v[114:115], 0 op_sel_hi:[1,0]
	v_pk_add_f32 v[122:123], v[112:113], 0 op_sel_hi:[1,0]
	v_pk_add_f32 v[112:113], v[110:111], 0 op_sel_hi:[1,0]
	v_cvt_pk_bf16_f32 v110, v118, v119
	v_cvt_pk_bf16_f32 v111, v120, v121
	v_pk_add_f32 v[102:103], v[102:103], 0 op_sel_hi:[1,0]
	v_cvt_pk_bf16_f32 v112, v112, v113
	v_cvt_pk_bf16_f32 v113, v122, v123
	global_store_dwordx4 v[146:147], v[110:113], off offset:256 nt
	v_pk_add_f32 v[104:105], v[104:105], 0 op_sel_hi:[1,0]
	v_pk_add_f32 v[98:99], v[98:99], 0 op_sel_hi:[1,0]
	v_or_b32_e32 v110, 16, v154
	v_mad_i64_i32 v[110:111], s[20:21], v110, s11, v[140:141]
	v_pk_add_f32 v[112:113], v[116:117], 0 op_sel_hi:[1,0]
	v_pk_add_f32 v[116:117], v[108:109], 0 op_sel_hi:[1,0]
	v_pk_add_f32 v[108:109], v[106:107], 0 op_sel_hi:[1,0]
	v_cvt_pk_bf16_f32 v106, v114, v115
	v_cvt_pk_bf16_f32 v107, v112, v113
	v_pk_add_f32 v[86:87], v[86:87], 0 op_sel_hi:[1,0]
	v_cvt_pk_bf16_f32 v108, v108, v109
	v_cvt_pk_bf16_f32 v109, v116, v117
	global_store_dwordx4 v[110:111], v[106:109], off nt
	v_pk_add_f32 v[88:89], v[88:89], 0 op_sel_hi:[1,0]
	v_pk_add_f32 v[82:83], v[82:83], 0 op_sel_hi:[1,0]
	v_pk_add_f32 v[106:107], v[96:97], 0 op_sel_hi:[1,0]
	v_pk_add_f32 v[96:97], v[94:95], 0 op_sel_hi:[1,0]
	v_cvt_pk_bf16_f32 v94, v102, v103
	v_cvt_pk_bf16_f32 v95, v104, v105
	v_pk_add_f32 v[70:71], v[70:71], 0 op_sel_hi:[1,0]
	v_cvt_pk_bf16_f32 v96, v96, v97
	v_cvt_pk_bf16_f32 v97, v106, v107
	global_store_dwordx4 v[110:111], v[94:97], off offset:256 nt
	v_pk_add_f32 v[72:73], v[72:73], 0 op_sel_hi:[1,0]
	v_pk_add_f32 v[64:65], v[64:65], 0 op_sel_hi:[1,0]
	v_or_b32_e32 v94, 32, v154
	v_mad_i64_i32 v[94:95], s[20:21], v94, s11, v[140:141]
	v_pk_add_f32 v[96:97], v[100:101], 0 op_sel_hi:[1,0]
	v_pk_add_f32 v[100:101], v[92:93], 0 op_sel_hi:[1,0]
	v_pk_add_f32 v[92:93], v[90:91], 0 op_sel_hi:[1,0]
	v_cvt_pk_bf16_f32 v90, v98, v99
	v_cvt_pk_bf16_f32 v91, v96, v97
	v_pk_add_f32 v[62:63], v[62:63], 0 op_sel_hi:[1,0]
	v_cvt_pk_bf16_f32 v92, v92, v93
	v_cvt_pk_bf16_f32 v93, v100, v101
	global_store_dwordx4 v[94:95], v[90:93], off nt
	v_pk_add_f32 v[54:55], v[54:55], 0 op_sel_hi:[1,0]
	v_pk_add_f32 v[56:57], v[56:57], 0 op_sel_hi:[1,0]
	v_pk_add_f32 v[90:91], v[80:81], 0 op_sel_hi:[1,0]
	v_pk_add_f32 v[80:81], v[78:79], 0 op_sel_hi:[1,0]
	v_cvt_pk_bf16_f32 v78, v86, v87
	v_cvt_pk_bf16_f32 v79, v88, v89
	v_pk_add_f32 v[50:51], v[50:51], 0 op_sel_hi:[1,0]
	v_cvt_pk_bf16_f32 v80, v80, v81
	v_cvt_pk_bf16_f32 v81, v90, v91
	global_store_dwordx4 v[94:95], v[78:81], off offset:256 nt
	v_pk_add_f32 v[38:39], v[38:39], 0 op_sel_hi:[1,0]
	v_pk_add_f32 v[40:41], v[40:41], 0 op_sel_hi:[1,0]
	v_or_b32_e32 v78, 48, v154
	v_mad_i64_i32 v[78:79], s[20:21], v78, s11, v[140:141]
	v_pk_add_f32 v[80:81], v[84:85], 0 op_sel_hi:[1,0]
	v_pk_add_f32 v[84:85], v[76:77], 0 op_sel_hi:[1,0]
	v_pk_add_f32 v[76:77], v[74:75], 0 op_sel_hi:[1,0]
	v_cvt_pk_bf16_f32 v74, v82, v83
	v_cvt_pk_bf16_f32 v75, v80, v81
	v_pk_add_f32 v[34:35], v[34:35], 0 op_sel_hi:[1,0]
	v_cvt_pk_bf16_f32 v76, v76, v77
	v_cvt_pk_bf16_f32 v77, v84, v85
	global_store_dwordx4 v[78:79], v[74:77], off nt
	v_pk_add_f32 v[22:23], v[22:23], 0 op_sel_hi:[1,0]
	v_pk_add_f32 v[24:25], v[24:25], 0 op_sel_hi:[1,0]
	v_pk_add_f32 v[74:75], v[68:69], 0 op_sel_hi:[1,0]
	v_pk_add_f32 v[68:69], v[66:67], 0 op_sel_hi:[1,0]
	v_cvt_pk_bf16_f32 v66, v70, v71
	v_cvt_pk_bf16_f32 v67, v72, v73
	v_pk_add_f32 v[18:19], v[18:19], 0 op_sel_hi:[1,0]
	v_cvt_pk_bf16_f32 v68, v68, v69
	v_cvt_pk_bf16_f32 v69, v74, v75
	global_store_dwordx4 v[78:79], v[66:69], off offset:256 nt
	s_andn2_b64 vcc, exec, s[0:1]
	s_mov_b64 s[0:1], -1
	v_add_u32_e32 v66, 0x80, v154
	v_mad_i64_i32 v[66:67], s[20:21], v66, s11, v[140:141]
	v_pk_add_f32 v[68:69], v[60:61], 0 op_sel_hi:[1,0]
	v_pk_add_f32 v[60:61], v[58:59], 0 op_sel_hi:[1,0]
	v_cvt_pk_bf16_f32 v58, v62, v63
	v_cvt_pk_bf16_f32 v59, v64, v65
	s_movk_i32 s46, 0xd000
	v_cvt_pk_bf16_f32 v60, v60, v61
	v_cvt_pk_bf16_f32 v61, v68, v69
	global_store_dwordx4 v[66:67], v[58:61], off nt
	s_movk_i32 s47, 0xec00
	s_movk_i32 s55, 0xf000
	v_pk_add_f32 v[58:59], v[48:49], 0 op_sel_hi:[1,0]
	v_pk_add_f32 v[48:49], v[46:47], 0 op_sel_hi:[1,0]
	v_cvt_pk_bf16_f32 v46, v54, v55
	v_cvt_pk_bf16_f32 v47, v56, v57
	v_pk_add_f32 v[8:9], v[8:9], 0 op_sel_hi:[1,0]
	v_cvt_pk_bf16_f32 v48, v48, v49
	v_cvt_pk_bf16_f32 v49, v58, v59
	global_store_dwordx4 v[66:67], v[46:49], off offset:256 nt
	v_pk_add_f32 v[6:7], v[6:7], 0 op_sel_hi:[1,0]
	s_nop 0
	v_add_u32_e32 v46, 0x90, v154
	v_mad_i64_i32 v[46:47], s[20:21], v46, s11, v[140:141]
	v_pk_add_f32 v[48:49], v[52:53], 0 op_sel_hi:[1,0]
	v_pk_add_f32 v[52:53], v[44:45], 0 op_sel_hi:[1,0]
	v_pk_add_f32 v[44:45], v[42:43], 0 op_sel_hi:[1,0]
	v_cvt_pk_bf16_f32 v42, v50, v51
	v_cvt_pk_bf16_f32 v43, v48, v49
	s_nop 0
	v_cvt_pk_bf16_f32 v44, v44, v45
	v_cvt_pk_bf16_f32 v45, v52, v53
	global_store_dwordx4 v[46:47], v[42:45], off nt
	s_nop 1
	v_pk_add_f32 v[42:43], v[32:33], 0 op_sel_hi:[1,0]
	v_pk_add_f32 v[32:33], v[30:31], 0 op_sel_hi:[1,0]
	v_cvt_pk_bf16_f32 v30, v38, v39
	v_cvt_pk_bf16_f32 v31, v40, v41
	s_nop 0
	v_cvt_pk_bf16_f32 v32, v32, v33
	v_cvt_pk_bf16_f32 v33, v42, v43
	global_store_dwordx4 v[46:47], v[30:33], off offset:256 nt
	s_nop 1
	v_add_u32_e32 v30, 0xa0, v154
	v_mad_i64_i32 v[30:31], s[20:21], v30, s11, v[140:141]
	v_pk_add_f32 v[32:33], v[36:37], 0 op_sel_hi:[1,0]
	v_pk_add_f32 v[36:37], v[28:29], 0 op_sel_hi:[1,0]
	v_pk_add_f32 v[28:29], v[26:27], 0 op_sel_hi:[1,0]
	v_cvt_pk_bf16_f32 v26, v34, v35
	v_cvt_pk_bf16_f32 v27, v32, v33
	s_nop 0
	v_cvt_pk_bf16_f32 v28, v28, v29
	v_cvt_pk_bf16_f32 v29, v36, v37
	global_store_dwordx4 v[30:31], v[26:29], off nt
	s_nop 1
	v_pk_add_f32 v[26:27], v[16:17], 0 op_sel_hi:[1,0]
	v_pk_add_f32 v[16:17], v[14:15], 0 op_sel_hi:[1,0]
	v_cvt_pk_bf16_f32 v14, v22, v23
	v_cvt_pk_bf16_f32 v15, v24, v25
	s_nop 0
	v_cvt_pk_bf16_f32 v16, v16, v17
	v_cvt_pk_bf16_f32 v17, v26, v27
	global_store_dwordx4 v[30:31], v[14:17], off offset:256 nt
	s_nop 1
	v_add_u32_e32 v14, 0xb0, v154
	v_mad_i64_i32 v[14:15], s[20:21], v14, s11, v[140:141]
	v_pk_add_f32 v[16:17], v[20:21], 0 op_sel_hi:[1,0]
	v_pk_add_f32 v[20:21], v[12:13], 0 op_sel_hi:[1,0]
	v_pk_add_f32 v[12:13], v[10:11], 0 op_sel_hi:[1,0]
	v_cvt_pk_bf16_f32 v10, v18, v19
	v_cvt_pk_bf16_f32 v11, v16, v17
	s_nop 0
	v_cvt_pk_bf16_f32 v12, v12, v13
	v_cvt_pk_bf16_f32 v13, v20, v21
	global_store_dwordx4 v[14:15], v[10:13], off nt
	s_nop 1
	v_pk_add_f32 v[10:11], v[4:5], 0 op_sel_hi:[1,0]
	v_pk_add_f32 v[4:5], v[2:3], 0 op_sel_hi:[1,0]
	v_cvt_pk_bf16_f32 v2, v6, v7
	v_cvt_pk_bf16_f32 v3, v8, v9
	s_nop 0
	v_cvt_pk_bf16_f32 v4, v4, v5
	v_cvt_pk_bf16_f32 v5, v10, v11
	global_store_dwordx4 v[14:15], v[2:5], off offset:256 nt
	s_mov_b32 s98, 1
	s_cbranch_vccnz .LBB0_349
	s_andn2_b64 vcc, exec, s[4:5]
	s_cbranch_vccnz .LBB0_348
	s_barrier
	s_branch .LBB0_348

.LBB0_371:
	s_add_u32 s6, s2, 0x5c00000
	v_readlane_b32 s10, v254, 49
	s_sext_i32_i8 s46, s0
	s_addc_u32 s7, s3, 0
	s_mul_hi_i32 s0, s10, 0x30000
	s_mul_i32 s10, s10, 0x30000
	v_lshrrev_b32_e32 v17, 1, v158
	s_add_u32 s10, s82, s10
	v_and_b32_e32 v17, 24, v17
	s_addc_u32 s0, s83, s0
	v_and_b32_e32 v16, 15, v158
	v_lshlrev_b32_e32 v18, 1, v17
	s_add_u32 s40, s10, 0x5000
	v_lshl_or_b32 v159, s9, 6, v16
	v_lshl_or_b32 v16, v16, 6, v18
	v_lshlrev_b32_e32 v18, 2, v158
	s_addc_u32 s41, s0, 0
	s_lshl_b32 s0, s9, 13
	v_and_b32_e32 v18, 32, v18
	v_bitop3_b32 v19, v16, s0, v18 bitop3:0xde
	s_lshl_b32 s0, s1, 5
	s_and_b32 s10, s0, 0x60
	s_add_i32 m0, s19, 0x18000
	v_lshl_add_u64 v[8:9], v[8:9], 0, s[96:97]
	s_lshl_b32 s0, s10, 7
	s_waitcnt vmcnt(2)
	s_barrier
	global_load_lds_dwordx4 v[8:9], off
	v_lshl_add_u64 v[6:7], v[6:7], 0, s[96:97]
	s_add_i32 m0, s19, 0x1a000
	s_add_i32 s42, s19, 0x8000
	s_add_i32 s43, s19, 0xa000
	v_bitop3_b32 v176, s0, v16, v18 bitop3:0xf6
	global_load_lds_dwordx4 v[6:7], off
	v_lshl_add_u64 v[2:3], v[2:3], 0, s[96:97]
	s_mov_b32 m0, s42
	s_add_u32 s0, s20, 0x100080
	global_load_lds_dwordx4 v[2:3], off
	v_lshl_add_u64 v[2:3], v[4:5], 0, s[96:97]
	s_mov_b32 m0, s43
	s_addc_u32 s1, s21, 0
	global_load_lds_dwordx4 v[2:3], off
	s_add_i32 m0, s19, 0x1c000
	v_lshl_add_u64 v[2:3], s[0:1], 0, v[0:1]
	global_load_lds_dwordx4 v[2:3], off
	v_lshl_add_u64 v[2:3], s[0:1], 0, v[166:167]
	s_add_i32 m0, s19, 0x1e000
	s_cmpk_lt_u32 s8, 0x100
	global_load_lds_dwordx4 v[2:3], off
	v_lshlrev_b32_e32 v2, 16, v13
	v_and_b32_e32 v2, 0xfffe0000, v2
	v_lshl_add_u32 v2, v14, 13, v2
	v_and_b32_e32 v3, 1, v13
	v_lshl_or_b32 v2, v3, 6, v2
	v_lshl_add_u32 v168, v15, 1, v2
	v_lshlrev_b32_e32 v2, 16, v10
	v_and_b32_e32 v2, 0xfffe0000, v2
	s_waitcnt vmcnt(6)
	v_lshl_add_u32 v2, v11, 13, v2
	v_and_b32_e32 v3, 1, v10
	v_lshl_or_b32 v2, v3, 6, v2
	s_cselect_b64 s[8:9], -1, 0
	s_ashr_i32 s44, s36, 31
	v_or_b32_e32 v177, s10, v17
	v_mov_b32_e32 v169, v1
	v_lshl_add_u32 v170, v12, 1, v2
	v_mov_b32_e32 v171, v1
	s_mov_b32 s45, 0
	v_add_u32_e32 v178, 0, v19
	v_readlane_b32 s11, v254, 50
	s_barrier
	s_mov_b32 s98, 0
	s_branch .LBB0_374

.LBB0_381:
	s_add_u32 s22, s20, 0xfff00080
	s_addc_u32 s23, s21, -1
	s_add_i32 s57, 0, 0x10000
	s_cmp_eq_u32 s56, 60
	s_cselect_b32 s25, s13, s23
	s_cselect_b32 s24, s47, s22
	s_cselect_b32 s23, s11, s55
	s_cselect_b32 s22, s48, s49
	s_add_i32 s60, 0, 0x14000
	v_add_u32_e32 v134, s57, v176
	v_add_u32_e32 v179, s60, v176
	ds_read_b128 v[122:125], v134
	ds_read_b128 v[126:129], v134 offset:1024
	ds_read_b128 v[130:133], v134 offset:2048
	ds_read_b128 v[134:137], v134 offset:3072
	ds_read_b128 v[146:149], v179
	ds_read_b128 v[154:157], v179 offset:1024
	ds_read_b128 v[172:175], v179 offset:2048
	ds_read_b128 v[180:183], v179 offset:3072
	v_lshl_add_u64 v[212:213], s[20:21], 0, v[170:171]
	s_add_i32 m0, s19, 0xc000
	ds_read_b128 v[184:187], v178
	ds_read_b128 v[188:191], v178 offset:1024
	ds_read_b128 v[192:195], v178 offset:2048
	ds_read_b128 v[196:199], v178 offset:3072
	ds_read_b128 v[200:203], v178 offset:4096
	ds_read_b128 v[204:207], v178 offset:5120
	ds_read_b128 v[208:211], v178 offset:6144
	ds_read_b128 v[222:225], v178 offset:7168
	global_load_lds_dwordx4 v[212:213], off
	v_lshl_add_u64 v[212:213], s[20:21], 0, v[168:169]
	s_add_i32 m0, s19, 0xe000
	s_nop 0
	global_load_lds_dwordx4 v[212:213], off
	s_cmp_lg_u32 s98, 0
	s_cbranch_scc1 .Lrelax_g5_w1
	s_waitcnt vmcnt(8)
.Lback_g5_w1:
	s_waitcnt lgkmcnt(0)
	s_barrier
	s_setprio 1
	s_waitcnt lgkmcnt(0)
	v_mfma_f32_16x16x32_bf16 v[142:145], v[122:125], v[184:187], v[142:145]
	v_mfma_f32_16x16x32_bf16 v[138:141], v[130:133], v[184:187], v[138:141]
	v_mfma_f32_16x16x32_bf16 v[118:121], v[122:125], v[192:195], v[118:121]
	v_mfma_f32_16x16x32_bf16 v[106:109], v[130:133], v[192:195], v[106:109]
	v_mfma_f32_16x16x32_bf16 v[98:101], v[122:125], v[200:203], v[98:101]
	v_mfma_f32_16x16x32_bf16 v[90:93], v[130:133], v[200:203], v[90:93]
	v_mfma_f32_16x16x32_bf16 v[86:89], v[122:125], v[208:211], v[86:89]
	v_mfma_f32_16x16x32_bf16 v[74:77], v[130:133], v[208:211], v[74:77]
	v_mfma_f32_16x16x32_bf16 v[142:145], v[126:129], v[188:191], v[142:145]
	v_mfma_f32_16x16x32_bf16 v[138:141], v[134:137], v[188:191], v[138:141]
	v_mfma_f32_16x16x32_bf16 v[118:121], v[126:129], v[196:199], v[118:121]
	v_mfma_f32_16x16x32_bf16 v[106:109], v[134:137], v[196:199], v[106:109]
	v_mfma_f32_16x16x32_bf16 v[98:101], v[126:129], v[204:207], v[98:101]
	v_mfma_f32_16x16x32_bf16 v[90:93], v[134:137], v[204:207], v[90:93]
	v_mfma_f32_16x16x32_bf16 v[86:89], v[126:129], v[222:225], v[86:89]
	v_mfma_f32_16x16x32_bf16 v[74:77], v[134:137], v[222:225], v[74:77]
	s_setprio 0
	s_setprio 1
	v_mfma_f32_16x16x32_bf16 v[114:117], v[146:149], v[184:187], v[114:117]
	v_mfma_f32_16x16x32_bf16 v[110:113], v[172:175], v[184:187], v[110:113]
	v_mfma_f32_16x16x32_bf16 v[102:105], v[146:149], v[192:195], v[102:105]
	v_mfma_f32_16x16x32_bf16 v[94:97], v[172:175], v[192:195], v[94:97]
	v_mfma_f32_16x16x32_bf16 v[82:85], v[146:149], v[200:203], v[82:85]
	v_mfma_f32_16x16x32_bf16 v[78:81], v[172:175], v[200:203], v[78:81]
	v_mfma_f32_16x16x32_bf16 v[70:73], v[146:149], v[208:211], v[70:73]
	v_mfma_f32_16x16x32_bf16 v[66:69], v[172:175], v[208:211], v[66:69]
	v_mfma_f32_16x16x32_bf16 v[114:117], v[154:157], v[188:191], v[114:117]
	v_mfma_f32_16x16x32_bf16 v[110:113], v[180:183], v[188:191], v[110:113]
	v_mfma_f32_16x16x32_bf16 v[102:105], v[154:157], v[196:199], v[102:105]
	v_mfma_f32_16x16x32_bf16 v[94:97], v[180:183], v[196:199], v[94:97]
	v_mfma_f32_16x16x32_bf16 v[82:85], v[154:157], v[204:207], v[82:85]
	v_mfma_f32_16x16x32_bf16 v[78:81], v[180:183], v[204:207], v[78:81]
	v_mfma_f32_16x16x32_bf16 v[70:73], v[154:157], v[222:225], v[70:73]
	v_mfma_f32_16x16x32_bf16 v[66:69], v[180:183], v[222:225], v[66:69]
	s_setprio 0
	s_barrier
	s_add_i32 s57, s57, s31
	v_lshl_add_u64 v[212:213], s[22:23], 0, v[0:1]
	s_mov_b32 m0, s57
	ds_read_b128 v[184:187], v178 offset:16384
	ds_read_b128 v[188:191], v178 offset:17408
	ds_read_b128 v[192:195], v178 offset:18432
	ds_read_b128 v[196:199], v178 offset:19456
	ds_read_b128 v[200:203], v178 offset:20480
	ds_read_b128 v[204:207], v178 offset:21504
	ds_read_b128 v[208:211], v178 offset:22528
	ds_read_b128 v[222:225], v178 offset:23552
	global_load_lds_dwordx4 v[212:213], off
	s_add_i32 m0, s57, 0x2000
	s_add_u32 s58, s22, 0x100000
	v_lshl_add_u64 v[226:227], s[22:23], 0, v[166:167]
	s_addc_u32 s59, s23, 0
	s_add_i32 s57, s60, s31
	global_load_lds_dwordx4 v[226:227], off
	v_lshl_add_u64 v[228:229], s[58:59], 0, v[0:1]
	s_mov_b32 m0, s57
	v_lshl_add_u64 v[230:231], s[24:25], 0, v[164:165]
	global_load_lds_dwordx4 v[228:229], off
	v_lshl_add_u64 v[228:229], s[58:59], 0, v[166:167]
	s_add_i32 m0, s57, 0x2000
	s_nop 0
	global_load_lds_dwordx4 v[228:229], off
	v_lshl_add_u64 v[228:229], s[24:25], 0, v[162:163]
	s_mov_b32 m0, s19
	s_nop 0
	global_load_lds_dwordx4 v[228:229], off
	s_mov_b32 m0, s37
	s_nop 0
	global_load_lds_dwordx4 v[230:231], off
	s_cmp_lg_u32 s98, 0
	s_cbranch_scc1 .Lrelax_g5_w2
	s_waitcnt vmcnt(8)
.Lback_g5_w2:
	s_waitcnt lgkmcnt(0)
	s_barrier
	s_setprio 1
	s_waitcnt lgkmcnt(0)
	v_mfma_f32_16x16x32_bf16 v[62:65], v[122:125], v[184:187], v[62:65]
	v_mfma_f32_16x16x32_bf16 v[58:61], v[130:133], v[184:187], v[58:61]
	v_mfma_f32_16x16x32_bf16 v[54:57], v[122:125], v[192:195], v[54:57]
	v_mfma_f32_16x16x32_bf16 v[42:45], v[130:133], v[192:195], v[42:45]
	v_mfma_f32_16x16x32_bf16 v[34:37], v[122:125], v[200:203], v[34:37]
	v_mfma_f32_16x16x32_bf16 v[26:29], v[130:133], v[200:203], v[26:29]
	v_mfma_f32_16x16x32_bf16 v[22:25], v[122:125], v[208:211], v[22:25]
	v_mfma_f32_16x16x32_bf16 v[10:13], v[130:133], v[208:211], v[10:13]
	v_mfma_f32_16x16x32_bf16 v[62:65], v[126:129], v[188:191], v[62:65]
	v_mfma_f32_16x16x32_bf16 v[58:61], v[134:137], v[188:191], v[58:61]
	v_mfma_f32_16x16x32_bf16 v[54:57], v[126:129], v[196:199], v[54:57]
	v_mfma_f32_16x16x32_bf16 v[42:45], v[134:137], v[196:199], v[42:45]
	v_mfma_f32_16x16x32_bf16 v[34:37], v[126:129], v[204:207], v[34:37]
	v_mfma_f32_16x16x32_bf16 v[26:29], v[134:137], v[204:207], v[26:29]
	v_mfma_f32_16x16x32_bf16 v[22:25], v[126:129], v[222:225], v[22:25]
	v_mfma_f32_16x16x32_bf16 v[10:13], v[134:137], v[222:225], v[10:13]
	s_setprio 0
	s_setprio 1
	v_mfma_f32_16x16x32_bf16 v[50:53], v[146:149], v[184:187], v[50:53]
	v_mfma_f32_16x16x32_bf16 v[46:49], v[172:175], v[184:187], v[46:49]
	v_mfma_f32_16x16x32_bf16 v[38:41], v[146:149], v[192:195], v[38:41]
	v_mfma_f32_16x16x32_bf16 v[30:33], v[172:175], v[192:195], v[30:33]
	v_mfma_f32_16x16x32_bf16 v[18:21], v[146:149], v[200:203], v[18:21]
	v_mfma_f32_16x16x32_bf16 v[14:17], v[172:175], v[200:203], v[14:17]
	v_mfma_f32_16x16x32_bf16 v[6:9], v[146:149], v[208:211], v[6:9]
	v_mfma_f32_16x16x32_bf16 v[2:5], v[172:175], v[208:211], v[2:5]
	v_mfma_f32_16x16x32_bf16 v[50:53], v[154:157], v[188:191], v[50:53]
	v_mfma_f32_16x16x32_bf16 v[46:49], v[180:183], v[188:191], v[46:49]
	v_mfma_f32_16x16x32_bf16 v[38:41], v[154:157], v[196:199], v[38:41]
	v_mfma_f32_16x16x32_bf16 v[30:33], v[180:183], v[196:199], v[30:33]
	v_mfma_f32_16x16x32_bf16 v[18:21], v[154:157], v[204:207], v[18:21]
	v_mfma_f32_16x16x32_bf16 v[14:17], v[180:183], v[204:207], v[14:17]
	v_mfma_f32_16x16x32_bf16 v[6:9], v[154:157], v[222:225], v[6:9]
	v_mfma_f32_16x16x32_bf16 v[2:5], v[180:183], v[222:225], v[2:5]
	s_setprio 0
	s_barrier
	s_add_i32 s57, 0, 0x18000
	s_add_i32 s58, 0, 0x1c000
	v_add_u32_e32 v134, s57, v176
	v_add_u32_e32 v179, s58, v176
	ds_read_b128 v[122:125], v134
	ds_read_b128 v[126:129], v134 offset:1024
	ds_read_b128 v[130:133], v134 offset:2048
	ds_read_b128 v[134:137], v134 offset:3072
	ds_read_b128 v[146:149], v179
	ds_read_b128 v[154:157], v179 offset:1024
	ds_read_b128 v[172:175], v179 offset:2048
	ds_read_b128 v[180:183], v179 offset:3072
	s_add_u32 s24, s24, 0x100000
	s_addc_u32 s25, s25, 0
	s_mov_b32 m0, s38
	v_lshl_add_u64 v[232:233], s[24:25], 0, v[162:163]
	ds_read_b128 v[184:187], v178 offset:32768
	ds_read_b128 v[188:191], v178 offset:33792
	ds_read_b128 v[192:195], v178 offset:34816
	ds_read_b128 v[196:199], v178 offset:35840
	ds_read_b128 v[200:203], v178 offset:36864
	ds_read_b128 v[204:207], v178 offset:37888
	ds_read_b128 v[208:211], v178 offset:38912
	ds_read_b128 v[222:225], v178 offset:39936
	global_load_lds_dwordx4 v[232:233], off
	v_lshl_add_u64 v[232:233], s[24:25], 0, v[164:165]
	s_mov_b32 m0, s39
	s_nop 0
	global_load_lds_dwordx4 v[232:233], off
	s_waitcnt vmcnt(8)
	s_waitcnt lgkmcnt(0)
	s_barrier
	s_setprio 1
	s_waitcnt lgkmcnt(0)
	v_mfma_f32_16x16x32_bf16 v[142:145], v[122:125], v[184:187], v[142:145]
	v_mfma_f32_16x16x32_bf16 v[138:141], v[130:133], v[184:187], v[138:141]
	v_mfma_f32_16x16x32_bf16 v[118:121], v[122:125], v[192:195], v[118:121]
	v_mfma_f32_16x16x32_bf16 v[106:109], v[130:133], v[192:195], v[106:109]
	v_mfma_f32_16x16x32_bf16 v[98:101], v[122:125], v[200:203], v[98:101]
	v_mfma_f32_16x16x32_bf16 v[90:93], v[130:133], v[200:203], v[90:93]
	v_mfma_f32_16x16x32_bf16 v[86:89], v[122:125], v[208:211], v[86:89]
	v_mfma_f32_16x16x32_bf16 v[74:77], v[130:133], v[208:211], v[74:77]
	v_mfma_f32_16x16x32_bf16 v[142:145], v[126:129], v[188:191], v[142:145]
	v_mfma_f32_16x16x32_bf16 v[138:141], v[134:137], v[188:191], v[138:141]
	v_mfma_f32_16x16x32_bf16 v[118:121], v[126:129], v[196:199], v[118:121]
	v_mfma_f32_16x16x32_bf16 v[106:109], v[134:137], v[196:199], v[106:109]
	v_mfma_f32_16x16x32_bf16 v[98:101], v[126:129], v[204:207], v[98:101]
	v_mfma_f32_16x16x32_bf16 v[90:93], v[134:137], v[204:207], v[90:93]
	v_mfma_f32_16x16x32_bf16 v[86:89], v[126:129], v[222:225], v[86:89]
	v_mfma_f32_16x16x32_bf16 v[74:77], v[134:137], v[222:225], v[74:77]
	s_setprio 0
	s_setprio 1
	v_mfma_f32_16x16x32_bf16 v[114:117], v[146:149], v[184:187], v[114:117]
	v_mfma_f32_16x16x32_bf16 v[110:113], v[172:175], v[184:187], v[110:113]
	v_mfma_f32_16x16x32_bf16 v[102:105], v[146:149], v[192:195], v[102:105]
	v_mfma_f32_16x16x32_bf16 v[94:97], v[172:175], v[192:195], v[94:97]
	v_mfma_f32_16x16x32_bf16 v[82:85], v[146:149], v[200:203], v[82:85]
	v_mfma_f32_16x16x32_bf16 v[78:81], v[172:175], v[200:203], v[78:81]
	v_mfma_f32_16x16x32_bf16 v[70:73], v[146:149], v[208:211], v[70:73]
	v_mfma_f32_16x16x32_bf16 v[66:69], v[172:175], v[208:211], v[66:69]
	v_mfma_f32_16x16x32_bf16 v[114:117], v[154:157], v[188:191], v[114:117]
	v_mfma_f32_16x16x32_bf16 v[110:113], v[180:183], v[188:191], v[110:113]
	v_mfma_f32_16x16x32_bf16 v[102:105], v[154:157], v[196:199], v[102:105]
	v_mfma_f32_16x16x32_bf16 v[94:97], v[180:183], v[196:199], v[94:97]
	v_mfma_f32_16x16x32_bf16 v[82:85], v[154:157], v[204:207], v[82:85]
	v_mfma_f32_16x16x32_bf16 v[78:81], v[180:183], v[204:207], v[78:81]
	v_mfma_f32_16x16x32_bf16 v[70:73], v[154:157], v[222:225], v[70:73]
	v_mfma_f32_16x16x32_bf16 v[66:69], v[180:183], v[222:225], v[66:69]
	s_setprio 0
	s_barrier
	s_add_i32 s24, s57, s31
	v_lshl_add_u64 v[212:213], v[212:213], 0, s[96:97]
	s_mov_b32 m0, s24
	ds_read_b128 v[184:187], v178 offset:49152
	ds_read_b128 v[188:191], v178 offset:50176
	ds_read_b128 v[192:195], v178 offset:51200
	ds_read_b128 v[196:199], v178 offset:52224
	ds_read_b128 v[200:203], v178 offset:53248
	ds_read_b128 v[204:207], v178 offset:54272
	ds_read_b128 v[208:211], v178 offset:55296
	ds_read_b128 v[222:225], v178 offset:56320
	global_load_lds_dwordx4 v[212:213], off
	s_add_i32 m0, s24, 0x2000
	s_add_u32 s22, s22, 0x100080
	v_lshl_add_u64 v[212:213], v[226:227], 0, s[96:97]
	s_addc_u32 s23, s23, 0
	s_add_i32 s24, s58, s31
	global_load_lds_dwordx4 v[212:213], off
	v_lshl_add_u64 v[212:213], s[22:23], 0, v[0:1]
	s_mov_b32 m0, s24
	s_nop 0
	global_load_lds_dwordx4 v[212:213], off
	v_lshl_add_u64 v[212:213], s[22:23], 0, v[166:167]
	s_add_i32 m0, s24, 0x2000
	s_nop 0
	global_load_lds_dwordx4 v[212:213], off
	v_lshl_add_u64 v[212:213], v[228:229], 0, s[96:97]
	s_mov_b32 m0, s42
	s_nop 0
	global_load_lds_dwordx4 v[212:213], off
	v_lshl_add_u64 v[212:213], v[230:231], 0, s[96:97]
	s_mov_b32 m0, s43
	s_nop 0
	global_load_lds_dwordx4 v[212:213], off
	s_waitcnt vmcnt(8)
	s_waitcnt lgkmcnt(0)
	s_barrier
	s_setprio 1
	s_waitcnt lgkmcnt(0)
	v_mfma_f32_16x16x32_bf16 v[62:65], v[122:125], v[184:187], v[62:65]
	v_mfma_f32_16x16x32_bf16 v[58:61], v[130:133], v[184:187], v[58:61]
	v_mfma_f32_16x16x32_bf16 v[54:57], v[122:125], v[192:195], v[54:57]
	v_mfma_f32_16x16x32_bf16 v[42:45], v[130:133], v[192:195], v[42:45]
	v_mfma_f32_16x16x32_bf16 v[34:37], v[122:125], v[200:203], v[34:37]
	v_mfma_f32_16x16x32_bf16 v[26:29], v[130:133], v[200:203], v[26:29]
	v_mfma_f32_16x16x32_bf16 v[22:25], v[122:125], v[208:211], v[22:25]
	v_mfma_f32_16x16x32_bf16 v[10:13], v[130:133], v[208:211], v[10:13]
	v_mfma_f32_16x16x32_bf16 v[62:65], v[126:129], v[188:191], v[62:65]
	v_mfma_f32_16x16x32_bf16 v[58:61], v[134:137], v[188:191], v[58:61]
	v_mfma_f32_16x16x32_bf16 v[54:57], v[126:129], v[196:199], v[54:57]
	v_mfma_f32_16x16x32_bf16 v[42:45], v[134:137], v[196:199], v[42:45]
	v_mfma_f32_16x16x32_bf16 v[34:37], v[126:129], v[204:207], v[34:37]
	v_mfma_f32_16x16x32_bf16 v[26:29], v[134:137], v[204:207], v[26:29]
	v_mfma_f32_16x16x32_bf16 v[22:25], v[126:129], v[222:225], v[22:25]
	v_mfma_f32_16x16x32_bf16 v[10:13], v[134:137], v[222:225], v[10:13]
	s_setprio 0
	s_setprio 1
	v_mfma_f32_16x16x32_bf16 v[50:53], v[146:149], v[184:187], v[50:53]
	v_mfma_f32_16x16x32_bf16 v[46:49], v[172:175], v[184:187], v[46:49]
	v_mfma_f32_16x16x32_bf16 v[38:41], v[146:149], v[192:195], v[38:41]
	v_mfma_f32_16x16x32_bf16 v[30:33], v[172:175], v[192:195], v[30:33]
	v_mfma_f32_16x16x32_bf16 v[18:21], v[146:149], v[200:203], v[18:21]
	v_mfma_f32_16x16x32_bf16 v[14:17], v[172:175], v[200:203], v[14:17]
	v_mfma_f32_16x16x32_bf16 v[6:9], v[146:149], v[208:211], v[6:9]
	v_mfma_f32_16x16x32_bf16 v[2:5], v[172:175], v[208:211], v[2:5]
	v_mfma_f32_16x16x32_bf16 v[50:53], v[154:157], v[188:191], v[50:53]
	v_mfma_f32_16x16x32_bf16 v[46:49], v[180:183], v[188:191], v[46:49]
	v_mfma_f32_16x16x32_bf16 v[38:41], v[154:157], v[196:199], v[38:41]
	v_mfma_f32_16x16x32_bf16 v[30:33], v[180:183], v[196:199], v[30:33]
	v_mfma_f32_16x16x32_bf16 v[18:21], v[154:157], v[204:207], v[18:21]
	v_mfma_f32_16x16x32_bf16 v[14:17], v[180:183], v[204:207], v[14:17]
	v_mfma_f32_16x16x32_bf16 v[6:9], v[154:157], v[222:225], v[6:9]
	v_mfma_f32_16x16x32_bf16 v[2:5], v[180:183], v[222:225], v[2:5]
	s_setprio 0
	s_barrier
	s_add_i32 s56, s56, 2
	s_add_u32 s49, s49, 0x100
	s_addc_u32 s55, s55, 0
	s_add_u32 s20, s20, 0x100
	s_addc_u32 s21, s21, 0
	s_cmp_gt_u32 s56, 61
	s_cbranch_scc0 .LBB0_381
	s_and_b64 vcc, exec, s[8:9]
	s_movk_i32 s47, 0xec00
	s_movk_i32 s55, 0xf000
	s_cbranch_vccz .LBB0_384
	s_barrier
.LBB0_384:
	v_lshl_add_u32 v172, s18, 8, v159
	v_lshl_or_b32 v122, s46, 8, v177
	v_ashrrev_i32_e32 v173, 31, v172
	v_ashrrev_i32_e32 v123, 31, v122
	v_lshlrev_b64 v[124:125], 11, v[172:173]
	v_lshl_add_u64 v[124:125], s[6:7], 0, v[124:125]
	v_lshlrev_b64 v[174:175], 1, v[122:123]
	s_ashr_i32 s11, s18, 4
	v_lshl_add_u64 v[154:155], v[124:125], 0, v[174:175]
	s_mul_hi_i32 s13, s11, 0x6000
	s_mulk_i32 s11, 0x6000
	flat_load_dwordx4 v[146:149], v[154:155]
	s_add_u32 s20, s40, s11
	s_addc_u32 s21, s41, s13
	v_lshl_add_u64 v[122:123], v[122:123], 2, s[20:21]
	flat_load_dwordx4 v[134:137], v[122:123]
	flat_load_dwordx4 v[130:133], v[122:123] offset:16
	flat_load_dwordx4 v[126:129], v[122:123] offset:512
	s_nop 0
	flat_load_dwordx4 v[122:125], v[122:123] offset:528
	s_andn2_b64 vcc, exec, s[0:1]
	s_mov_b64 s[0:1], -1
	s_movk_i32 s60, 0xe400
	s_waitcnt vmcnt(0) lgkmcnt(0)
	v_lshlrev_b32_e32 v156, 16, v146
	v_and_b32_e32 v157, 0xffff0000, v146
	v_lshlrev_b32_e32 v146, 16, v147
	v_and_b32_e32 v147, 0xffff0000, v147
	v_lshlrev_b32_e32 v180, 16, v148
	v_and_b32_e32 v181, 0xffff0000, v148
	v_lshlrev_b32_e32 v148, 16, v149
	v_and_b32_e32 v149, 0xffff0000, v149
	v_pk_fma_f32 v[144:145], v[144:145], v[136:137], v[146:147]
	v_pk_fma_f32 v[142:143], v[142:143], v[134:135], v[156:157]
	v_pk_fma_f32 v[146:147], v[140:141], v[132:133], v[148:149]
	v_pk_fma_f32 v[140:141], v[138:139], v[130:131], v[180:181]
	v_cvt_pk_bf16_f32 v138, v142, v143
	v_cvt_pk_bf16_f32 v139, v144, v145
	s_nop 0
	v_cvt_pk_bf16_f32 v140, v140, v141
	v_cvt_pk_bf16_f32 v141, v146, v147
	flat_load_dwordx4 v[142:145], v[154:155] offset:256
	v_or_b32_e32 v146, 16, v172
	v_ashrrev_i32_e32 v147, 31, v146
	v_lshlrev_b64 v[146:147], 11, v[146:147]
	v_lshl_add_u64 v[146:147], s[6:7], 0, v[146:147]
	flat_store_dwordx4 v[154:155], v[138:141]
	v_lshl_add_u64 v[146:147], v[146:147], 0, v[174:175]
	s_waitcnt vmcnt(0) lgkmcnt(0)
	v_lshlrev_b32_e32 v138, 16, v142
	v_and_b32_e32 v139, 0xffff0000, v142
	v_lshlrev_b32_e32 v140, 16, v143
	v_and_b32_e32 v141, 0xffff0000, v143
	v_lshlrev_b32_e32 v142, 16, v144
	v_and_b32_e32 v143, 0xffff0000, v144
	v_lshlrev_b32_e32 v144, 16, v145
	v_and_b32_e32 v145, 0xffff0000, v145
	v_pk_fma_f32 v[116:117], v[116:117], v[128:129], v[140:141]
	v_pk_fma_f32 v[114:115], v[114:115], v[126:127], v[138:139]
	v_pk_fma_f32 v[138:139], v[112:113], v[124:125], v[144:145]
	v_pk_fma_f32 v[112:113], v[110:111], v[122:123], v[142:143]
	v_cvt_pk_bf16_f32 v110, v114, v115
	v_cvt_pk_bf16_f32 v111, v116, v117
	s_nop 0
	v_cvt_pk_bf16_f32 v112, v112, v113
	v_cvt_pk_bf16_f32 v113, v138, v139
	flat_load_dwordx4 v[114:117], v[146:147]
	s_nop 0
	flat_store_dwordx4 v[154:155], v[110:113] offset:256
	s_waitcnt vmcnt(0) lgkmcnt(0)
	s_nop 0
	v_lshlrev_b32_e32 v110, 16, v114
	v_and_b32_e32 v111, 0xffff0000, v114
	v_lshlrev_b32_e32 v112, 16, v115
	v_and_b32_e32 v113, 0xffff0000, v115
	v_lshlrev_b32_e32 v114, 16, v116
	v_and_b32_e32 v115, 0xffff0000, v116
	v_lshlrev_b32_e32 v116, 16, v117
	v_and_b32_e32 v117, 0xffff0000, v117
	v_pk_fma_f32 v[112:113], v[120:121], v[136:137], v[112:113]
	v_pk_fma_f32 v[110:111], v[118:119], v[134:135], v[110:111]
	v_pk_fma_f32 v[116:117], v[108:109], v[132:133], v[116:117]
	v_pk_fma_f32 v[108:109], v[106:107], v[130:131], v[114:115]
	v_cvt_pk_bf16_f32 v106, v110, v111
	v_cvt_pk_bf16_f32 v107, v112, v113
	v_or_b32_e32 v114, 32, v172
	v_cvt_pk_bf16_f32 v108, v108, v109
	v_cvt_pk_bf16_f32 v109, v116, v117
	flat_load_dwordx4 v[110:113], v[146:147] offset:256
	v_ashrrev_i32_e32 v115, 31, v114
	flat_store_dwordx4 v[146:147], v[106:109]
	v_lshlrev_b64 v[114:115], 11, v[114:115]
	v_lshl_add_u64 v[114:115], s[6:7], 0, v[114:115]
	v_lshl_add_u64 v[114:115], v[114:115], 0, v[174:175]
	s_waitcnt vmcnt(0) lgkmcnt(0)
	v_lshlrev_b32_e32 v106, 16, v110
	v_and_b32_e32 v107, 0xffff0000, v110
	v_lshlrev_b32_e32 v108, 16, v111
	v_and_b32_e32 v109, 0xffff0000, v111
	v_lshlrev_b32_e32 v110, 16, v112
	v_and_b32_e32 v111, 0xffff0000, v112
	v_lshlrev_b32_e32 v112, 16, v113
	v_and_b32_e32 v113, 0xffff0000, v113
	v_pk_fma_f32 v[102:103], v[102:103], v[126:127], v[106:107]
	v_pk_fma_f32 v[106:107], v[96:97], v[124:125], v[112:113]
	v_pk_fma_f32 v[96:97], v[94:95], v[122:123], v[110:111]
	v_pk_fma_f32 v[104:105], v[104:105], v[128:129], v[108:109]
	v_cvt_pk_bf16_f32 v94, v102, v103
	s_nop 0
	v_cvt_pk_bf16_f32 v95, v104, v105
	v_cvt_pk_bf16_f32 v96, v96, v97
	v_cvt_pk_bf16_f32 v97, v106, v107
	flat_store_dwordx4 v[146:147], v[94:97] offset:256
	flat_load_dwordx4 v[94:97], v[114:115]
	s_waitcnt vmcnt(0) lgkmcnt(0)
	v_lshlrev_b32_e32 v102, 16, v94
	v_and_b32_e32 v103, 0xffff0000, v94
	v_lshlrev_b32_e32 v94, 16, v95
	v_and_b32_e32 v95, 0xffff0000, v95
	v_lshlrev_b32_e32 v104, 16, v96
	v_and_b32_e32 v105, 0xffff0000, v96
	v_lshlrev_b32_e32 v96, 16, v97
	v_and_b32_e32 v97, 0xffff0000, v97
	v_pk_fma_f32 v[94:95], v[100:101], v[136:137], v[94:95]
	v_pk_fma_f32 v[96:97], v[92:93], v[132:133], v[96:97]
	v_pk_fma_f32 v[92:93], v[90:91], v[130:131], v[104:105]
	v_pk_fma_f32 v[98:99], v[98:99], v[134:135], v[102:103]
	s_nop 0
	v_cvt_pk_bf16_f32 v90, v98, v99
	v_cvt_pk_bf16_f32 v91, v94, v95
	v_cvt_pk_bf16_f32 v92, v92, v93
	v_cvt_pk_bf16_f32 v93, v96, v97
	flat_load_dwordx4 v[94:97], v[114:115] offset:256
	v_or_b32_e32 v98, 48, v172
	v_ashrrev_i32_e32 v99, 31, v98
	v_lshlrev_b64 v[98:99], 11, v[98:99]
	v_lshl_add_u64 v[98:99], s[6:7], 0, v[98:99]
	flat_store_dwordx4 v[114:115], v[90:93]
	v_lshl_add_u64 v[98:99], v[98:99], 0, v[174:175]
	s_waitcnt vmcnt(0) lgkmcnt(0)
	v_lshlrev_b32_e32 v90, 16, v94
	v_and_b32_e32 v91, 0xffff0000, v94
	v_lshlrev_b32_e32 v92, 16, v95
	v_and_b32_e32 v93, 0xffff0000, v95
	v_lshlrev_b32_e32 v94, 16, v96
	v_and_b32_e32 v95, 0xffff0000, v96
	v_lshlrev_b32_e32 v96, 16, v97
	v_and_b32_e32 v97, 0xffff0000, v97
	v_pk_fma_f32 v[84:85], v[84:85], v[128:129], v[92:93]
	v_pk_fma_f32 v[82:83], v[82:83], v[126:127], v[90:91]
	v_pk_fma_f32 v[90:91], v[80:81], v[124:125], v[96:97]
	v_pk_fma_f32 v[80:81], v[78:79], v[122:123], v[94:95]
	v_cvt_pk_bf16_f32 v78, v82, v83
	v_cvt_pk_bf16_f32 v79, v84, v85
	s_nop 0
	v_cvt_pk_bf16_f32 v80, v80, v81
	v_cvt_pk_bf16_f32 v81, v90, v91
	flat_load_dwordx4 v[82:85], v[98:99]
	s_nop 0
	flat_store_dwordx4 v[114:115], v[78:81] offset:256
	s_waitcnt vmcnt(0) lgkmcnt(0)
	s_nop 0
	v_lshlrev_b32_e32 v78, 16, v82
	v_and_b32_e32 v79, 0xffff0000, v82
	v_lshlrev_b32_e32 v80, 16, v83
	v_and_b32_e32 v81, 0xffff0000, v83
	v_lshlrev_b32_e32 v82, 16, v84
	v_and_b32_e32 v83, 0xffff0000, v84
	v_lshlrev_b32_e32 v84, 16, v85
	v_and_b32_e32 v85, 0xffff0000, v85
	v_pk_fma_f32 v[80:81], v[88:89], v[136:137], v[80:81]
	v_pk_fma_f32 v[78:79], v[86:87], v[134:135], v[78:79]
	v_pk_fma_f32 v[84:85], v[76:77], v[132:133], v[84:85]
	v_pk_fma_f32 v[76:77], v[74:75], v[130:131], v[82:83]
	v_cvt_pk_bf16_f32 v74, v78, v79
	v_cvt_pk_bf16_f32 v75, v80, v81
	v_add_u32_e32 v82, 0x80, v172
	v_cvt_pk_bf16_f32 v76, v76, v77
	v_cvt_pk_bf16_f32 v77, v84, v85
	flat_load_dwordx4 v[78:81], v[98:99] offset:256
	v_ashrrev_i32_e32 v83, 31, v82
	flat_store_dwordx4 v[98:99], v[74:77]
	v_lshlrev_b64 v[82:83], 11, v[82:83]
	v_lshl_add_u64 v[82:83], s[6:7], 0, v[82:83]
	v_lshl_add_u64 v[82:83], v[82:83], 0, v[174:175]
	s_waitcnt vmcnt(0) lgkmcnt(0)
	v_lshlrev_b32_e32 v74, 16, v78
	v_and_b32_e32 v75, 0xffff0000, v78
	v_lshlrev_b32_e32 v76, 16, v79
	v_and_b32_e32 v77, 0xffff0000, v79
	v_lshlrev_b32_e32 v78, 16, v80
	v_and_b32_e32 v79, 0xffff0000, v80
	v_lshlrev_b32_e32 v80, 16, v81
	v_and_b32_e32 v81, 0xffff0000, v81
	v_pk_fma_f32 v[70:71], v[70:71], v[126:127], v[74:75]
	v_pk_fma_f32 v[74:75], v[68:69], v[124:125], v[80:81]
	v_pk_fma_f32 v[68:69], v[66:67], v[122:123], v[78:79]
	v_pk_fma_f32 v[72:73], v[72:73], v[128:129], v[76:77]
	v_cvt_pk_bf16_f32 v66, v70, v71
	s_nop 0
	v_cvt_pk_bf16_f32 v67, v72, v73
	v_cvt_pk_bf16_f32 v68, v68, v69
	v_cvt_pk_bf16_f32 v69, v74, v75
	flat_store_dwordx4 v[98:99], v[66:69] offset:256
	flat_load_dwordx4 v[66:69], v[82:83]
	s_waitcnt vmcnt(0) lgkmcnt(0)
	v_lshlrev_b32_e32 v70, 16, v66
	v_and_b32_e32 v71, 0xffff0000, v66
	v_lshlrev_b32_e32 v66, 16, v67
	v_and_b32_e32 v67, 0xffff0000, v67
	v_lshlrev_b32_e32 v72, 16, v68
	v_and_b32_e32 v73, 0xffff0000, v68
	v_lshlrev_b32_e32 v68, 16, v69
	v_and_b32_e32 v69, 0xffff0000, v69
	v_pk_fma_f32 v[64:65], v[64:65], v[136:137], v[66:67]
	v_pk_fma_f32 v[62:63], v[62:63], v[134:135], v[70:71]
	v_pk_fma_f32 v[66:67], v[60:61], v[132:133], v[68:69]
	v_pk_fma_f32 v[60:61], v[58:59], v[130:131], v[72:73]
	v_cvt_pk_bf16_f32 v58, v62, v63
	v_cvt_pk_bf16_f32 v59, v64, v65
	s_nop 0
	v_cvt_pk_bf16_f32 v60, v60, v61
	v_cvt_pk_bf16_f32 v61, v66, v67
	flat_load_dwordx4 v[62:65], v[82:83] offset:256
	v_add_u32_e32 v66, 0x90, v172
	v_ashrrev_i32_e32 v67, 31, v66
	v_lshlrev_b64 v[66:67], 11, v[66:67]
	v_lshl_add_u64 v[66:67], s[6:7], 0, v[66:67]
	flat_store_dwordx4 v[82:83], v[58:61]
	v_lshl_add_u64 v[66:67], v[66:67], 0, v[174:175]
	s_waitcnt vmcnt(0) lgkmcnt(0)
	v_lshlrev_b32_e32 v58, 16, v62
	v_and_b32_e32 v59, 0xffff0000, v62
	v_lshlrev_b32_e32 v60, 16, v63
	v_and_b32_e32 v61, 0xffff0000, v63
	v_lshlrev_b32_e32 v62, 16, v64
	v_and_b32_e32 v63, 0xffff0000, v64
	v_lshlrev_b32_e32 v64, 16, v65
	v_and_b32_e32 v65, 0xffff0000, v65
	v_pk_fma_f32 v[52:53], v[52:53], v[128:129], v[60:61]
	v_pk_fma_f32 v[50:51], v[50:51], v[126:127], v[58:59]
	v_pk_fma_f32 v[58:59], v[48:49], v[124:125], v[64:65]
	v_pk_fma_f32 v[48:49], v[46:47], v[122:123], v[62:63]
	v_cvt_pk_bf16_f32 v46, v50, v51
	v_cvt_pk_bf16_f32 v47, v52, v53
	s_nop 0
	v_cvt_pk_bf16_f32 v48, v48, v49
	v_cvt_pk_bf16_f32 v49, v58, v59
	flat_load_dwordx4 v[50:53], v[66:67]
	s_nop 0
	flat_store_dwordx4 v[82:83], v[46:49] offset:256
	s_waitcnt vmcnt(0) lgkmcnt(0)
	s_nop 0
	v_lshlrev_b32_e32 v46, 16, v50
	v_and_b32_e32 v47, 0xffff0000, v50
	v_lshlrev_b32_e32 v48, 16, v51
	v_and_b32_e32 v49, 0xffff0000, v51
	v_lshlrev_b32_e32 v50, 16, v52
	v_and_b32_e32 v51, 0xffff0000, v52
	v_lshlrev_b32_e32 v52, 16, v53
	v_and_b32_e32 v53, 0xffff0000, v53
	v_pk_fma_f32 v[48:49], v[56:57], v[136:137], v[48:49]
	v_pk_fma_f32 v[46:47], v[54:55], v[134:135], v[46:47]
	v_pk_fma_f32 v[52:53], v[44:45], v[132:133], v[52:53]
	v_pk_fma_f32 v[44:45], v[42:43], v[130:131], v[50:51]
	v_cvt_pk_bf16_f32 v42, v46, v47
	v_cvt_pk_bf16_f32 v43, v48, v49
	v_add_u32_e32 v50, 0xa0, v172
	v_cvt_pk_bf16_f32 v44, v44, v45
	v_cvt_pk_bf16_f32 v45, v52, v53
	flat_load_dwordx4 v[46:49], v[66:67] offset:256
	v_ashrrev_i32_e32 v51, 31, v50
	flat_store_dwordx4 v[66:67], v[42:45]
	v_lshlrev_b64 v[50:51], 11, v[50:51]
	v_lshl_add_u64 v[50:51], s[6:7], 0, v[50:51]
	v_lshl_add_u64 v[50:51], v[50:51], 0, v[174:175]
	s_waitcnt vmcnt(0) lgkmcnt(0)
	v_lshlrev_b32_e32 v42, 16, v46
	v_and_b32_e32 v43, 0xffff0000, v46
	v_lshlrev_b32_e32 v44, 16, v47
	v_and_b32_e32 v45, 0xffff0000, v47
	v_lshlrev_b32_e32 v46, 16, v48
	v_and_b32_e32 v47, 0xffff0000, v48
	v_lshlrev_b32_e32 v48, 16, v49
	v_and_b32_e32 v49, 0xffff0000, v49
	v_pk_fma_f32 v[38:39], v[38:39], v[126:127], v[42:43]
	v_pk_fma_f32 v[42:43], v[32:33], v[124:125], v[48:49]
	v_pk_fma_f32 v[32:33], v[30:31], v[122:123], v[46:47]
	v_pk_fma_f32 v[40:41], v[40:41], v[128:129], v[44:45]
	v_cvt_pk_bf16_f32 v30, v38, v39
	s_nop 0
	v_cvt_pk_bf16_f32 v31, v40, v41
	v_cvt_pk_bf16_f32 v32, v32, v33
	v_cvt_pk_bf16_f32 v33, v42, v43
	flat_store_dwordx4 v[66:67], v[30:33] offset:256
	flat_load_dwordx4 v[30:33], v[50:51]
	s_waitcnt vmcnt(0) lgkmcnt(0)
	v_lshlrev_b32_e32 v38, 16, v30
	v_and_b32_e32 v39, 0xffff0000, v30
	v_lshlrev_b32_e32 v30, 16, v31
	v_and_b32_e32 v31, 0xffff0000, v31
	v_lshlrev_b32_e32 v40, 16, v32
	v_and_b32_e32 v41, 0xffff0000, v32
	v_lshlrev_b32_e32 v32, 16, v33
	v_and_b32_e32 v33, 0xffff0000, v33
	v_pk_fma_f32 v[30:31], v[36:37], v[136:137], v[30:31]
	v_pk_fma_f32 v[32:33], v[28:29], v[132:133], v[32:33]
	v_pk_fma_f32 v[28:29], v[26:27], v[130:131], v[40:41]
	v_pk_fma_f32 v[34:35], v[34:35], v[134:135], v[38:39]
	s_nop 0
	v_cvt_pk_bf16_f32 v26, v34, v35
	v_cvt_pk_bf16_f32 v27, v30, v31
	v_cvt_pk_bf16_f32 v28, v28, v29
	v_cvt_pk_bf16_f32 v29, v32, v33
	flat_load_dwordx4 v[30:33], v[50:51] offset:256
	v_add_u32_e32 v34, 0xb0, v172
	v_ashrrev_i32_e32 v35, 31, v34
	v_lshlrev_b64 v[34:35], 11, v[34:35]
	v_lshl_add_u64 v[34:35], s[6:7], 0, v[34:35]
	flat_store_dwordx4 v[50:51], v[26:29]
	v_lshl_add_u64 v[34:35], v[34:35], 0, v[174:175]
	s_waitcnt vmcnt(0) lgkmcnt(0)
	v_lshlrev_b32_e32 v26, 16, v30
	v_and_b32_e32 v27, 0xffff0000, v30
	v_lshlrev_b32_e32 v28, 16, v31
	v_and_b32_e32 v29, 0xffff0000, v31
	v_lshlrev_b32_e32 v30, 16, v32
	v_and_b32_e32 v31, 0xffff0000, v32
	v_lshlrev_b32_e32 v32, 16, v33
	v_and_b32_e32 v33, 0xffff0000, v33
	v_pk_fma_f32 v[20:21], v[20:21], v[128:129], v[28:29]
	v_pk_fma_f32 v[18:19], v[18:19], v[126:127], v[26:27]
	v_pk_fma_f32 v[26:27], v[16:17], v[124:125], v[32:33]
	v_pk_fma_f32 v[16:17], v[14:15], v[122:123], v[30:31]
	v_cvt_pk_bf16_f32 v14, v18, v19
	v_cvt_pk_bf16_f32 v15, v20, v21
	s_nop 0
	v_cvt_pk_bf16_f32 v16, v16, v17
	v_cvt_pk_bf16_f32 v17, v26, v27
	flat_load_dwordx4 v[18:21], v[34:35]
	s_nop 0
	flat_store_dwordx4 v[50:51], v[14:17] offset:256
	s_waitcnt vmcnt(0) lgkmcnt(0)
	s_nop 0
	v_lshlrev_b32_e32 v14, 16, v18
	v_and_b32_e32 v15, 0xffff0000, v18
	v_lshlrev_b32_e32 v16, 16, v19
	v_and_b32_e32 v17, 0xffff0000, v19
	v_lshlrev_b32_e32 v18, 16, v20
	v_and_b32_e32 v19, 0xffff0000, v20
	v_lshlrev_b32_e32 v20, 16, v21
	v_and_b32_e32 v21, 0xffff0000, v21
	v_pk_fma_f32 v[16:17], v[24:25], v[136:137], v[16:17]
	v_pk_fma_f32 v[14:15], v[22:23], v[134:135], v[14:15]
	v_pk_fma_f32 v[20:21], v[12:13], v[132:133], v[20:21]
	v_pk_fma_f32 v[12:13], v[10:11], v[130:131], v[18:19]
	v_cvt_pk_bf16_f32 v10, v14, v15
	v_cvt_pk_bf16_f32 v11, v16, v17
	s_nop 0
	v_cvt_pk_bf16_f32 v12, v12, v13
	v_cvt_pk_bf16_f32 v13, v20, v21
	flat_load_dwordx4 v[14:17], v[34:35] offset:256
	s_nop 0
	flat_store_dwordx4 v[34:35], v[10:13]
	s_waitcnt vmcnt(0) lgkmcnt(0)
	s_nop 0
	v_lshlrev_b32_e32 v10, 16, v14
	v_and_b32_e32 v11, 0xffff0000, v14
	v_lshlrev_b32_e32 v12, 16, v15
	v_and_b32_e32 v13, 0xffff0000, v15
	v_lshlrev_b32_e32 v14, 16, v16
	v_and_b32_e32 v15, 0xffff0000, v16
	v_lshlrev_b32_e32 v16, 16, v17
	v_and_b32_e32 v17, 0xffff0000, v17
	v_pk_fma_f32 v[6:7], v[6:7], v[126:127], v[10:11]
	v_pk_fma_f32 v[10:11], v[4:5], v[124:125], v[16:17]
	v_pk_fma_f32 v[4:5], v[2:3], v[122:123], v[14:15]
	v_pk_fma_f32 v[8:9], v[8:9], v[128:129], v[12:13]
	v_cvt_pk_bf16_f32 v2, v6, v7
	s_nop 0
	v_cvt_pk_bf16_f32 v3, v8, v9
	v_cvt_pk_bf16_f32 v4, v4, v5
	v_cvt_pk_bf16_f32 v5, v10, v11
	flat_store_dwordx4 v[34:35], v[2:5] offset:256
	s_mov_b32 s98, 1
	s_cbranch_vccnz .LBB0_373
	s_andn2_b64 vcc, exec, s[4:5]
	s_cbranch_vccnz .LBB0_372
	s_barrier
	s_branch .LBB0_372
